# attention tile loops replicated 3x so the ring stage is static: stage offsets as ds_read immediates, no per-ITER address adds, no stage rotation
# speedup vs baseline: 1.0122x; 1.0122x over previous
.Ltb_u1_b:
	s_ashr_i32 s11, s6, 6
	s_lshl_b32 s10, s43, 4
	s_lshl_b32 s26, s11, 2
	v_bfe_u32 v233, v237, 4, 2
	s_and_b32 s60, s10, 0xfffff000
	v_or_b32_e32 v52, s26, v233
	s_waitcnt vmcnt(0)
	v_add_u32_e32 v2, s60, v52
	v_ashrrev_i32_e32 v3, 31, v2
	v_readlane_b32 s18, v252, 31
	v_bitop3_b32 v0, s26, v237, v233 bitop3:0x36
	v_lshlrev_b64 v[2:3], 12, v[2:3]
	v_readlane_b32 s19, v252, 32
	s_and_b32 s46, s43, 15
	s_lshl_b32 s84, s28, 8
	v_lshl_add_u64 v[2:3], s[18:19], 0, v[2:3]
	v_lshlrev_b32_e32 v0, 4, v0
	s_xor_b32 s17, s46, 31
	s_and_b32 s2, s11, 3
	v_lshl_add_u64 v[2:3], v[2:3], 0, s[84:85]
	v_and_b32_e32 v0, 0xf0, v0
	s_lshl_b32 s27, s11, 3
	v_bfe_u32 v53, v237, 3, 3
	s_lshl_b32 s21, s17, 7
	s_lshl_b32 s22, s2, 5
	s_lshl_b32 s18, s28, 7
	v_lshl_add_u64 v[2:3], v[2:3], 0, v[0:1]
	v_or_b32_e32 v0, s27, v53
	s_or_b32 s20, s22, s21
	v_lshrrev_b32_e32 v54, 1, v0
	v_add_u32_e32 v4, s18, v0
	v_and_b32_e32 v235, 31, v237
	v_xor_b32_e32 v6, v54, v237
	v_ashrrev_i32_e32 v5, 31, v4
	v_readlane_b32 s36, v252, 39
	s_or_b32 s10, s20, s60
	v_lshlrev_b64 v[4:5], 15, v[4:5]
	v_readlane_b32 s37, v252, 40
	v_lshlrev_b32_e32 v0, 4, v6
	v_or_b32_e32 v6, s10, v235
	v_lshl_add_u64 v[4:5], s[36:37], 0, v[4:5]
	v_ashrrev_i32_e32 v7, 31, v6
	v_readlane_b32 s36, v252, 17
	s_ashr_i32 s3, s6, 8
	v_lshlrev_b64 v[6:7], 12, v[6:7]
	v_readlane_b32 s37, v252, 18
	s_ashr_i32 s61, s60, 31
	v_bfe_u32 v234, v237, 5, 1
	v_lshl_add_u64 v[6:7], s[36:37], 0, v[6:7]
	s_lshl_b32 s36, s3, 6
	v_lshl_add_u64 v[4:5], s[60:61], 1, v[4:5]
	v_and_b32_e32 v0, 0x70, v0
	v_lshl_add_u64 v[6:7], v[6:7], 0, s[84:85]
	s_ashr_i32 s37, s36, 31
	v_lshl_add_u64 v[4:5], v[4:5], 0, v[0:1]
	v_lshl_add_u64 v[6:7], s[36:37], 1, v[6:7]
	v_lshlrev_b32_e32 v0, 4, v234
	v_lshl_add_u64 v[6:7], v[6:7], 0, v[0:1]
	global_load_dwordx4 v[146:149], v[6:7], off nt
	global_load_dwordx4 v[150:153], v[6:7], off offset:32 nt
	global_load_dwordx4 v[154:157], v[6:7], off offset:64 nt
	global_load_dwordx4 v[158:161], v[6:7], off offset:96 nt
	s_lshl_b32 s11, s11, 10
	s_add_i32 s11, s11, 0
	s_mov_b32 m0, s11
	s_mov_b64 s[36:37], 0x20000
	global_load_lds_dwordx4 v[2:3], off
	v_lshl_add_u64 v[8:9], v[2:3], 0, s[36:37]
	s_add_i32 m0, s11, 0x2000
	s_mov_b64 s[36:37], 0x40000
	global_load_lds_dwordx4 v[8:9], off
	s_add_i32 m0, s11, 0x4000
	v_lshl_add_u64 v[8:9], v[2:3], 0, s[36:37]
	s_mov_b64 s[36:37], 0x60000
	global_load_lds_dwordx4 v[8:9], off
	v_lshl_add_u64 v[8:9], v[2:3], 0, s[36:37]
	s_add_i32 m0, s11, 0x6000
	s_mov_b64 s[36:37], 0x200000
	global_load_lds_dwordx4 v[8:9], off
	s_add_i32 m0, s11, 0xc000
	v_lshl_add_u64 v[8:9], v[4:5], 0, s[36:37]
	global_load_lds_dwordx4 v[4:5], off
	s_add_i32 m0, s11, 0xe000
	s_mov_b64 s[36:37], 0xa0000
	global_load_lds_dwordx4 v[8:9], off
	s_add_i32 m0, s11, 0x8000
	v_lshl_add_u64 v[8:9], v[2:3], 0, s[34:35]
	global_load_lds_dwordx4 v[8:9], off
	v_lshl_add_u64 v[2:3], v[2:3], 0, s[36:37]
	s_add_i32 m0, s11, 0xa000
	s_mov_b64 s[36:37], 0x80
	global_load_lds_dwordx4 v[2:3], off
	s_add_i32 m0, s11, 0x10000
	v_lshl_add_u64 v[2:3], v[4:5], 0, s[36:37]
	s_mov_b64 s[36:37], 0x200080
	global_load_lds_dwordx4 v[2:3], off
	v_lshl_add_u64 v[2:3], v[4:5], 0, s[36:37]
	s_add_i32 m0, s11, 0x12000
	v_and_b32_e32 v0, 19, v237
	global_load_lds_dwordx4 v[2:3], off
	v_lshlrev_b32_e32 v2, 1, v237
	v_lshrrev_b32_e32 v35, 1, v34
	v_and_or_b32 v0, v2, 8, v0
	v_and_b32_e32 v22, 4, v35
	v_or_b32_e32 v2, v0, v22
	v_lshl_or_b32 v45, s3, 3, v234
	v_lshlrev_b32_e32 v44, 8, v2
	v_bitop3_b32 v2, v2, v45, 15 bitop3:0x6c
	v_lshl_add_u32 v239, v2, 4, v44
	s_waitcnt vmcnt(4)
	s_barrier
	v_add_u32_e32 v6, 0, v239
	v_bitop3_b32 v0, v0, 15, v22 bitop3:0xc8
	ds_read_b128 v[2:5], v6
	ds_read_b128 v[18:21], v6 offset:8192
	v_bitop3_b32 v22, v45, v0, 2 bitop3:0x36
	v_lshl_add_u32 v240, v22, 4, v44
	v_add_u32_e32 v40, 0, v240
	ds_read_b128 v[36:39], v40
	s_waitcnt vmcnt(0) lgkmcnt(0)
	v_mfma_f32_32x32x16_bf16 v[2:17], v[2:5], v[146:149], 0
	ds_read_b128 v[40:43], v40 offset:8192
	v_bfe_u32 v34, v34, 1, 3
	v_bitop3_b32 v57, v234, v34, 2 bitop3:0x36
	v_bitop3_b32 v58, v234, v34, 4 bitop3:0x36
	v_bitop3_b32 v59, v234, v34, 6 bitop3:0x36
	s_and_b32 s56, s42, 0xfffff000
	s_add_i32 s26, s26, s56
	v_mfma_f32_32x32x16_bf16 v[18:33], v[18:21], v[146:149], 0
	s_lshr_b32 s16, s43, 4
	s_and_b32 s16, s16, 15
	s_lshl_b32 s36, s16, 7
	s_lshl_b32 s37, s16, 8
	s_add_i32 s27, s27, s36
	s_ashr_i32 s57, s56, 31
	s_lshl_b64 s[44:45], s[56:57], 1
	v_mfma_f32_32x32x16_bf16 v[2:17], v[36:39], v[150:153], v[2:17]
	v_bitop3_b32 v36, v45, v0, 4 bitop3:0x36
	v_lshl_add_u32 v241, v36, 4, v44
	v_add_u32_e32 v46, 0, v241
	ds_read_b128 v[36:39], v46
	v_bitop3_b32 v0, v45, v0, 6 bitop3:0x36
	v_lshl_add_u32 v243, v0, 4, v44
	v_add_u32_e32 v0, 0, v243
	s_waitcnt lgkmcnt(1)
	v_mfma_f32_32x32x16_bf16 v[18:33], v[40:43], v[150:153], v[18:33]
	ds_read_b128 v[40:43], v46 offset:8192
	v_lshlrev_b32_e32 v236, 3, v234
	s_mov_b32 s84, s85
	v_bitop3_b32 v56, v35, v234, 7 bitop3:0x6c
	s_mov_b32 s86, s85
	s_mov_b32 s87, s85
	s_mov_b32 s88, s85
	s_waitcnt lgkmcnt(1)
	v_mfma_f32_32x32x16_bf16 v[2:17], v[36:39], v[154:157], v[2:17]
	ds_read_b128 v[36:39], v0
	s_mov_b32 s89, s85
	s_mov_b32 s90, s85
	s_mov_b32 s91, s85
	s_mov_b32 s92, s85
	s_mov_b32 s93, s85
	s_mov_b32 s94, s85
	s_waitcnt lgkmcnt(1)
	v_mfma_f32_32x32x16_bf16 v[18:33], v[40:43], v[154:157], v[18:33]
	ds_read_b128 v[40:43], v0 offset:8192
	s_mov_b32 s95, s85
	s_mov_b32 s96, s85
	s_mov_b32 s97, s85
	s_mov_b32 s98, s85
	s_mov_b32 s99, s85
	s_lshl_b32 s16, s17, 1
	s_waitcnt lgkmcnt(1)
	v_mfma_f32_32x32x16_bf16 v[2:17], v[36:39], v[158:161], v[2:17]
	v_lshlrev_b32_e32 v55, 7, v235
	s_lshr_b32 s19, s20, 6
	s_add_i32 s17, s16, 2
	s_add_i32 s19, s19, 1
	v_lshl_or_b32 v244, v56, 4, v55
	v_lshl_or_b32 v245, v57, 4, v55
	v_lshl_or_b32 v246, v58, 4, v55
	s_waitcnt lgkmcnt(0)
	v_mfma_f32_32x32x16_bf16 v[18:33], v[40:43], v[158:161], v[18:33]
	s_nop 2
	v_max_f32_e32 v34, v3, v3
	v_lshl_or_b32 v247, v59, 4, v55
	s_mov_b32 s23, 1
	v_and_b32_e32 v238, 63, v237
	s_mov_b32 s31, 0x8000
	s_min_u32 s19, s17, s19
	s_addk_i32 s20, 0xff50
	s_nop 1
	v_max_f32_e32 v0, v19, v19
	v_max_f32_e32 v0, v34, v0
	v_max3_f32 v0, v2, v18, v0
	v_max3_f32 v34, v20, v5, v21
	v_max3_f32 v0, v0, v4, v34
	v_max3_f32 v34, v22, v7, v23
	v_max3_f32 v0, v0, v6, v34
	v_max3_f32 v34, v24, v9, v25
	v_max3_f32 v0, v0, v8, v34
	v_max3_f32 v34, v26, v11, v27
	v_max3_f32 v0, v0, v10, v34
	v_max3_f32 v34, v28, v13, v29
	v_max3_f32 v0, v0, v12, v34
	v_max3_f32 v34, v30, v15, v31
	v_max3_f32 v0, v0, v14, v34
	v_max3_f32 v34, v32, v17, v33
	v_max3_f32 v0, v0, v16, v34
	v_mov_b32_e32 v34, v0
	s_nop 1
	v_permlane32_swap_b32_e32 v0, v34
	v_max_f32_e32 v34, v34, v34
	v_max_f32_e32 v0, v0, v0
	v_max_f32_e32 v213, v0, v34
	v_sub_f32_e32 v0, v2, v213
	v_exp_f32_e32 v60, v0
	v_sub_f32_e32 v0, v18, v213
	v_exp_f32_e32 v61, v0
	v_sub_f32_e32 v0, v3, v213
	v_sub_f32_e32 v2, v19, v213
	v_exp_f32_e32 v0, v0
	v_exp_f32_e32 v2, v2
	v_add_f32_e32 v3, v61, v60
	v_mov_b64_e32 v[34:35], s[84:85]
	v_cvt_pk_bf16_f32 v162, v60, v0
	v_pk_add_f32 v[18:19], v[2:3], v[0:1]
	v_sub_f32_e32 v3, v4, v213
	v_sub_f32_e32 v4, v20, v213
	v_pk_add_f32 v[18:19], v[18:19], v[18:19] op_sel_hi:[0,1]
	v_exp_f32_e32 v62, v4
	v_sub_f32_e32 v4, v5, v213
	v_exp_f32_e32 v3, v3
	v_exp_f32_e32 v18, v4
	v_sub_f32_e32 v4, v21, v213
	v_exp_f32_e32 v4, v4
	v_add_f32_e32 v5, v62, v3
	v_sub_u32_e32 v0, 7, v237
	v_cvt_pk_bf16_f32 v178, v61, v2
	v_pk_add_f32 v[20:21], v[4:5], v[18:19]
	v_sub_f32_e32 v5, v6, v213
	v_sub_f32_e32 v6, v22, v213
	v_pk_add_f32 v[20:21], v[20:21], v[20:21] op_sel_hi:[0,1]
	v_exp_f32_e32 v19, v6
	v_sub_f32_e32 v6, v7, v213
	v_exp_f32_e32 v5, v5
	v_exp_f32_e32 v20, v6
	v_sub_f32_e32 v6, v23, v213
	v_exp_f32_e32 v6, v6
	v_add_f32_e32 v7, v19, v5
	v_and_b32_e32 v0, 3, v0
	v_mov_b32_e32 v2, s33
	v_pk_add_f32 v[22:23], v[6:7], v[20:21]
	v_sub_f32_e32 v7, v8, v213
	v_sub_f32_e32 v8, v24, v213
	v_pk_add_f32 v[22:23], v[22:23], v[22:23] op_sel_hi:[0,1]
	v_exp_f32_e32 v21, v8
	v_sub_f32_e32 v8, v9, v213
	v_exp_f32_e32 v7, v7
	v_exp_f32_e32 v22, v8
	v_sub_f32_e32 v8, v25, v213
	v_exp_f32_e32 v8, v8
	v_add_f32_e32 v9, v21, v7
	s_movk_i32 s33, 0x510
	v_mad_u32_u24 v0, v0, s33, v2
	v_pk_add_f32 v[24:25], v[8:9], v[22:23]
	v_sub_f32_e32 v9, v10, v213
	v_sub_f32_e32 v10, v26, v213
	v_pk_add_f32 v[24:25], v[24:25], v[24:25] op_sel_hi:[0,1]
	v_exp_f32_e32 v23, v10
	v_sub_f32_e32 v10, v11, v213
	v_exp_f32_e32 v9, v9
	v_exp_f32_e32 v24, v10
	v_sub_f32_e32 v10, v27, v213
	v_exp_f32_e32 v10, v10
	v_add_f32_e32 v11, v23, v9
	v_or_b32_e32 v2, s26, v233
	v_cvt_pk_bf16_f32 v163, v3, v18
	v_pk_add_f32 v[26:27], v[10:11], v[24:25]
	v_sub_f32_e32 v11, v12, v213
	v_sub_f32_e32 v12, v28, v213
	v_pk_add_f32 v[26:27], v[26:27], v[26:27] op_sel_hi:[0,1]
	v_exp_f32_e32 v25, v12
	v_sub_f32_e32 v12, v13, v213
	v_exp_f32_e32 v11, v11
	v_exp_f32_e32 v26, v12
	v_sub_f32_e32 v12, v29, v213
	v_exp_f32_e32 v12, v12
	v_add_f32_e32 v13, v25, v11
	v_ashrrev_i32_e32 v3, 31, v2
	v_lshlrev_b64 v[214:215], 12, v[2:3]
	v_pk_add_f32 v[28:29], v[12:13], v[26:27]
	v_sub_f32_e32 v13, v14, v213
	v_sub_f32_e32 v14, v30, v213
	v_pk_add_f32 v[28:29], v[28:29], v[28:29] op_sel_hi:[0,1]
	v_exp_f32_e32 v27, v14
	v_sub_f32_e32 v14, v15, v213
	v_exp_f32_e32 v13, v13
	v_exp_f32_e32 v28, v14
	v_sub_f32_e32 v14, v31, v213
	v_exp_f32_e32 v14, v14
	v_sub_f32_e32 v15, v16, v213
	v_exp_f32_e32 v63, v15
	v_sub_f32_e32 v15, v32, v213
	v_exp_f32_e32 v32, v15
	v_add_f32_e32 v15, v27, v13
	v_pk_add_f32 v[30:31], v[14:15], v[28:29]
	v_bitop3_b32 v2, v52, 15, v237 bitop3:0x48
	v_pk_add_f32 v[30:31], v[30:31], v[30:31] op_sel_hi:[0,1]
	v_sub_f32_e32 v15, v17, v213
	v_lshlrev_b32_e32 v2, 4, v2
	v_exp_f32_e32 v30, v15
	v_sub_f32_e32 v15, v33, v213
	v_or3_b32 v214, v214, s37, v2
	v_or_b32_e32 v2, s27, v53
	v_exp_f32_e32 v50, v15
	v_ashrrev_i32_e32 v3, 31, v2
	v_cvt_pk_bf16_f32 v179, v62, v4
	v_lshlrev_b64 v[2:3], 15, v[2:3]
	v_bitop3_b32 v4, v54, 7, v237 bitop3:0x48
	v_lshl_or_b32 v2, v4, 4, v2
	v_add_f32_e32 v51, v32, v63
	v_lshl_add_u64 v[216:217], v[2:3], 0, s[44:45]
	v_sub_u32_e32 v2, v236, v235
	v_mov_b64_e32 v[48:49], s[98:99]
	v_pk_add_f32 v[16:17], v[50:51], v[30:31]
	v_subrev_u32_e32 v2, s22, v2
	v_mov_b64_e32 v[36:37], s[86:87]
	v_mov_b64_e32 v[38:39], s[88:89]
	v_mov_b64_e32 v[40:41], s[90:91]
	v_mov_b64_e32 v[42:43], s[92:93]
	v_mov_b64_e32 v[44:45], s[94:95]
	v_mov_b64_e32 v[46:47], s[96:97]
	v_xor_b32_e32 v66, 0x80000000, v213
	v_add_f32_e32 v242, v16, v17
	v_cvt_pk_bf16_f32 v164, v5, v20
	v_cvt_pk_bf16_f32 v165, v7, v22
	v_cvt_pk_bf16_f32 v170, v9, v24
	v_cvt_pk_bf16_f32 v171, v11, v26
	v_cvt_pk_bf16_f32 v172, v13, v28
	v_cvt_pk_bf16_f32 v173, v63, v30
	v_cvt_pk_bf16_f32 v180, v19, v6
	v_cvt_pk_bf16_f32 v181, v21, v8
	v_cvt_pk_bf16_f32 v186, v23, v10
	v_cvt_pk_bf16_f32 v187, v25, v12
	v_cvt_pk_bf16_f32 v188, v27, v14
	v_cvt_pk_bf16_f32 v189, v32, v50
	v_subrev_u32_e32 v248, s21, v2
	v_mov_b64_e32 v[64:65], v[48:49]
	v_mov_b64_e32 v[18:19], v[34:35]
	v_mov_b64_e32 v[2:3], v[34:35]
	v_readlane_b32 s94, v255, 10
	v_readlane_b32 s90, v255, 12
	v_mov_b32_e32 v67, v66
	v_mov_b32_e32 v68, v66
	v_mov_b32_e32 v69, v66
	v_mov_b32_e32 v70, v66
	v_mov_b32_e32 v71, v66
	v_mov_b32_e32 v72, v66
	v_mov_b32_e32 v73, v66
	v_mov_b32_e32 v74, v66
	v_mov_b32_e32 v75, v66
	v_mov_b32_e32 v76, v66
	v_mov_b32_e32 v77, v66
	v_mov_b32_e32 v78, v66
	v_mov_b32_e32 v79, v66
	v_mov_b32_e32 v80, v66
	v_mov_b32_e32 v81, v66
	s_mov_b32 s21, 0
	v_mov_b32_e32 v166, 0
	v_mov_b32_e32 v167, 0
	v_mov_b32_e32 v168, 0
	v_mov_b32_e32 v169, 0
	v_mov_b32_e32 v174, 0
	v_mov_b32_e32 v175, 0
	v_mov_b32_e32 v176, 0
	v_mov_b32_e32 v177, 0
	v_mov_b32_e32 v182, 0
	v_mov_b32_e32 v183, 0
	v_mov_b32_e32 v184, 0
	v_mov_b32_e32 v185, 0
	v_mov_b32_e32 v190, 0
	v_mov_b32_e32 v191, 0
	v_mov_b32_e32 v192, 0
	v_mov_b32_e32 v193, 0
	v_mov_b64_e32 v[62:63], v[46:47]
	v_mov_b64_e32 v[60:61], v[44:45]
	v_mov_b64_e32 v[58:59], v[42:43]
	v_mov_b64_e32 v[56:57], v[40:41]
	v_mov_b64_e32 v[54:55], v[38:39]
	v_mov_b64_e32 v[52:53], v[36:37]
	v_mov_b64_e32 v[50:51], v[34:35]
	v_mov_b64_e32 v[20:21], v[36:37]
	v_mov_b64_e32 v[22:23], v[38:39]
	v_mov_b64_e32 v[24:25], v[40:41]
	v_mov_b64_e32 v[26:27], v[42:43]
	v_mov_b64_e32 v[28:29], v[44:45]
	v_mov_b64_e32 v[30:31], v[46:47]
	v_mov_b64_e32 v[32:33], v[48:49]
	v_mov_b64_e32 v[4:5], v[36:37]
	v_mov_b64_e32 v[6:7], v[38:39]
	v_mov_b64_e32 v[8:9], v[40:41]
	v_mov_b64_e32 v[10:11], v[42:43]
	v_mov_b64_e32 v[12:13], v[44:45]
	v_mov_b64_e32 v[14:15], v[46:47]
	v_mov_b64_e32 v[16:17], v[48:49]
	s_mov_b32 s33, 0x4000
	s_mov_b32 s48, 0
	s_mov_b32 s49, 0
	s_movk_i32 s92, 0x6e
	s_movk_i32 s93, 0xd0
	s_mov_b32 s57, 0x41000000
	v_readlane_b32 s95, v255, 11
	v_readlane_b32 s91, v255, 13
	s_add_u32 s80, s8, 0xd0c0000
	s_addc_u32 s81, s9, 0
	s_add_u32 s62, s8, 0xd0e0000
	s_addc_u32 s63, s9, 0
	s_add_u32 s96, s8, 0x15000100
	s_addc_u32 s97, s9, 0
	s_add_u32 s58, s8, 0x15200100
	s_addc_u32 s59, s9, 0
	s_add_u32 s50, s8, 0xd100000
	s_addc_u32 s51, s9, 0
	s_add_u32 s4, s8, 0xd120000
	s_addc_u32 s5, s9, 0
	s_add_u32 s0, s8, 0x15000180
	s_addc_u32 s1, s9, 0
	s_add_u32 s52, s8, 0x15200180
	s_addc_u32 s53, s9, 0
	v_add_u32_e32 v244, 0x8000, v244
	v_add_u32_e32 v245, 0x8000, v245
	v_add_u32_e32 v246, 0x8000, v246
	v_add_u32_e32 v247, 0x8000, v247

.LBB0_168:
	ds_read_b128 v[98:101], v239 offset:16384
	ds_read_b128 v[114:117], v239 offset:24576
	ds_read_b128 v[118:121], v240 offset:16384
	s_barrier
.LBB0_174:
	s_mov_b32 s54, 0xffff8000
	s_cmp_ge_u32 s23, s19
	s_cbranch_scc1 .Lslow_u1e
.LBB0_185:
	s_add_i32 s100, s11, 0x0
	s_add_i32 s101, s11, 0x8000
	ds_read_b128 v[126:129], v244 offset:16384
	s_waitcnt lgkmcnt(1)
	v_mfma_f32_32x32x16_bf16 v[82:97], v[98:101], v[146:149], v[66:81]
	ds_read_b128 v[122:125], v240 offset:24576
	v_mfma_f32_32x32x16_bf16 v[98:113], v[114:117], v[146:149], v[66:81]
	ds_read_b128 v[114:117], v241 offset:16384
	v_mfma_f32_32x32x16_bf16 v[82:97], v[118:121], v[150:153], v[82:97]
	ds_read_b128 v[118:121], v241 offset:24576
	s_waitcnt lgkmcnt(0)
	v_mfma_f32_32x32x16_bf16 v[98:113], v[122:125], v[150:153], v[98:113]
	ds_read_b128 v[122:125], v243 offset:16384
	v_mfma_f32_32x32x16_bf16 v[82:97], v[114:117], v[154:157], v[82:97]
	ds_read_b128 v[114:117], v243 offset:24576
	v_mfma_f32_32x32x16_bf16 v[98:113], v[118:121], v[154:157], v[98:113]
	s_waitcnt lgkmcnt(0)
	v_mfma_f32_32x32x16_bf16 v[82:97], v[122:125], v[158:161], v[82:97]
	v_mfma_f32_32x32x16_bf16 v[98:113], v[114:117], v[158:161], v[98:113]
	s_nop 0
	ds_read_b128 v[122:125], v244 offset:20480
	ds_read_b128 v[118:121], v244 offset:24576
	ds_read_b128 v[114:117], v244 offset:28672
	s_add_i32 s22, s21, 64
	s_cmp_le_u32 s22, s20
	s_cbranch_scc0 .Lnear_u1e
.LBB0_188:
	v_mfma_f32_32x32x16_bf16 v[34:49], v[126:129], v[162:165], v[34:49]
	ds_read_b128 v[126:129], v245 offset:16384
	s_nop 0
	v_exp_f32_e32 v130, v82
	v_exp_f32_e32 v131, v83
	v_add_f32_e32 v132, v1, v130
	v_add_f32_e32 v133, v1, v131
	v_cvt_pk_bf16_f32 v166, v130, v131
	s_waitcnt lgkmcnt(3)
	v_mfma_f32_32x32x16_bf16 v[50:65], v[122:125], v[162:165], v[50:65]
	ds_read_b128 v[122:125], v245 offset:20480
	v_exp_f32_e32 v134, v84
	v_exp_f32_e32 v135, v85
	s_add_i32 s22, s23, 2
	v_add_f32_e32 v130, v132, v134
	v_add_f32_e32 v131, v133, v135
	v_cvt_pk_bf16_f32 v167, v134, v135
	s_mov_b32 m0, s100
	s_cmp_ge_u32 s22, s17
	s_cbranch_scc1 .LBB0_190
	global_load_lds_dwordx4 v214, s[80:81]
	s_add_i32 m0, s100, 0x2000
	s_nop 0
	global_load_lds_dwordx4 v214, s[62:63]
.LBB0_190:
	s_waitcnt lgkmcnt(2)
	v_mfma_f32_32x32x16_bf16 v[18:33], v[118:121], v[162:165], v[18:33]
	ds_read_b128 v[118:121], v245 offset:24576
	v_exp_f32_e32 v132, v86
	v_exp_f32_e32 v133, v87
	v_add_f32_e32 v130, v130, v132
	v_add_f32_e32 v131, v131, v133
	v_cvt_pk_bf16_f32 v168, v132, v133
	v_mfma_f32_32x32x16_bf16 v[2:17], v[114:117], v[162:165], v[2:17]
	ds_read_b128 v[114:117], v245 offset:28672
	v_exp_f32_e32 v132, v88
	v_exp_f32_e32 v133, v89
	v_add_f32_e32 v134, v130, v132
	v_add_f32_e32 v131, v131, v133
	v_cvt_pk_bf16_f32 v169, v132, v133
	s_waitcnt lgkmcnt(2)
	v_mfma_f32_32x32x16_bf16 v[34:49], v[126:129], v[170:173], v[34:49]
	ds_read_b128 v[126:129], v246 offset:16384
	v_exp_f32_e32 v132, v90
	v_exp_f32_e32 v133, v91
	v_add_f32_e32 v134, v134, v132
	v_add_f32_e32 v135, v131, v133
	v_cvt_pk_bf16_f32 v174, v132, v133
	v_mfma_f32_32x32x16_bf16 v[50:65], v[122:125], v[170:173], v[50:65]
	ds_read_b128 v[122:125], v246 offset:20480
	v_exp_f32_e32 v133, v92
	v_exp_f32_e32 v136, v93
	v_add_f32_e32 v131, v134, v133
	v_add_f32_e32 v132, v135, v136
	v_cvt_pk_bf16_f32 v175, v133, v136
.LBB0_192:
	s_waitcnt lgkmcnt(2)
	v_mfma_f32_32x32x16_bf16 v[18:33], v[118:121], v[170:173], v[18:33]
	ds_read_b128 v[118:121], v246 offset:24576
	v_exp_f32_e32 v133, v94
	v_exp_f32_e32 v134, v95
	v_add_f32_e32 v131, v131, v133
	v_add_f32_e32 v132, v132, v134
	v_cvt_pk_bf16_f32 v176, v133, v134
	v_mfma_f32_32x32x16_bf16 v[2:17], v[114:117], v[170:173], v[2:17]
	ds_read_b128 v[114:117], v246 offset:28672
	v_exp_f32_e32 v130, v96
	v_exp_f32_e32 v133, v97
	v_add_f32_e32 v131, v131, v130
	v_add_f32_e32 v132, v132, v133
	v_cvt_pk_bf16_f32 v177, v130, v133
	s_waitcnt lgkmcnt(2)
	v_mfma_f32_32x32x16_bf16 v[34:49], v[126:129], v[178:181], v[34:49]
	ds_read_b128 v[126:129], v247 offset:16384
	v_exp_f32_e32 v133, v98
	v_exp_f32_e32 v134, v99
	v_add_f32_e32 v131, v131, v133
	v_add_f32_e32 v132, v132, v134
	v_cvt_pk_bf16_f32 v182, v133, v134
	v_mfma_f32_32x32x16_bf16 v[50:65], v[122:125], v[178:181], v[50:65]
	v_exp_f32_e32 v133, v100
	v_exp_f32_e32 v134, v101
	ds_read_b128 v[122:125], v247 offset:20480
	v_add_f32_e32 v131, v131, v133
	v_add_f32_e32 v132, v132, v134
	v_cvt_pk_bf16_f32 v183, v133, v134
	s_add_i32 m0, s101, 0xc000
	s_cmp_eq_u64 s[88:89], 0
	s_cbranch_scc1 .LBB0_194
	global_load_lds_dwordx4 v216, s[96:97]
	s_add_i32 m0, s101, 0xe000
	s_nop 0
	global_load_lds_dwordx4 v216, s[58:59]
.LBB0_194:
	s_waitcnt lgkmcnt(2)
	v_mfma_f32_32x32x16_bf16 v[18:33], v[118:121], v[178:181], v[18:33]
	ds_read_b128 v[118:121], v247 offset:24576
	v_exp_f32_e32 v133, v102
	v_exp_f32_e32 v134, v103
	v_add_f32_e32 v131, v131, v133
	v_add_f32_e32 v132, v132, v134
	v_cvt_pk_bf16_f32 v184, v133, v134
	v_mfma_f32_32x32x16_bf16 v[2:17], v[114:117], v[178:181], v[2:17]
	ds_read_b128 v[114:117], v247 offset:28672
	v_exp_f32_e32 v130, v104
	v_exp_f32_e32 v133, v105
	v_add_f32_e32 v131, v131, v130
	v_add_f32_e32 v132, v132, v133
	v_cvt_pk_bf16_f32 v185, v130, v133
	s_waitcnt lgkmcnt(2)
	v_mfma_f32_32x32x16_bf16 v[34:49], v[126:129], v[186:189], v[34:49]
	v_exp_f32_e32 v126, v106
	v_exp_f32_e32 v127, v107
	v_add_f32_e32 v128, v131, v126
	v_add_f32_e32 v129, v132, v127
	v_cvt_pk_bf16_f32 v190, v126, v127
	v_mfma_f32_32x32x16_bf16 v[50:65], v[122:125], v[186:189], v[50:65]
	v_exp_f32_e32 v124, v108
	v_exp_f32_e32 v125, v109
	v_add_f32_e32 v122, v128, v124
	v_add_f32_e32 v123, v129, v125
	v_cvt_pk_bf16_f32 v191, v124, v125

.LBB0_208:
	ds_read_b128 v[98:101], v239 offset:32768
	ds_read_b128 v[114:117], v239 offset:40960
	ds_read_b128 v[118:121], v240 offset:32768
	s_barrier
.LBB0_214:
	s_add_i32 s40, s23, 1
	s_mov_b32 s54, 0xffffc000
	s_cmp_ge_u32 s40, s19
	s_cbranch_scc1 .Lslow_u1o
.LBB0_225:
	s_add_i32 s100, s11, 0x4000
	s_add_i32 s101, s11, 0x0
	ds_read_b128 v[126:129], v244 offset:32768
	s_waitcnt lgkmcnt(1)
	v_mfma_f32_32x32x16_bf16 v[82:97], v[98:101], v[146:149], v[66:81]
	ds_read_b128 v[122:125], v240 offset:40960
	v_mfma_f32_32x32x16_bf16 v[98:113], v[114:117], v[146:149], v[66:81]
	ds_read_b128 v[114:117], v241 offset:32768
	v_mfma_f32_32x32x16_bf16 v[82:97], v[118:121], v[150:153], v[82:97]
	ds_read_b128 v[118:121], v241 offset:40960
	s_waitcnt lgkmcnt(0)
	v_mfma_f32_32x32x16_bf16 v[98:113], v[122:125], v[150:153], v[98:113]
	ds_read_b128 v[122:125], v243 offset:32768
	v_mfma_f32_32x32x16_bf16 v[82:97], v[114:117], v[154:157], v[82:97]
	ds_read_b128 v[114:117], v243 offset:40960
	v_mfma_f32_32x32x16_bf16 v[98:113], v[118:121], v[154:157], v[98:113]
	s_waitcnt lgkmcnt(0)
	v_mfma_f32_32x32x16_bf16 v[82:97], v[122:125], v[158:161], v[82:97]
	v_mfma_f32_32x32x16_bf16 v[98:113], v[114:117], v[158:161], v[98:113]
	s_nop 0
	ds_read_b128 v[122:125], v244 offset:36864
	ds_read_b128 v[118:121], v244 offset:40960
	ds_read_b128 v[114:117], v244 offset:45056
	s_add_i32 s26, s21, 0x80
	s_cmp_le_u32 s26, s20
	s_cbranch_scc0 .Lnear_u1o
.LBB0_228:
	v_mfma_f32_32x32x16_bf16 v[34:49], v[126:129], v[166:169], v[34:49]
	ds_read_b128 v[126:129], v245 offset:32768
	s_nop 0
	v_exp_f32_e32 v130, v82
	v_exp_f32_e32 v131, v83
	v_add_f32_e32 v132, v1, v130
	v_add_f32_e32 v133, v1, v131
	v_cvt_pk_bf16_f32 v162, v130, v131
	s_waitcnt lgkmcnt(3)
	v_mfma_f32_32x32x16_bf16 v[50:65], v[122:125], v[166:169], v[50:65]
	ds_read_b128 v[122:125], v245 offset:36864
	v_exp_f32_e32 v130, v84
	v_exp_f32_e32 v131, v85
	s_add_i32 s23, s23, 3
	v_add_f32_e32 v132, v132, v130
	v_add_f32_e32 v133, v133, v131
	v_cvt_pk_bf16_f32 v163, v130, v131
	s_mov_b32 m0, s100
	s_cmp_gt_u32 s23, s16
	s_cbranch_scc1 .LBB0_230
	global_load_lds_dwordx4 v214, s[50:51]
	s_add_i32 m0, s100, 0x2000
	s_nop 0
	global_load_lds_dwordx4 v214, s[4:5]
.LBB0_230:
	s_waitcnt lgkmcnt(2)
	v_mfma_f32_32x32x16_bf16 v[18:33], v[118:121], v[166:169], v[18:33]
	ds_read_b128 v[118:121], v245 offset:40960
	v_exp_f32_e32 v134, v86
	v_exp_f32_e32 v135, v87
	v_add_f32_e32 v132, v132, v134
	v_add_f32_e32 v133, v133, v135
	v_cvt_pk_bf16_f32 v164, v134, v135
	v_mfma_f32_32x32x16_bf16 v[2:17], v[114:117], v[166:169], v[2:17]
	ds_read_b128 v[114:117], v245 offset:45056
	v_exp_f32_e32 v134, v88
	v_exp_f32_e32 v135, v89
	v_add_f32_e32 v136, v132, v134
	v_add_f32_e32 v133, v133, v135
	v_cvt_pk_bf16_f32 v165, v134, v135
	s_waitcnt lgkmcnt(2)
	v_mfma_f32_32x32x16_bf16 v[34:49], v[126:129], v[174:177], v[34:49]
	ds_read_b128 v[126:129], v246 offset:32768
	v_exp_f32_e32 v134, v90
	v_exp_f32_e32 v135, v91
	v_add_f32_e32 v136, v136, v134
	v_add_f32_e32 v137, v133, v135
	v_cvt_pk_bf16_f32 v170, v134, v135
	v_mfma_f32_32x32x16_bf16 v[50:65], v[122:125], v[174:177], v[50:65]
	ds_read_b128 v[122:125], v246 offset:36864
	v_exp_f32_e32 v135, v92
	v_exp_f32_e32 v138, v93
	v_add_f32_e32 v133, v136, v135
	v_add_f32_e32 v134, v137, v138
	v_cvt_pk_bf16_f32 v171, v135, v138
.LBB0_232:
	s_waitcnt lgkmcnt(2)
	v_mfma_f32_32x32x16_bf16 v[18:33], v[118:121], v[174:177], v[18:33]
	ds_read_b128 v[118:121], v246 offset:40960
	v_exp_f32_e32 v130, v94
	v_exp_f32_e32 v131, v95
	v_add_f32_e32 v133, v133, v130
	v_add_f32_e32 v134, v134, v131
	v_cvt_pk_bf16_f32 v172, v130, v131
	v_mfma_f32_32x32x16_bf16 v[2:17], v[114:117], v[174:177], v[2:17]
	ds_read_b128 v[114:117], v246 offset:45056
	v_exp_f32_e32 v130, v96
	v_exp_f32_e32 v131, v97
	v_add_f32_e32 v133, v133, v130
	v_add_f32_e32 v134, v134, v131
	v_cvt_pk_bf16_f32 v173, v130, v131
	s_waitcnt lgkmcnt(2)
	v_mfma_f32_32x32x16_bf16 v[34:49], v[126:129], v[182:185], v[34:49]
	ds_read_b128 v[126:129], v247 offset:32768
	v_exp_f32_e32 v130, v98
	v_exp_f32_e32 v131, v99
	v_add_f32_e32 v133, v133, v130
	v_add_f32_e32 v134, v134, v131
	v_cvt_pk_bf16_f32 v178, v130, v131
	v_mfma_f32_32x32x16_bf16 v[50:65], v[122:125], v[182:185], v[50:65]
	v_exp_f32_e32 v130, v100
	v_exp_f32_e32 v131, v101
	ds_read_b128 v[122:125], v247 offset:36864
	v_add_f32_e32 v133, v133, v130
	v_add_f32_e32 v134, v134, v131
	v_cvt_pk_bf16_f32 v179, v130, v131
	s_add_i32 m0, s101, 0xc000
	s_cmp_eq_u64 s[88:89], 0
	s_cbranch_scc1 .LBB0_234
	global_load_lds_dwordx4 v216, s[0:1]
	s_add_i32 m0, s101, 0xe000
	s_nop 0
	global_load_lds_dwordx4 v216, s[52:53]
.LBB0_234:
	s_waitcnt lgkmcnt(2)
	v_mfma_f32_32x32x16_bf16 v[18:33], v[118:121], v[182:185], v[18:33]
	ds_read_b128 v[118:121], v247 offset:40960
	v_exp_f32_e32 v135, v102
	v_exp_f32_e32 v136, v103
	v_add_f32_e32 v133, v133, v135
	v_add_f32_e32 v134, v134, v136
	v_cvt_pk_bf16_f32 v180, v135, v136
	v_mfma_f32_32x32x16_bf16 v[2:17], v[114:117], v[182:185], v[2:17]
	ds_read_b128 v[114:117], v247 offset:45056
	v_exp_f32_e32 v132, v104
	v_exp_f32_e32 v135, v105
	v_add_f32_e32 v133, v133, v132
	v_add_f32_e32 v134, v134, v135
	v_cvt_pk_bf16_f32 v181, v132, v135
	s_waitcnt lgkmcnt(2)
	v_mfma_f32_32x32x16_bf16 v[34:49], v[126:129], v[190:193], v[34:49]
	v_exp_f32_e32 v126, v106
	v_exp_f32_e32 v127, v107
	v_add_f32_e32 v128, v133, v126
	v_add_f32_e32 v129, v134, v127
	v_cvt_pk_bf16_f32 v186, v126, v127
	v_mfma_f32_32x32x16_bf16 v[50:65], v[122:125], v[190:193], v[50:65]
	v_exp_f32_e32 v124, v108
	v_exp_f32_e32 v125, v109
	v_add_f32_e32 v122, v128, v124
	v_add_f32_e32 v123, v129, v125
	v_cvt_pk_bf16_f32 v187, v124, v125

.LBB0_240:
	s_addk_i32 s21, 0x80
	s_add_i32 s23, s22, -3
	v_lshl_add_u64 v[214:215], v[214:215], 0, s[34:35]
	s_cmp_ge_u32 s23, s16
	v_lshl_add_u64 v[216:217], v[216:217], 0, s[24:25]
	s_cbranch_scc1 .LBB0_242
	s_mov_b32 s23, s22
	s_branch .Lr1u1_LBB0_164

.Lhd_u1e:
	s_add_i32 s22, s23, 2
	s_cmp_ge_u32 s22, s17
	s_cbranch_scc1 .LBB0_171
	s_mov_b32 s26, 0x0
	s_add_i32 s26, s11, s26
	s_add_i32 s27, s26, 0x2000
	s_mov_b32 m0, s26
	s_nop 0
	global_load_lds_dwordx4 v214, s[80:81]
	s_mov_b32 m0, s27
	s_nop 0
	global_load_lds_dwordx4 v214, s[62:63]
.LBB0_171:
	s_andn2_b64 vcc, exec, s[88:89]
	s_cbranch_vccnz .LBB0_173
	s_mov_b32 s26, 0x8000
	s_add_i32 s26, s11, s26
	s_add_i32 m0, s26, 0xc000
	s_add_i32 s26, s26, 0xe000
	global_load_lds_dwordx4 v216, s[96:97]
	s_mov_b32 m0, s26
	s_nop 0
	global_load_lds_dwordx4 v216, s[58:59]

.Lpvo_u1e:
	v_add_u32_e32 v249, s54, v244
	v_add_u32_e32 v212, s54, v245
	s_mov_b64 s[26:27], -1
	ds_read_b128 v[98:101], v249 offset:49152
	ds_read_b128 v[114:117], v249 offset:53248
	ds_read_b128 v[130:133], v249 offset:57344
	ds_read_b128 v[194:197], v249 offset:61440
	s_waitcnt lgkmcnt(0)
	v_mfma_f32_32x32x16_bf16 v[82:97], v[98:101], v[162:165], v[34:49]
	ds_read_b128 v[206:209], v212 offset:49152
	v_mfma_f32_32x32x16_bf16 v[98:113], v[114:117], v[162:165], v[50:65]
	ds_read_b128 v[198:201], v212 offset:53248
	s_add_i32 s22, s23, 2
	s_cmp_lt_u32 s22, s17
	s_cselect_b64 s[26:27], -1, 0
	s_cmp_ge_u32 s22, s17
	s_cbranch_scc1 .LBB0_178
	s_mov_b32 s40, 0x0
	s_add_i32 m0, s11, s40
	s_nop 0
	global_load_lds_dwordx4 v214, s[80:81]
.LBB0_178:
	v_mfma_f32_32x32x16_bf16 v[114:129], v[130:133], v[162:165], v[18:33]
	ds_read_b128 v[202:205], v212 offset:57344
	v_mfma_f32_32x32x16_bf16 v[130:145], v[194:197], v[162:165], v[2:17]
	ds_read_b128 v[194:197], v212 offset:61440
	s_waitcnt lgkmcnt(0)
	v_mfma_f32_32x32x16_bf16 v[82:97], v[206:209], v[170:173], v[82:97]
	v_add_u32_e32 v250, s54, v246
	ds_read_b128 v[206:209], v250 offset:49152
	v_mfma_f32_32x32x16_bf16 v[98:113], v[198:201], v[170:173], v[98:113]
	ds_read_b128 v[198:201], v250 offset:53248
	s_andn2_b64 vcc, exec, s[26:27]
	s_cbranch_vccnz .LBB0_180
	s_mov_b32 s26, 0x0
	s_add_i32 s26, s11, s26
	s_add_i32 m0, s26, 0x2000
	s_nop 0
	global_load_lds_dwordx4 v214, s[62:63]
.LBB0_180:
	v_mfma_f32_32x32x16_bf16 v[114:129], v[202:205], v[170:173], v[114:129]
	ds_read_b128 v[202:205], v250 offset:57344
	v_mfma_f32_32x32x16_bf16 v[130:145], v[194:197], v[170:173], v[130:145]
	ds_read_b128 v[194:197], v250 offset:61440
	s_waitcnt lgkmcnt(0)
	v_mfma_f32_32x32x16_bf16 v[82:97], v[206:209], v[178:181], v[82:97]
	v_add_u32_e32 v250, s54, v247
	ds_read_b128 v[206:209], v250 offset:49152
	v_mfma_f32_32x32x16_bf16 v[98:113], v[198:201], v[178:181], v[98:113]
	ds_read_b128 v[198:201], v250 offset:53248
	v_cndmask_b32_e64 v224, 0, 1, s[88:89]
	v_cmp_ne_u32_e64 s[40:41], 1, v224
	s_andn2_b64 vcc, exec, s[88:89]
	s_cbranch_vccnz .LBB0_182
	s_mov_b32 s26, 0x8000
	s_add_i32 s26, s11, s26
	s_add_i32 m0, s26, 0xc000
	s_nop 0
	global_load_lds_dwordx4 v216, s[96:97]
.LBB0_182:
	v_mfma_f32_32x32x16_bf16 v[114:129], v[202:205], v[178:181], v[114:129]
	ds_read_b128 v[202:205], v250 offset:57344
	v_mfma_f32_32x32x16_bf16 v[130:145], v[194:197], v[178:181], v[130:145]
	ds_read_b128 v[194:197], v250 offset:61440
	s_waitcnt lgkmcnt(0)
	v_mfma_f32_32x32x16_bf16 v[82:97], v[206:209], v[186:189], v[82:97]
	v_mfma_f32_32x32x16_bf16 v[98:113], v[198:201], v[186:189], v[98:113]
	s_and_b64 vcc, exec, s[40:41]
	s_cbranch_vccnz .LBB0_184
	s_mov_b32 s26, 0x8000
	s_add_i32 s26, s11, s26
	s_add_i32 m0, s26, 0xe000
	s_nop 0
	global_load_lds_dwordx4 v216, s[58:59]

.Lhd_u1o:
	s_add_i32 s26, s23, 3
	s_cmp_gt_u32 s26, s16
	s_cbranch_scc1 .LBB0_211
	s_mov_b32 s26, 0x4000
	s_add_i32 s26, s11, s26
	s_add_i32 s27, s26, 0x2000
	s_mov_b32 m0, s26
	s_nop 0
	global_load_lds_dwordx4 v214, s[50:51]
	s_mov_b32 m0, s27
	s_nop 0
	global_load_lds_dwordx4 v214, s[4:5]
.LBB0_211:
	s_andn2_b64 vcc, exec, s[88:89]
	s_cbranch_vccnz .LBB0_213
	s_mov_b32 s26, 0x0
	s_add_i32 s26, s11, s26
	s_add_i32 m0, s26, 0xc000
	s_add_i32 s26, s26, 0xe000
	global_load_lds_dwordx4 v216, s[0:1]
	s_mov_b32 m0, s26
	s_nop 0
	global_load_lds_dwordx4 v216, s[52:53]

.Lpvo_u1o:
	v_add_u32_e32 v249, s54, v244
	v_add_u32_e32 v212, s54, v245
	s_mov_b64 s[26:27], -1
	ds_read_b128 v[98:101], v249 offset:49152
	ds_read_b128 v[114:117], v249 offset:53248
	ds_read_b128 v[130:133], v249 offset:57344
	ds_read_b128 v[194:197], v249 offset:61440
	s_waitcnt lgkmcnt(0)
	v_mfma_f32_32x32x16_bf16 v[82:97], v[98:101], v[166:169], v[34:49]
	ds_read_b128 v[206:209], v212 offset:49152
	v_mfma_f32_32x32x16_bf16 v[98:113], v[114:117], v[166:169], v[50:65]
	ds_read_b128 v[198:201], v212 offset:53248
	s_add_i32 s40, s23, 3
	s_cmp_le_u32 s40, s16
	s_cselect_b64 s[26:27], -1, 0
	s_cmp_gt_u32 s40, s16
	s_cbranch_scc1 .LBB0_218
	s_mov_b32 s40, 0x4000
	s_add_i32 m0, s11, s40
	s_nop 0
	global_load_lds_dwordx4 v214, s[50:51]
.LBB0_218:
	v_mfma_f32_32x32x16_bf16 v[114:129], v[130:133], v[166:169], v[18:33]
	ds_read_b128 v[202:205], v212 offset:57344
	v_mfma_f32_32x32x16_bf16 v[130:145], v[194:197], v[166:169], v[2:17]
	ds_read_b128 v[194:197], v212 offset:61440
	s_waitcnt lgkmcnt(0)
	v_mfma_f32_32x32x16_bf16 v[82:97], v[206:209], v[174:177], v[82:97]
	v_add_u32_e32 v250, s54, v246
	ds_read_b128 v[206:209], v250 offset:49152
	v_mfma_f32_32x32x16_bf16 v[98:113], v[198:201], v[174:177], v[98:113]
	ds_read_b128 v[198:201], v250 offset:53248
	s_andn2_b64 vcc, exec, s[26:27]
	s_cbranch_vccnz .LBB0_220
	s_mov_b32 s26, 0x4000
	s_add_i32 s26, s11, s26
	s_add_i32 m0, s26, 0x2000
	s_nop 0
	global_load_lds_dwordx4 v214, s[4:5]
.LBB0_220:
	v_mfma_f32_32x32x16_bf16 v[114:129], v[202:205], v[174:177], v[114:129]
	ds_read_b128 v[202:205], v250 offset:57344
	v_mfma_f32_32x32x16_bf16 v[130:145], v[194:197], v[174:177], v[130:145]
	ds_read_b128 v[194:197], v250 offset:61440
	s_waitcnt lgkmcnt(0)
	v_mfma_f32_32x32x16_bf16 v[82:97], v[206:209], v[182:185], v[82:97]
	v_add_u32_e32 v250, s54, v247
	ds_read_b128 v[206:209], v250 offset:49152
	v_mfma_f32_32x32x16_bf16 v[98:113], v[198:201], v[182:185], v[98:113]
	ds_read_b128 v[198:201], v250 offset:53248
	v_cndmask_b32_e64 v224, 0, 1, s[88:89]
	v_cmp_ne_u32_e64 s[40:41], 1, v224
	s_andn2_b64 vcc, exec, s[88:89]
	s_cbranch_vccnz .LBB0_222
	s_mov_b32 s26, 0x0
	s_add_i32 s26, s11, s26
	s_add_i32 m0, s26, 0xc000
	s_nop 0
	global_load_lds_dwordx4 v216, s[0:1]
.LBB0_222:
	v_mfma_f32_32x32x16_bf16 v[114:129], v[202:205], v[182:185], v[114:129]
	ds_read_b128 v[202:205], v250 offset:57344
	v_mfma_f32_32x32x16_bf16 v[130:145], v[194:197], v[182:185], v[130:145]
	ds_read_b128 v[194:197], v250 offset:61440
	s_waitcnt lgkmcnt(0)
	v_mfma_f32_32x32x16_bf16 v[82:97], v[206:209], v[190:193], v[82:97]
	v_mfma_f32_32x32x16_bf16 v[98:113], v[198:201], v[190:193], v[98:113]
	s_and_b64 vcc, exec, s[40:41]
	s_cbranch_vccnz .LBB0_224
	s_mov_b32 s26, 0x0
	s_add_i32 s26, s11, s26
	s_add_i32 m0, s26, 0xe000
	s_nop 0
	global_load_lds_dwordx4 v216, s[52:53]

.Lotail_u1o:
	s_add_i32 s26, s23, -1
	s_cmp_lt_u32 s26, s16
	s_cbranch_scc1 .Low2_u1o
	s_waitcnt vmcnt(0)
	s_branch .LBB0_208
.Lr1u1_LBB0_164:
	s_add_i32 s22, s23, -1
	s_cmp_lt_u32 s22, s16
	s_cselect_b64 s[88:89], -1, 0
	s_waitcnt vmcnt(2)
.Lr1u1_LBB0_168:
	ds_read_b128 v[98:101], v239
	ds_read_b128 v[114:117], v239 offset:8192
	ds_read_b128 v[118:121], v240
	s_barrier
.Lr1u1_LBB0_174:
	s_mov_b32 s54, 0x0
	s_cmp_ge_u32 s23, s19
	s_cbranch_scc1 .Lr1u1_Lslow_u1e
.Lr1u1_LBB0_185:
	s_add_i32 s100, s11, 0x8000
	s_add_i32 s101, s11, 0x4000
	ds_read_b128 v[126:129], v244 offset:49152
	s_waitcnt lgkmcnt(1)
	v_mfma_f32_32x32x16_bf16 v[82:97], v[98:101], v[146:149], v[66:81]
	ds_read_b128 v[122:125], v240 offset:8192
	v_mfma_f32_32x32x16_bf16 v[98:113], v[114:117], v[146:149], v[66:81]
	ds_read_b128 v[114:117], v241
	v_mfma_f32_32x32x16_bf16 v[82:97], v[118:121], v[150:153], v[82:97]
	ds_read_b128 v[118:121], v241 offset:8192
	s_waitcnt lgkmcnt(0)
	v_mfma_f32_32x32x16_bf16 v[98:113], v[122:125], v[150:153], v[98:113]
	ds_read_b128 v[122:125], v243
	v_mfma_f32_32x32x16_bf16 v[82:97], v[114:117], v[154:157], v[82:97]
	ds_read_b128 v[114:117], v243 offset:8192
	v_mfma_f32_32x32x16_bf16 v[98:113], v[118:121], v[154:157], v[98:113]
	s_waitcnt lgkmcnt(0)
	v_mfma_f32_32x32x16_bf16 v[82:97], v[122:125], v[158:161], v[82:97]
	v_mfma_f32_32x32x16_bf16 v[98:113], v[114:117], v[158:161], v[98:113]
	s_nop 0
	ds_read_b128 v[122:125], v244 offset:53248
	ds_read_b128 v[118:121], v244 offset:57344
	ds_read_b128 v[114:117], v244 offset:61440
	s_add_i32 s22, s21, 64
	s_cmp_le_u32 s22, s20
	s_cbranch_scc0 .Lr1u1_Lnear_u1e
.Lr1u1_LBB0_188:
	v_mfma_f32_32x32x16_bf16 v[34:49], v[126:129], v[162:165], v[34:49]
	ds_read_b128 v[126:129], v245 offset:49152
	s_nop 0
	v_exp_f32_e32 v130, v82
	v_exp_f32_e32 v131, v83
	v_add_f32_e32 v132, v1, v130
	v_add_f32_e32 v133, v1, v131
	v_cvt_pk_bf16_f32 v166, v130, v131
	s_waitcnt lgkmcnt(3)
	v_mfma_f32_32x32x16_bf16 v[50:65], v[122:125], v[162:165], v[50:65]
	ds_read_b128 v[122:125], v245 offset:53248
	v_exp_f32_e32 v134, v84
	v_exp_f32_e32 v135, v85
	s_add_i32 s22, s23, 2
	v_add_f32_e32 v130, v132, v134
	v_add_f32_e32 v131, v133, v135
	v_cvt_pk_bf16_f32 v167, v134, v135
	s_mov_b32 m0, s100
	s_cmp_ge_u32 s22, s17
	s_cbranch_scc1 .Lr1u1_LBB0_190
	global_load_lds_dwordx4 v214, s[80:81]
	s_add_i32 m0, s100, 0x2000
	s_nop 0
	global_load_lds_dwordx4 v214, s[62:63]
.Lr1u1_LBB0_190:
	s_waitcnt lgkmcnt(2)
	v_mfma_f32_32x32x16_bf16 v[18:33], v[118:121], v[162:165], v[18:33]
	ds_read_b128 v[118:121], v245 offset:57344
	v_exp_f32_e32 v132, v86
	v_exp_f32_e32 v133, v87
	v_add_f32_e32 v130, v130, v132
	v_add_f32_e32 v131, v131, v133
	v_cvt_pk_bf16_f32 v168, v132, v133
	v_mfma_f32_32x32x16_bf16 v[2:17], v[114:117], v[162:165], v[2:17]
	ds_read_b128 v[114:117], v245 offset:61440
	v_exp_f32_e32 v132, v88
	v_exp_f32_e32 v133, v89
	v_add_f32_e32 v134, v130, v132
	v_add_f32_e32 v131, v131, v133
	v_cvt_pk_bf16_f32 v169, v132, v133
	s_waitcnt lgkmcnt(2)
	v_mfma_f32_32x32x16_bf16 v[34:49], v[126:129], v[170:173], v[34:49]
	ds_read_b128 v[126:129], v246 offset:49152
	v_exp_f32_e32 v132, v90
	v_exp_f32_e32 v133, v91
	v_add_f32_e32 v134, v134, v132
	v_add_f32_e32 v135, v131, v133
	v_cvt_pk_bf16_f32 v174, v132, v133
	v_mfma_f32_32x32x16_bf16 v[50:65], v[122:125], v[170:173], v[50:65]
	ds_read_b128 v[122:125], v246 offset:53248
	v_exp_f32_e32 v133, v92
	v_exp_f32_e32 v136, v93
	v_add_f32_e32 v131, v134, v133
	v_add_f32_e32 v132, v135, v136
	v_cvt_pk_bf16_f32 v175, v133, v136
.Lr1u1_LBB0_192:
	s_waitcnt lgkmcnt(2)
	v_mfma_f32_32x32x16_bf16 v[18:33], v[118:121], v[170:173], v[18:33]
	ds_read_b128 v[118:121], v246 offset:57344
	v_exp_f32_e32 v133, v94
	v_exp_f32_e32 v134, v95
	v_add_f32_e32 v131, v131, v133
	v_add_f32_e32 v132, v132, v134
	v_cvt_pk_bf16_f32 v176, v133, v134
	v_mfma_f32_32x32x16_bf16 v[2:17], v[114:117], v[170:173], v[2:17]
	ds_read_b128 v[114:117], v246 offset:61440
	v_exp_f32_e32 v130, v96
	v_exp_f32_e32 v133, v97
	v_add_f32_e32 v131, v131, v130
	v_add_f32_e32 v132, v132, v133
	v_cvt_pk_bf16_f32 v177, v130, v133
	s_waitcnt lgkmcnt(2)
	v_mfma_f32_32x32x16_bf16 v[34:49], v[126:129], v[178:181], v[34:49]
	ds_read_b128 v[126:129], v247 offset:49152
	v_exp_f32_e32 v133, v98
	v_exp_f32_e32 v134, v99
	v_add_f32_e32 v131, v131, v133
	v_add_f32_e32 v132, v132, v134
	v_cvt_pk_bf16_f32 v182, v133, v134
	v_mfma_f32_32x32x16_bf16 v[50:65], v[122:125], v[178:181], v[50:65]
	v_exp_f32_e32 v133, v100
	v_exp_f32_e32 v134, v101
	ds_read_b128 v[122:125], v247 offset:53248
	v_add_f32_e32 v131, v131, v133
	v_add_f32_e32 v132, v132, v134
	v_cvt_pk_bf16_f32 v183, v133, v134
	s_add_i32 m0, s101, 0xc000
	s_cmp_eq_u64 s[88:89], 0
	s_cbranch_scc1 .Lr1u1_LBB0_194
	global_load_lds_dwordx4 v216, s[96:97]
	s_add_i32 m0, s101, 0xe000
	s_nop 0
	global_load_lds_dwordx4 v216, s[58:59]
.Lr1u1_LBB0_194:
	s_waitcnt lgkmcnt(2)
	v_mfma_f32_32x32x16_bf16 v[18:33], v[118:121], v[178:181], v[18:33]
	ds_read_b128 v[118:121], v247 offset:57344
	v_exp_f32_e32 v133, v102
	v_exp_f32_e32 v134, v103
	v_add_f32_e32 v131, v131, v133
	v_add_f32_e32 v132, v132, v134
	v_cvt_pk_bf16_f32 v184, v133, v134
	v_mfma_f32_32x32x16_bf16 v[2:17], v[114:117], v[178:181], v[2:17]
	ds_read_b128 v[114:117], v247 offset:61440
	v_exp_f32_e32 v130, v104
	v_exp_f32_e32 v133, v105
	v_add_f32_e32 v131, v131, v130
	v_add_f32_e32 v132, v132, v133
	v_cvt_pk_bf16_f32 v185, v130, v133
	s_waitcnt lgkmcnt(2)
	v_mfma_f32_32x32x16_bf16 v[34:49], v[126:129], v[186:189], v[34:49]
	v_exp_f32_e32 v126, v106
	v_exp_f32_e32 v127, v107
	v_add_f32_e32 v128, v131, v126
	v_add_f32_e32 v129, v132, v127
	v_cvt_pk_bf16_f32 v190, v126, v127
	v_mfma_f32_32x32x16_bf16 v[50:65], v[122:125], v[186:189], v[50:65]
	v_exp_f32_e32 v124, v108
	v_exp_f32_e32 v125, v109
	v_add_f32_e32 v122, v128, v124
	v_add_f32_e32 v123, v129, v125
	v_cvt_pk_bf16_f32 v191, v124, v125

.Lr1u1_LBB0_214:
	s_add_i32 s40, s23, 1
	s_mov_b32 s54, 0xffff8000
	s_cmp_ge_u32 s40, s19
	s_cbranch_scc1 .Lr1u1_Lslow_u1o
.Lr1u1_LBB0_225:
	s_add_i32 s100, s11, 0x0
	s_add_i32 s101, s11, 0x8000
	ds_read_b128 v[126:129], v244 offset:16384
	s_waitcnt lgkmcnt(1)
	v_mfma_f32_32x32x16_bf16 v[82:97], v[98:101], v[146:149], v[66:81]
	ds_read_b128 v[122:125], v240 offset:24576
	v_mfma_f32_32x32x16_bf16 v[98:113], v[114:117], v[146:149], v[66:81]
	ds_read_b128 v[114:117], v241 offset:16384
	v_mfma_f32_32x32x16_bf16 v[82:97], v[118:121], v[150:153], v[82:97]
	ds_read_b128 v[118:121], v241 offset:24576
	s_waitcnt lgkmcnt(0)
	v_mfma_f32_32x32x16_bf16 v[98:113], v[122:125], v[150:153], v[98:113]
	ds_read_b128 v[122:125], v243 offset:16384
	v_mfma_f32_32x32x16_bf16 v[82:97], v[114:117], v[154:157], v[82:97]
	ds_read_b128 v[114:117], v243 offset:24576
	v_mfma_f32_32x32x16_bf16 v[98:113], v[118:121], v[154:157], v[98:113]
	s_waitcnt lgkmcnt(0)
	v_mfma_f32_32x32x16_bf16 v[82:97], v[122:125], v[158:161], v[82:97]
	v_mfma_f32_32x32x16_bf16 v[98:113], v[114:117], v[158:161], v[98:113]
	s_nop 0
	ds_read_b128 v[122:125], v244 offset:20480
	ds_read_b128 v[118:121], v244 offset:24576
	ds_read_b128 v[114:117], v244 offset:28672
	s_add_i32 s26, s21, 0x80
	s_cmp_le_u32 s26, s20
	s_cbranch_scc0 .Lr1u1_Lnear_u1o
.Lr1u1_LBB0_228:
	v_mfma_f32_32x32x16_bf16 v[34:49], v[126:129], v[166:169], v[34:49]
	ds_read_b128 v[126:129], v245 offset:16384
	s_nop 0
	v_exp_f32_e32 v130, v82
	v_exp_f32_e32 v131, v83
	v_add_f32_e32 v132, v1, v130
	v_add_f32_e32 v133, v1, v131
	v_cvt_pk_bf16_f32 v162, v130, v131
	s_waitcnt lgkmcnt(3)
	v_mfma_f32_32x32x16_bf16 v[50:65], v[122:125], v[166:169], v[50:65]
	ds_read_b128 v[122:125], v245 offset:20480
	v_exp_f32_e32 v130, v84
	v_exp_f32_e32 v131, v85
	s_add_i32 s23, s23, 3
	v_add_f32_e32 v132, v132, v130
	v_add_f32_e32 v133, v133, v131
	v_cvt_pk_bf16_f32 v163, v130, v131
	s_mov_b32 m0, s100
	s_cmp_gt_u32 s23, s16
	s_cbranch_scc1 .Lr1u1_LBB0_230
	global_load_lds_dwordx4 v214, s[50:51]
	s_add_i32 m0, s100, 0x2000
	s_nop 0
	global_load_lds_dwordx4 v214, s[4:5]
.Lr1u1_LBB0_230:
	s_waitcnt lgkmcnt(2)
	v_mfma_f32_32x32x16_bf16 v[18:33], v[118:121], v[166:169], v[18:33]
	ds_read_b128 v[118:121], v245 offset:24576
	v_exp_f32_e32 v134, v86
	v_exp_f32_e32 v135, v87
	v_add_f32_e32 v132, v132, v134
	v_add_f32_e32 v133, v133, v135
	v_cvt_pk_bf16_f32 v164, v134, v135
	v_mfma_f32_32x32x16_bf16 v[2:17], v[114:117], v[166:169], v[2:17]
	ds_read_b128 v[114:117], v245 offset:28672
	v_exp_f32_e32 v134, v88
	v_exp_f32_e32 v135, v89
	v_add_f32_e32 v136, v132, v134
	v_add_f32_e32 v133, v133, v135
	v_cvt_pk_bf16_f32 v165, v134, v135
	s_waitcnt lgkmcnt(2)
	v_mfma_f32_32x32x16_bf16 v[34:49], v[126:129], v[174:177], v[34:49]
	ds_read_b128 v[126:129], v246 offset:16384
	v_exp_f32_e32 v134, v90
	v_exp_f32_e32 v135, v91
	v_add_f32_e32 v136, v136, v134
	v_add_f32_e32 v137, v133, v135
	v_cvt_pk_bf16_f32 v170, v134, v135
	v_mfma_f32_32x32x16_bf16 v[50:65], v[122:125], v[174:177], v[50:65]
	ds_read_b128 v[122:125], v246 offset:20480
	v_exp_f32_e32 v135, v92
	v_exp_f32_e32 v138, v93
	v_add_f32_e32 v133, v136, v135
	v_add_f32_e32 v134, v137, v138
	v_cvt_pk_bf16_f32 v171, v135, v138
.Lr1u1_LBB0_232:
	s_waitcnt lgkmcnt(2)
	v_mfma_f32_32x32x16_bf16 v[18:33], v[118:121], v[174:177], v[18:33]
	ds_read_b128 v[118:121], v246 offset:24576
	v_exp_f32_e32 v130, v94
	v_exp_f32_e32 v131, v95
	v_add_f32_e32 v133, v133, v130
	v_add_f32_e32 v134, v134, v131
	v_cvt_pk_bf16_f32 v172, v130, v131
	v_mfma_f32_32x32x16_bf16 v[2:17], v[114:117], v[174:177], v[2:17]
	ds_read_b128 v[114:117], v246 offset:28672
	v_exp_f32_e32 v130, v96
	v_exp_f32_e32 v131, v97
	v_add_f32_e32 v133, v133, v130
	v_add_f32_e32 v134, v134, v131
	v_cvt_pk_bf16_f32 v173, v130, v131
	s_waitcnt lgkmcnt(2)
	v_mfma_f32_32x32x16_bf16 v[34:49], v[126:129], v[182:185], v[34:49]
	ds_read_b128 v[126:129], v247 offset:16384
	v_exp_f32_e32 v130, v98
	v_exp_f32_e32 v131, v99
	v_add_f32_e32 v133, v133, v130
	v_add_f32_e32 v134, v134, v131
	v_cvt_pk_bf16_f32 v178, v130, v131
	v_mfma_f32_32x32x16_bf16 v[50:65], v[122:125], v[182:185], v[50:65]
	v_exp_f32_e32 v130, v100
	v_exp_f32_e32 v131, v101
	ds_read_b128 v[122:125], v247 offset:20480
	v_add_f32_e32 v133, v133, v130
	v_add_f32_e32 v134, v134, v131
	v_cvt_pk_bf16_f32 v179, v130, v131
	s_add_i32 m0, s101, 0xc000
	s_cmp_eq_u64 s[88:89], 0
	s_cbranch_scc1 .Lr1u1_LBB0_234
	global_load_lds_dwordx4 v216, s[0:1]
	s_add_i32 m0, s101, 0xe000
	s_nop 0
	global_load_lds_dwordx4 v216, s[52:53]
.Lr1u1_LBB0_234:
	s_waitcnt lgkmcnt(2)
	v_mfma_f32_32x32x16_bf16 v[18:33], v[118:121], v[182:185], v[18:33]
	ds_read_b128 v[118:121], v247 offset:24576
	v_exp_f32_e32 v135, v102
	v_exp_f32_e32 v136, v103
	v_add_f32_e32 v133, v133, v135
	v_add_f32_e32 v134, v134, v136
	v_cvt_pk_bf16_f32 v180, v135, v136
	v_mfma_f32_32x32x16_bf16 v[2:17], v[114:117], v[182:185], v[2:17]
	ds_read_b128 v[114:117], v247 offset:28672
	v_exp_f32_e32 v132, v104
	v_exp_f32_e32 v135, v105
	v_add_f32_e32 v133, v133, v132
	v_add_f32_e32 v134, v134, v135
	v_cvt_pk_bf16_f32 v181, v132, v135
	s_waitcnt lgkmcnt(2)
	v_mfma_f32_32x32x16_bf16 v[34:49], v[126:129], v[190:193], v[34:49]
	v_exp_f32_e32 v126, v106
	v_exp_f32_e32 v127, v107
	v_add_f32_e32 v128, v133, v126
	v_add_f32_e32 v129, v134, v127
	v_cvt_pk_bf16_f32 v186, v126, v127
	v_mfma_f32_32x32x16_bf16 v[50:65], v[122:125], v[190:193], v[50:65]
	v_exp_f32_e32 v124, v108
	v_exp_f32_e32 v125, v109
	v_add_f32_e32 v122, v128, v124
	v_add_f32_e32 v123, v129, v125
	v_cvt_pk_bf16_f32 v187, v124, v125

.Lr1u1_Lhd_u1e:
	s_add_i32 s22, s23, 2
	s_cmp_ge_u32 s22, s17
	s_cbranch_scc1 .Lr1u1_LBB0_171
	s_mov_b32 s26, 0x8000
	s_add_i32 s26, s11, s26
	s_add_i32 s27, s26, 0x2000
	s_mov_b32 m0, s26
	s_nop 0
	global_load_lds_dwordx4 v214, s[80:81]
	s_mov_b32 m0, s27
	s_nop 0
	global_load_lds_dwordx4 v214, s[62:63]
.Lr1u1_LBB0_171:
	s_andn2_b64 vcc, exec, s[88:89]
	s_cbranch_vccnz .Lr1u1_LBB0_173
	s_mov_b32 s26, 0x4000
	s_add_i32 s26, s11, s26
	s_add_i32 m0, s26, 0xc000
	s_add_i32 s26, s26, 0xe000
	global_load_lds_dwordx4 v216, s[96:97]
	s_mov_b32 m0, s26
	s_nop 0
	global_load_lds_dwordx4 v216, s[58:59]

.Lr1u1_Lpvo_u1e:
	v_add_u32_e32 v249, s54, v244
	v_add_u32_e32 v212, s54, v245
	s_mov_b64 s[26:27], -1
	ds_read_b128 v[98:101], v249 offset:49152
	ds_read_b128 v[114:117], v249 offset:53248
	ds_read_b128 v[130:133], v249 offset:57344
	ds_read_b128 v[194:197], v249 offset:61440
	s_waitcnt lgkmcnt(0)
	v_mfma_f32_32x32x16_bf16 v[82:97], v[98:101], v[162:165], v[34:49]
	ds_read_b128 v[206:209], v212 offset:49152
	v_mfma_f32_32x32x16_bf16 v[98:113], v[114:117], v[162:165], v[50:65]
	ds_read_b128 v[198:201], v212 offset:53248
	s_add_i32 s22, s23, 2
	s_cmp_lt_u32 s22, s17
	s_cselect_b64 s[26:27], -1, 0
	s_cmp_ge_u32 s22, s17
	s_cbranch_scc1 .Lr1u1_LBB0_178
	s_mov_b32 s40, 0x8000
	s_add_i32 m0, s11, s40
	s_nop 0
	global_load_lds_dwordx4 v214, s[80:81]
.Lr1u1_LBB0_178:
	v_mfma_f32_32x32x16_bf16 v[114:129], v[130:133], v[162:165], v[18:33]
	ds_read_b128 v[202:205], v212 offset:57344
	v_mfma_f32_32x32x16_bf16 v[130:145], v[194:197], v[162:165], v[2:17]
	ds_read_b128 v[194:197], v212 offset:61440
	s_waitcnt lgkmcnt(0)
	v_mfma_f32_32x32x16_bf16 v[82:97], v[206:209], v[170:173], v[82:97]
	v_add_u32_e32 v250, s54, v246
	ds_read_b128 v[206:209], v250 offset:49152
	v_mfma_f32_32x32x16_bf16 v[98:113], v[198:201], v[170:173], v[98:113]
	ds_read_b128 v[198:201], v250 offset:53248
	s_andn2_b64 vcc, exec, s[26:27]
	s_cbranch_vccnz .Lr1u1_LBB0_180
	s_mov_b32 s26, 0x8000
	s_add_i32 s26, s11, s26
	s_add_i32 m0, s26, 0x2000
	s_nop 0
	global_load_lds_dwordx4 v214, s[62:63]
.Lr1u1_LBB0_180:
	v_mfma_f32_32x32x16_bf16 v[114:129], v[202:205], v[170:173], v[114:129]
	ds_read_b128 v[202:205], v250 offset:57344
	v_mfma_f32_32x32x16_bf16 v[130:145], v[194:197], v[170:173], v[130:145]
	ds_read_b128 v[194:197], v250 offset:61440
	s_waitcnt lgkmcnt(0)
	v_mfma_f32_32x32x16_bf16 v[82:97], v[206:209], v[178:181], v[82:97]
	v_add_u32_e32 v250, s54, v247
	ds_read_b128 v[206:209], v250 offset:49152
	v_mfma_f32_32x32x16_bf16 v[98:113], v[198:201], v[178:181], v[98:113]
	ds_read_b128 v[198:201], v250 offset:53248
	v_cndmask_b32_e64 v224, 0, 1, s[88:89]
	v_cmp_ne_u32_e64 s[40:41], 1, v224
	s_andn2_b64 vcc, exec, s[88:89]
	s_cbranch_vccnz .Lr1u1_LBB0_182
	s_mov_b32 s26, 0x4000
	s_add_i32 s26, s11, s26
	s_add_i32 m0, s26, 0xc000
	s_nop 0
	global_load_lds_dwordx4 v216, s[96:97]
.Lr1u1_LBB0_182:
	v_mfma_f32_32x32x16_bf16 v[114:129], v[202:205], v[178:181], v[114:129]
	ds_read_b128 v[202:205], v250 offset:57344
	v_mfma_f32_32x32x16_bf16 v[130:145], v[194:197], v[178:181], v[130:145]
	ds_read_b128 v[194:197], v250 offset:61440
	s_waitcnt lgkmcnt(0)
	v_mfma_f32_32x32x16_bf16 v[82:97], v[206:209], v[186:189], v[82:97]
	v_mfma_f32_32x32x16_bf16 v[98:113], v[198:201], v[186:189], v[98:113]
	s_and_b64 vcc, exec, s[40:41]
	s_cbranch_vccnz .Lr1u1_LBB0_184
	s_mov_b32 s26, 0x4000
	s_add_i32 s26, s11, s26
	s_add_i32 m0, s26, 0xe000
	s_nop 0
	global_load_lds_dwordx4 v216, s[58:59]

.Lr1u1_Lhd_u1o:
	s_add_i32 s26, s23, 3
	s_cmp_gt_u32 s26, s16
	s_cbranch_scc1 .Lr1u1_LBB0_211
	s_mov_b32 s26, 0x0
	s_add_i32 s26, s11, s26
	s_add_i32 s27, s26, 0x2000
	s_mov_b32 m0, s26
	s_nop 0
	global_load_lds_dwordx4 v214, s[50:51]
	s_mov_b32 m0, s27
	s_nop 0
	global_load_lds_dwordx4 v214, s[4:5]
.Lr1u1_LBB0_211:
	s_andn2_b64 vcc, exec, s[88:89]
	s_cbranch_vccnz .Lr1u1_LBB0_213
	s_mov_b32 s26, 0x8000
	s_add_i32 s26, s11, s26
	s_add_i32 m0, s26, 0xc000
	s_add_i32 s26, s26, 0xe000
	global_load_lds_dwordx4 v216, s[0:1]
	s_mov_b32 m0, s26
	s_nop 0
	global_load_lds_dwordx4 v216, s[52:53]

.Lr1u1_Lpvo_u1o:
	v_add_u32_e32 v249, s54, v244
	v_add_u32_e32 v212, s54, v245
	s_mov_b64 s[26:27], -1
	ds_read_b128 v[98:101], v249 offset:49152
	ds_read_b128 v[114:117], v249 offset:53248
	ds_read_b128 v[130:133], v249 offset:57344
	ds_read_b128 v[194:197], v249 offset:61440
	s_waitcnt lgkmcnt(0)
	v_mfma_f32_32x32x16_bf16 v[82:97], v[98:101], v[166:169], v[34:49]
	ds_read_b128 v[206:209], v212 offset:49152
	v_mfma_f32_32x32x16_bf16 v[98:113], v[114:117], v[166:169], v[50:65]
	ds_read_b128 v[198:201], v212 offset:53248
	s_add_i32 s40, s23, 3
	s_cmp_le_u32 s40, s16
	s_cselect_b64 s[26:27], -1, 0
	s_cmp_gt_u32 s40, s16
	s_cbranch_scc1 .Lr1u1_LBB0_218
	s_mov_b32 s40, 0x0
	s_add_i32 m0, s11, s40
	s_nop 0
	global_load_lds_dwordx4 v214, s[50:51]
.Lr1u1_LBB0_218:
	v_mfma_f32_32x32x16_bf16 v[114:129], v[130:133], v[166:169], v[18:33]
	ds_read_b128 v[202:205], v212 offset:57344
	v_mfma_f32_32x32x16_bf16 v[130:145], v[194:197], v[166:169], v[2:17]
	ds_read_b128 v[194:197], v212 offset:61440
	s_waitcnt lgkmcnt(0)
	v_mfma_f32_32x32x16_bf16 v[82:97], v[206:209], v[174:177], v[82:97]
	v_add_u32_e32 v250, s54, v246
	ds_read_b128 v[206:209], v250 offset:49152
	v_mfma_f32_32x32x16_bf16 v[98:113], v[198:201], v[174:177], v[98:113]
	ds_read_b128 v[198:201], v250 offset:53248
	s_andn2_b64 vcc, exec, s[26:27]
	s_cbranch_vccnz .Lr1u1_LBB0_220
	s_mov_b32 s26, 0x0
	s_add_i32 s26, s11, s26
	s_add_i32 m0, s26, 0x2000
	s_nop 0
	global_load_lds_dwordx4 v214, s[4:5]
.Lr1u1_LBB0_220:
	v_mfma_f32_32x32x16_bf16 v[114:129], v[202:205], v[174:177], v[114:129]
	ds_read_b128 v[202:205], v250 offset:57344
	v_mfma_f32_32x32x16_bf16 v[130:145], v[194:197], v[174:177], v[130:145]
	ds_read_b128 v[194:197], v250 offset:61440
	s_waitcnt lgkmcnt(0)
	v_mfma_f32_32x32x16_bf16 v[82:97], v[206:209], v[182:185], v[82:97]
	v_add_u32_e32 v250, s54, v247
	ds_read_b128 v[206:209], v250 offset:49152
	v_mfma_f32_32x32x16_bf16 v[98:113], v[198:201], v[182:185], v[98:113]
	ds_read_b128 v[198:201], v250 offset:53248
	v_cndmask_b32_e64 v224, 0, 1, s[88:89]
	v_cmp_ne_u32_e64 s[40:41], 1, v224
	s_andn2_b64 vcc, exec, s[88:89]
	s_cbranch_vccnz .Lr1u1_LBB0_222
	s_mov_b32 s26, 0x8000
	s_add_i32 s26, s11, s26
	s_add_i32 m0, s26, 0xc000
	s_nop 0
	global_load_lds_dwordx4 v216, s[0:1]
.Lr1u1_LBB0_222:
	v_mfma_f32_32x32x16_bf16 v[114:129], v[202:205], v[182:185], v[114:129]
	ds_read_b128 v[202:205], v250 offset:57344
	v_mfma_f32_32x32x16_bf16 v[130:145], v[194:197], v[182:185], v[130:145]
	ds_read_b128 v[194:197], v250 offset:61440
	s_waitcnt lgkmcnt(0)
	v_mfma_f32_32x32x16_bf16 v[82:97], v[206:209], v[190:193], v[82:97]
	v_mfma_f32_32x32x16_bf16 v[98:113], v[198:201], v[190:193], v[98:113]
	s_and_b64 vcc, exec, s[40:41]
	s_cbranch_vccnz .Lr1u1_LBB0_224
	s_mov_b32 s26, 0x8000
	s_add_i32 s26, s11, s26
	s_add_i32 m0, s26, 0xe000
	s_nop 0
	global_load_lds_dwordx4 v216, s[52:53]

.Lr1u1_Lotail_u1o:
	s_add_i32 s26, s23, -1
	s_cmp_lt_u32 s26, s16
	s_cbranch_scc1 .Lr1u1_Low2_u1o
	s_waitcnt vmcnt(0)
	s_branch .Lr1u1_LBB0_208
.Lr2u1_LBB0_164:
	s_add_i32 s22, s23, -1
	s_cmp_lt_u32 s22, s16
	s_cselect_b64 s[88:89], -1, 0
	s_waitcnt vmcnt(2)

.Lr2u1_LBB0_174:
	s_mov_b32 s54, 0xffffc000
	s_cmp_ge_u32 s23, s19
	s_cbranch_scc1 .Lr2u1_Lslow_u1e
.Lr2u1_LBB0_185:
	s_add_i32 s100, s11, 0x4000
	s_add_i32 s101, s11, 0x0
	ds_read_b128 v[126:129], v244 offset:32768
	s_waitcnt lgkmcnt(1)
	v_mfma_f32_32x32x16_bf16 v[82:97], v[98:101], v[146:149], v[66:81]
	ds_read_b128 v[122:125], v240 offset:40960
	v_mfma_f32_32x32x16_bf16 v[98:113], v[114:117], v[146:149], v[66:81]
	ds_read_b128 v[114:117], v241 offset:32768
	v_mfma_f32_32x32x16_bf16 v[82:97], v[118:121], v[150:153], v[82:97]
	ds_read_b128 v[118:121], v241 offset:40960
	s_waitcnt lgkmcnt(0)
	v_mfma_f32_32x32x16_bf16 v[98:113], v[122:125], v[150:153], v[98:113]
	ds_read_b128 v[122:125], v243 offset:32768
	v_mfma_f32_32x32x16_bf16 v[82:97], v[114:117], v[154:157], v[82:97]
	ds_read_b128 v[114:117], v243 offset:40960
	v_mfma_f32_32x32x16_bf16 v[98:113], v[118:121], v[154:157], v[98:113]
	s_waitcnt lgkmcnt(0)
	v_mfma_f32_32x32x16_bf16 v[82:97], v[122:125], v[158:161], v[82:97]
	v_mfma_f32_32x32x16_bf16 v[98:113], v[114:117], v[158:161], v[98:113]
	s_nop 0
	ds_read_b128 v[122:125], v244 offset:36864
	ds_read_b128 v[118:121], v244 offset:40960
	ds_read_b128 v[114:117], v244 offset:45056
	s_add_i32 s22, s21, 64
	s_cmp_le_u32 s22, s20
	s_cbranch_scc0 .Lr2u1_Lnear_u1e
.Lr2u1_LBB0_188:
	v_mfma_f32_32x32x16_bf16 v[34:49], v[126:129], v[162:165], v[34:49]
	ds_read_b128 v[126:129], v245 offset:32768
	s_nop 0
	v_exp_f32_e32 v130, v82
	v_exp_f32_e32 v131, v83
	v_add_f32_e32 v132, v1, v130
	v_add_f32_e32 v133, v1, v131
	v_cvt_pk_bf16_f32 v166, v130, v131
	s_waitcnt lgkmcnt(3)
	v_mfma_f32_32x32x16_bf16 v[50:65], v[122:125], v[162:165], v[50:65]
	ds_read_b128 v[122:125], v245 offset:36864
	v_exp_f32_e32 v134, v84
	v_exp_f32_e32 v135, v85
	s_add_i32 s22, s23, 2
	v_add_f32_e32 v130, v132, v134
	v_add_f32_e32 v131, v133, v135
	v_cvt_pk_bf16_f32 v167, v134, v135
	s_mov_b32 m0, s100
	s_cmp_ge_u32 s22, s17
	s_cbranch_scc1 .Lr2u1_LBB0_190
	global_load_lds_dwordx4 v214, s[80:81]
	s_add_i32 m0, s100, 0x2000
	s_nop 0
	global_load_lds_dwordx4 v214, s[62:63]
.Lr2u1_LBB0_190:
	s_waitcnt lgkmcnt(2)
	v_mfma_f32_32x32x16_bf16 v[18:33], v[118:121], v[162:165], v[18:33]
	ds_read_b128 v[118:121], v245 offset:40960
	v_exp_f32_e32 v132, v86
	v_exp_f32_e32 v133, v87
	v_add_f32_e32 v130, v130, v132
	v_add_f32_e32 v131, v131, v133
	v_cvt_pk_bf16_f32 v168, v132, v133
	v_mfma_f32_32x32x16_bf16 v[2:17], v[114:117], v[162:165], v[2:17]
	ds_read_b128 v[114:117], v245 offset:45056
	v_exp_f32_e32 v132, v88
	v_exp_f32_e32 v133, v89
	v_add_f32_e32 v134, v130, v132
	v_add_f32_e32 v131, v131, v133
	v_cvt_pk_bf16_f32 v169, v132, v133
	s_waitcnt lgkmcnt(2)
	v_mfma_f32_32x32x16_bf16 v[34:49], v[126:129], v[170:173], v[34:49]
	ds_read_b128 v[126:129], v246 offset:32768
	v_exp_f32_e32 v132, v90
	v_exp_f32_e32 v133, v91
	v_add_f32_e32 v134, v134, v132
	v_add_f32_e32 v135, v131, v133
	v_cvt_pk_bf16_f32 v174, v132, v133
	v_mfma_f32_32x32x16_bf16 v[50:65], v[122:125], v[170:173], v[50:65]
	ds_read_b128 v[122:125], v246 offset:36864
	v_exp_f32_e32 v133, v92
	v_exp_f32_e32 v136, v93
	v_add_f32_e32 v131, v134, v133
	v_add_f32_e32 v132, v135, v136
	v_cvt_pk_bf16_f32 v175, v133, v136
.Lr2u1_LBB0_192:
	s_waitcnt lgkmcnt(2)
	v_mfma_f32_32x32x16_bf16 v[18:33], v[118:121], v[170:173], v[18:33]
	ds_read_b128 v[118:121], v246 offset:40960
	v_exp_f32_e32 v133, v94
	v_exp_f32_e32 v134, v95
	v_add_f32_e32 v131, v131, v133
	v_add_f32_e32 v132, v132, v134
	v_cvt_pk_bf16_f32 v176, v133, v134
	v_mfma_f32_32x32x16_bf16 v[2:17], v[114:117], v[170:173], v[2:17]
	ds_read_b128 v[114:117], v246 offset:45056
	v_exp_f32_e32 v130, v96
	v_exp_f32_e32 v133, v97
	v_add_f32_e32 v131, v131, v130
	v_add_f32_e32 v132, v132, v133
	v_cvt_pk_bf16_f32 v177, v130, v133
	s_waitcnt lgkmcnt(2)
	v_mfma_f32_32x32x16_bf16 v[34:49], v[126:129], v[178:181], v[34:49]
	ds_read_b128 v[126:129], v247 offset:32768
	v_exp_f32_e32 v133, v98
	v_exp_f32_e32 v134, v99
	v_add_f32_e32 v131, v131, v133
	v_add_f32_e32 v132, v132, v134
	v_cvt_pk_bf16_f32 v182, v133, v134
	v_mfma_f32_32x32x16_bf16 v[50:65], v[122:125], v[178:181], v[50:65]
	v_exp_f32_e32 v133, v100
	v_exp_f32_e32 v134, v101
	ds_read_b128 v[122:125], v247 offset:36864
	v_add_f32_e32 v131, v131, v133
	v_add_f32_e32 v132, v132, v134
	v_cvt_pk_bf16_f32 v183, v133, v134
	s_add_i32 m0, s101, 0xc000
	s_cmp_eq_u64 s[88:89], 0
	s_cbranch_scc1 .Lr2u1_LBB0_194
	global_load_lds_dwordx4 v216, s[96:97]
	s_add_i32 m0, s101, 0xe000
	s_nop 0
	global_load_lds_dwordx4 v216, s[58:59]
.Lr2u1_LBB0_194:
	s_waitcnt lgkmcnt(2)
	v_mfma_f32_32x32x16_bf16 v[18:33], v[118:121], v[178:181], v[18:33]
	ds_read_b128 v[118:121], v247 offset:40960
	v_exp_f32_e32 v133, v102
	v_exp_f32_e32 v134, v103
	v_add_f32_e32 v131, v131, v133
	v_add_f32_e32 v132, v132, v134
	v_cvt_pk_bf16_f32 v184, v133, v134
	v_mfma_f32_32x32x16_bf16 v[2:17], v[114:117], v[178:181], v[2:17]
	ds_read_b128 v[114:117], v247 offset:45056
	v_exp_f32_e32 v130, v104
	v_exp_f32_e32 v133, v105
	v_add_f32_e32 v131, v131, v130
	v_add_f32_e32 v132, v132, v133
	v_cvt_pk_bf16_f32 v185, v130, v133
	s_waitcnt lgkmcnt(2)
	v_mfma_f32_32x32x16_bf16 v[34:49], v[126:129], v[186:189], v[34:49]
	v_exp_f32_e32 v126, v106
	v_exp_f32_e32 v127, v107
	v_add_f32_e32 v128, v131, v126
	v_add_f32_e32 v129, v132, v127
	v_cvt_pk_bf16_f32 v190, v126, v127
	v_mfma_f32_32x32x16_bf16 v[50:65], v[122:125], v[186:189], v[50:65]
	v_exp_f32_e32 v124, v108
	v_exp_f32_e32 v125, v109
	v_add_f32_e32 v122, v128, v124
	v_add_f32_e32 v123, v129, v125
	v_cvt_pk_bf16_f32 v191, v124, v125

.Lr2u1_LBB0_214:
	s_add_i32 s40, s23, 1
	s_mov_b32 s54, 0x0
	s_cmp_ge_u32 s40, s19
	s_cbranch_scc1 .Lr2u1_Lslow_u1o
.Lr2u1_LBB0_225:
	s_add_i32 s100, s11, 0x8000
	s_add_i32 s101, s11, 0x4000
	ds_read_b128 v[126:129], v244 offset:49152
	s_waitcnt lgkmcnt(1)
	v_mfma_f32_32x32x16_bf16 v[82:97], v[98:101], v[146:149], v[66:81]
	ds_read_b128 v[122:125], v240 offset:8192
	v_mfma_f32_32x32x16_bf16 v[98:113], v[114:117], v[146:149], v[66:81]
	ds_read_b128 v[114:117], v241
	v_mfma_f32_32x32x16_bf16 v[82:97], v[118:121], v[150:153], v[82:97]
	ds_read_b128 v[118:121], v241 offset:8192
	s_waitcnt lgkmcnt(0)
	v_mfma_f32_32x32x16_bf16 v[98:113], v[122:125], v[150:153], v[98:113]
	ds_read_b128 v[122:125], v243
	v_mfma_f32_32x32x16_bf16 v[82:97], v[114:117], v[154:157], v[82:97]
	ds_read_b128 v[114:117], v243 offset:8192
	v_mfma_f32_32x32x16_bf16 v[98:113], v[118:121], v[154:157], v[98:113]
	s_waitcnt lgkmcnt(0)
	v_mfma_f32_32x32x16_bf16 v[82:97], v[122:125], v[158:161], v[82:97]
	v_mfma_f32_32x32x16_bf16 v[98:113], v[114:117], v[158:161], v[98:113]
	s_nop 0
	ds_read_b128 v[122:125], v244 offset:53248
	ds_read_b128 v[118:121], v244 offset:57344
	ds_read_b128 v[114:117], v244 offset:61440
	s_add_i32 s26, s21, 0x80
	s_cmp_le_u32 s26, s20
	s_cbranch_scc0 .Lr2u1_Lnear_u1o
.Lr2u1_LBB0_228:
	v_mfma_f32_32x32x16_bf16 v[34:49], v[126:129], v[166:169], v[34:49]
	ds_read_b128 v[126:129], v245 offset:49152
	s_nop 0
	v_exp_f32_e32 v130, v82
	v_exp_f32_e32 v131, v83
	v_add_f32_e32 v132, v1, v130
	v_add_f32_e32 v133, v1, v131
	v_cvt_pk_bf16_f32 v162, v130, v131
	s_waitcnt lgkmcnt(3)
	v_mfma_f32_32x32x16_bf16 v[50:65], v[122:125], v[166:169], v[50:65]
	ds_read_b128 v[122:125], v245 offset:53248
	v_exp_f32_e32 v130, v84
	v_exp_f32_e32 v131, v85
	s_add_i32 s23, s23, 3
	v_add_f32_e32 v132, v132, v130
	v_add_f32_e32 v133, v133, v131
	v_cvt_pk_bf16_f32 v163, v130, v131
	s_mov_b32 m0, s100
	s_cmp_gt_u32 s23, s16
	s_cbranch_scc1 .Lr2u1_LBB0_230
	global_load_lds_dwordx4 v214, s[50:51]
	s_add_i32 m0, s100, 0x2000
	s_nop 0
	global_load_lds_dwordx4 v214, s[4:5]
.Lr2u1_LBB0_230:
	s_waitcnt lgkmcnt(2)
	v_mfma_f32_32x32x16_bf16 v[18:33], v[118:121], v[166:169], v[18:33]
	ds_read_b128 v[118:121], v245 offset:57344
	v_exp_f32_e32 v134, v86
	v_exp_f32_e32 v135, v87
	v_add_f32_e32 v132, v132, v134
	v_add_f32_e32 v133, v133, v135
	v_cvt_pk_bf16_f32 v164, v134, v135
	v_mfma_f32_32x32x16_bf16 v[2:17], v[114:117], v[166:169], v[2:17]
	ds_read_b128 v[114:117], v245 offset:61440
	v_exp_f32_e32 v134, v88
	v_exp_f32_e32 v135, v89
	v_add_f32_e32 v136, v132, v134
	v_add_f32_e32 v133, v133, v135
	v_cvt_pk_bf16_f32 v165, v134, v135
	s_waitcnt lgkmcnt(2)
	v_mfma_f32_32x32x16_bf16 v[34:49], v[126:129], v[174:177], v[34:49]
	ds_read_b128 v[126:129], v246 offset:49152
	v_exp_f32_e32 v134, v90
	v_exp_f32_e32 v135, v91
	v_add_f32_e32 v136, v136, v134
	v_add_f32_e32 v137, v133, v135
	v_cvt_pk_bf16_f32 v170, v134, v135
	v_mfma_f32_32x32x16_bf16 v[50:65], v[122:125], v[174:177], v[50:65]
	ds_read_b128 v[122:125], v246 offset:53248
	v_exp_f32_e32 v135, v92
	v_exp_f32_e32 v138, v93
	v_add_f32_e32 v133, v136, v135
	v_add_f32_e32 v134, v137, v138
	v_cvt_pk_bf16_f32 v171, v135, v138
.Lr2u1_LBB0_232:
	s_waitcnt lgkmcnt(2)
	v_mfma_f32_32x32x16_bf16 v[18:33], v[118:121], v[174:177], v[18:33]
	ds_read_b128 v[118:121], v246 offset:57344
	v_exp_f32_e32 v130, v94
	v_exp_f32_e32 v131, v95
	v_add_f32_e32 v133, v133, v130
	v_add_f32_e32 v134, v134, v131
	v_cvt_pk_bf16_f32 v172, v130, v131
	v_mfma_f32_32x32x16_bf16 v[2:17], v[114:117], v[174:177], v[2:17]
	ds_read_b128 v[114:117], v246 offset:61440
	v_exp_f32_e32 v130, v96
	v_exp_f32_e32 v131, v97
	v_add_f32_e32 v133, v133, v130
	v_add_f32_e32 v134, v134, v131
	v_cvt_pk_bf16_f32 v173, v130, v131
	s_waitcnt lgkmcnt(2)
	v_mfma_f32_32x32x16_bf16 v[34:49], v[126:129], v[182:185], v[34:49]
	ds_read_b128 v[126:129], v247 offset:49152
	v_exp_f32_e32 v130, v98
	v_exp_f32_e32 v131, v99
	v_add_f32_e32 v133, v133, v130
	v_add_f32_e32 v134, v134, v131
	v_cvt_pk_bf16_f32 v178, v130, v131
	v_mfma_f32_32x32x16_bf16 v[50:65], v[122:125], v[182:185], v[50:65]
	v_exp_f32_e32 v130, v100
	v_exp_f32_e32 v131, v101
	ds_read_b128 v[122:125], v247 offset:53248
	v_add_f32_e32 v133, v133, v130
	v_add_f32_e32 v134, v134, v131
	v_cvt_pk_bf16_f32 v179, v130, v131
	s_add_i32 m0, s101, 0xc000
	s_cmp_eq_u64 s[88:89], 0
	s_cbranch_scc1 .Lr2u1_LBB0_234
	global_load_lds_dwordx4 v216, s[0:1]
	s_add_i32 m0, s101, 0xe000
	s_nop 0
	global_load_lds_dwordx4 v216, s[52:53]
.Lr2u1_LBB0_234:
	s_waitcnt lgkmcnt(2)
	v_mfma_f32_32x32x16_bf16 v[18:33], v[118:121], v[182:185], v[18:33]
	ds_read_b128 v[118:121], v247 offset:57344
	v_exp_f32_e32 v135, v102
	v_exp_f32_e32 v136, v103
	v_add_f32_e32 v133, v133, v135
	v_add_f32_e32 v134, v134, v136
	v_cvt_pk_bf16_f32 v180, v135, v136
	v_mfma_f32_32x32x16_bf16 v[2:17], v[114:117], v[182:185], v[2:17]
	ds_read_b128 v[114:117], v247 offset:61440
	v_exp_f32_e32 v132, v104
	v_exp_f32_e32 v135, v105
	v_add_f32_e32 v133, v133, v132
	v_add_f32_e32 v134, v134, v135
	v_cvt_pk_bf16_f32 v181, v132, v135
	s_waitcnt lgkmcnt(2)
	v_mfma_f32_32x32x16_bf16 v[34:49], v[126:129], v[190:193], v[34:49]
	v_exp_f32_e32 v126, v106
	v_exp_f32_e32 v127, v107
	v_add_f32_e32 v128, v133, v126
	v_add_f32_e32 v129, v134, v127
	v_cvt_pk_bf16_f32 v186, v126, v127
	v_mfma_f32_32x32x16_bf16 v[50:65], v[122:125], v[190:193], v[50:65]
	v_exp_f32_e32 v124, v108
	v_exp_f32_e32 v125, v109
	v_add_f32_e32 v122, v128, v124
	v_add_f32_e32 v123, v129, v125
	v_cvt_pk_bf16_f32 v187, v124, v125

.Lr2u1_Lhd_u1e:
	s_add_i32 s22, s23, 2
	s_cmp_ge_u32 s22, s17
	s_cbranch_scc1 .Lr2u1_LBB0_171
	s_mov_b32 s26, 0x4000
	s_add_i32 s26, s11, s26
	s_add_i32 s27, s26, 0x2000
	s_mov_b32 m0, s26
	s_nop 0
	global_load_lds_dwordx4 v214, s[80:81]
	s_mov_b32 m0, s27
	s_nop 0
	global_load_lds_dwordx4 v214, s[62:63]
.Lr2u1_LBB0_171:
	s_andn2_b64 vcc, exec, s[88:89]
	s_cbranch_vccnz .Lr2u1_LBB0_173
	s_mov_b32 s26, 0x0
	s_add_i32 s26, s11, s26
	s_add_i32 m0, s26, 0xc000
	s_add_i32 s26, s26, 0xe000
	global_load_lds_dwordx4 v216, s[96:97]
	s_mov_b32 m0, s26
	s_nop 0
	global_load_lds_dwordx4 v216, s[58:59]

.Lr2u1_Lpvo_u1e:
	v_add_u32_e32 v249, s54, v244
	v_add_u32_e32 v212, s54, v245
	s_mov_b64 s[26:27], -1
	ds_read_b128 v[98:101], v249 offset:49152
	ds_read_b128 v[114:117], v249 offset:53248
	ds_read_b128 v[130:133], v249 offset:57344
	ds_read_b128 v[194:197], v249 offset:61440
	s_waitcnt lgkmcnt(0)
	v_mfma_f32_32x32x16_bf16 v[82:97], v[98:101], v[162:165], v[34:49]
	ds_read_b128 v[206:209], v212 offset:49152
	v_mfma_f32_32x32x16_bf16 v[98:113], v[114:117], v[162:165], v[50:65]
	ds_read_b128 v[198:201], v212 offset:53248
	s_add_i32 s22, s23, 2
	s_cmp_lt_u32 s22, s17
	s_cselect_b64 s[26:27], -1, 0
	s_cmp_ge_u32 s22, s17
	s_cbranch_scc1 .Lr2u1_LBB0_178
	s_mov_b32 s40, 0x4000
	s_add_i32 m0, s11, s40
	s_nop 0
	global_load_lds_dwordx4 v214, s[80:81]
.Lr2u1_LBB0_178:
	v_mfma_f32_32x32x16_bf16 v[114:129], v[130:133], v[162:165], v[18:33]
	ds_read_b128 v[202:205], v212 offset:57344
	v_mfma_f32_32x32x16_bf16 v[130:145], v[194:197], v[162:165], v[2:17]
	ds_read_b128 v[194:197], v212 offset:61440
	s_waitcnt lgkmcnt(0)
	v_mfma_f32_32x32x16_bf16 v[82:97], v[206:209], v[170:173], v[82:97]
	v_add_u32_e32 v250, s54, v246
	ds_read_b128 v[206:209], v250 offset:49152
	v_mfma_f32_32x32x16_bf16 v[98:113], v[198:201], v[170:173], v[98:113]
	ds_read_b128 v[198:201], v250 offset:53248
	s_andn2_b64 vcc, exec, s[26:27]
	s_cbranch_vccnz .Lr2u1_LBB0_180
	s_mov_b32 s26, 0x4000
	s_add_i32 s26, s11, s26
	s_add_i32 m0, s26, 0x2000
	s_nop 0
	global_load_lds_dwordx4 v214, s[62:63]
.Lr2u1_LBB0_180:
	v_mfma_f32_32x32x16_bf16 v[114:129], v[202:205], v[170:173], v[114:129]
	ds_read_b128 v[202:205], v250 offset:57344
	v_mfma_f32_32x32x16_bf16 v[130:145], v[194:197], v[170:173], v[130:145]
	ds_read_b128 v[194:197], v250 offset:61440
	s_waitcnt lgkmcnt(0)
	v_mfma_f32_32x32x16_bf16 v[82:97], v[206:209], v[178:181], v[82:97]
	v_add_u32_e32 v250, s54, v247
	ds_read_b128 v[206:209], v250 offset:49152
	v_mfma_f32_32x32x16_bf16 v[98:113], v[198:201], v[178:181], v[98:113]
	ds_read_b128 v[198:201], v250 offset:53248
	v_cndmask_b32_e64 v224, 0, 1, s[88:89]
	v_cmp_ne_u32_e64 s[40:41], 1, v224
	s_andn2_b64 vcc, exec, s[88:89]
	s_cbranch_vccnz .Lr2u1_LBB0_182
	s_mov_b32 s26, 0x0
	s_add_i32 s26, s11, s26
	s_add_i32 m0, s26, 0xc000
	s_nop 0
	global_load_lds_dwordx4 v216, s[96:97]
.Lr2u1_LBB0_182:
	v_mfma_f32_32x32x16_bf16 v[114:129], v[202:205], v[178:181], v[114:129]
	ds_read_b128 v[202:205], v250 offset:57344
	v_mfma_f32_32x32x16_bf16 v[130:145], v[194:197], v[178:181], v[130:145]
	ds_read_b128 v[194:197], v250 offset:61440
	s_waitcnt lgkmcnt(0)
	v_mfma_f32_32x32x16_bf16 v[82:97], v[206:209], v[186:189], v[82:97]
	v_mfma_f32_32x32x16_bf16 v[98:113], v[198:201], v[186:189], v[98:113]
	s_and_b64 vcc, exec, s[40:41]
	s_cbranch_vccnz .Lr2u1_LBB0_184
	s_mov_b32 s26, 0x0
	s_add_i32 s26, s11, s26
	s_add_i32 m0, s26, 0xe000
	s_nop 0
	global_load_lds_dwordx4 v216, s[58:59]

.Lr2u1_Lhd_u1o:
	s_add_i32 s26, s23, 3
	s_cmp_gt_u32 s26, s16
	s_cbranch_scc1 .Lr2u1_LBB0_211
	s_mov_b32 s26, 0x8000
	s_add_i32 s26, s11, s26
	s_add_i32 s27, s26, 0x2000
	s_mov_b32 m0, s26
	s_nop 0
	global_load_lds_dwordx4 v214, s[50:51]
	s_mov_b32 m0, s27
	s_nop 0
	global_load_lds_dwordx4 v214, s[4:5]
.Lr2u1_LBB0_211:
	s_andn2_b64 vcc, exec, s[88:89]
	s_cbranch_vccnz .Lr2u1_LBB0_213
	s_mov_b32 s26, 0x4000
	s_add_i32 s26, s11, s26
	s_add_i32 m0, s26, 0xc000
	s_add_i32 s26, s26, 0xe000
	global_load_lds_dwordx4 v216, s[0:1]
	s_mov_b32 m0, s26
	s_nop 0
	global_load_lds_dwordx4 v216, s[52:53]

.Lr2u1_Lpvo_u1o:
	v_add_u32_e32 v249, s54, v244
	v_add_u32_e32 v212, s54, v245
	s_mov_b64 s[26:27], -1
	ds_read_b128 v[98:101], v249 offset:49152
	ds_read_b128 v[114:117], v249 offset:53248
	ds_read_b128 v[130:133], v249 offset:57344
	ds_read_b128 v[194:197], v249 offset:61440
	s_waitcnt lgkmcnt(0)
	v_mfma_f32_32x32x16_bf16 v[82:97], v[98:101], v[166:169], v[34:49]
	ds_read_b128 v[206:209], v212 offset:49152
	v_mfma_f32_32x32x16_bf16 v[98:113], v[114:117], v[166:169], v[50:65]
	ds_read_b128 v[198:201], v212 offset:53248
	s_add_i32 s40, s23, 3
	s_cmp_le_u32 s40, s16
	s_cselect_b64 s[26:27], -1, 0
	s_cmp_gt_u32 s40, s16
	s_cbranch_scc1 .Lr2u1_LBB0_218
	s_mov_b32 s40, 0x8000
	s_add_i32 m0, s11, s40
	s_nop 0
	global_load_lds_dwordx4 v214, s[50:51]
.Lr2u1_LBB0_218:
	v_mfma_f32_32x32x16_bf16 v[114:129], v[130:133], v[166:169], v[18:33]
	ds_read_b128 v[202:205], v212 offset:57344
	v_mfma_f32_32x32x16_bf16 v[130:145], v[194:197], v[166:169], v[2:17]
	ds_read_b128 v[194:197], v212 offset:61440
	s_waitcnt lgkmcnt(0)
	v_mfma_f32_32x32x16_bf16 v[82:97], v[206:209], v[174:177], v[82:97]
	v_add_u32_e32 v250, s54, v246
	ds_read_b128 v[206:209], v250 offset:49152
	v_mfma_f32_32x32x16_bf16 v[98:113], v[198:201], v[174:177], v[98:113]
	ds_read_b128 v[198:201], v250 offset:53248
	s_andn2_b64 vcc, exec, s[26:27]
	s_cbranch_vccnz .Lr2u1_LBB0_220
	s_mov_b32 s26, 0x8000
	s_add_i32 s26, s11, s26
	s_add_i32 m0, s26, 0x2000
	s_nop 0
	global_load_lds_dwordx4 v214, s[4:5]
.Lr2u1_LBB0_220:
	v_mfma_f32_32x32x16_bf16 v[114:129], v[202:205], v[174:177], v[114:129]
	ds_read_b128 v[202:205], v250 offset:57344
	v_mfma_f32_32x32x16_bf16 v[130:145], v[194:197], v[174:177], v[130:145]
	ds_read_b128 v[194:197], v250 offset:61440
	s_waitcnt lgkmcnt(0)
	v_mfma_f32_32x32x16_bf16 v[82:97], v[206:209], v[182:185], v[82:97]
	v_add_u32_e32 v250, s54, v247
	ds_read_b128 v[206:209], v250 offset:49152
	v_mfma_f32_32x32x16_bf16 v[98:113], v[198:201], v[182:185], v[98:113]
	ds_read_b128 v[198:201], v250 offset:53248
	v_cndmask_b32_e64 v224, 0, 1, s[88:89]
	v_cmp_ne_u32_e64 s[40:41], 1, v224
	s_andn2_b64 vcc, exec, s[88:89]
	s_cbranch_vccnz .Lr2u1_LBB0_222
	s_mov_b32 s26, 0x4000
	s_add_i32 s26, s11, s26
	s_add_i32 m0, s26, 0xc000
	s_nop 0
	global_load_lds_dwordx4 v216, s[0:1]
.Lr2u1_LBB0_222:
	v_mfma_f32_32x32x16_bf16 v[114:129], v[202:205], v[182:185], v[114:129]
	ds_read_b128 v[202:205], v250 offset:57344
	v_mfma_f32_32x32x16_bf16 v[130:145], v[194:197], v[182:185], v[130:145]
	ds_read_b128 v[194:197], v250 offset:61440
	s_waitcnt lgkmcnt(0)
	v_mfma_f32_32x32x16_bf16 v[82:97], v[206:209], v[190:193], v[82:97]
	v_mfma_f32_32x32x16_bf16 v[98:113], v[198:201], v[190:193], v[98:113]
	s_and_b64 vcc, exec, s[40:41]
	s_cbranch_vccnz .Lr2u1_LBB0_224
	s_mov_b32 s26, 0x4000
	s_add_i32 s26, s11, s26
	s_add_i32 m0, s26, 0xe000
	s_nop 0
	global_load_lds_dwordx4 v216, s[52:53]

.LBB0_266:
	s_nop 6
	v_max_f32_e32 v0, v19, v19
	v_max_f32_e32 v39, v3, v3
	v_max_f32_e32 v0, v39, v0
	v_max3_f32 v0, v2, v18, v0
	v_max3_f32 v39, v20, v5, v21
	v_max3_f32 v0, v0, v4, v39
	v_max3_f32 v39, v22, v7, v23
	v_max3_f32 v0, v0, v6, v39
	v_max3_f32 v39, v24, v9, v25
	v_max3_f32 v0, v0, v8, v39
	v_max3_f32 v39, v26, v11, v27
	v_max3_f32 v0, v0, v10, v39
	v_max3_f32 v39, v28, v13, v29
	v_max3_f32 v0, v0, v12, v39
	v_max3_f32 v39, v30, v15, v31
	v_max3_f32 v0, v0, v14, v39
	v_max3_f32 v39, v32, v17, v33
	v_max3_f32 v0, v0, v16, v39
	v_mov_b32_e32 v39, v0
	s_nop 1
	v_permlane32_swap_b32_e32 v0, v39
	v_max_f32_e32 v39, v39, v39
	v_max_f32_e32 v0, v0, v0
	v_max_f32_e32 v213, v0, v39
	v_sub_f32_e32 v0, v2, v213
	v_exp_f32_e32 v40, v0
	v_sub_f32_e32 v0, v18, v213
	v_exp_f32_e32 v41, v0
	v_sub_f32_e32 v0, v3, v213
	v_sub_f32_e32 v2, v19, v213
	v_exp_f32_e32 v0, v0
	v_exp_f32_e32 v2, v2
	v_add_f32_e32 v3, v41, v40
	s_movk_i32 s27, 0x510
	v_cvt_pk_bf16_f32 v162, v40, v0
	v_pk_add_f32 v[18:19], v[2:3], v[0:1]
	v_sub_f32_e32 v3, v4, v213
	v_sub_f32_e32 v4, v20, v213
	v_pk_add_f32 v[18:19], v[18:19], v[18:19] op_sel_hi:[0,1]
	v_exp_f32_e32 v43, v4
	v_sub_f32_e32 v4, v5, v213
	v_exp_f32_e32 v3, v3
	v_exp_f32_e32 v18, v4
	v_sub_f32_e32 v4, v21, v213
	v_exp_f32_e32 v4, v4
	v_add_f32_e32 v5, v43, v3
	v_xad_u32 v0, v37, -1, v236
	v_cvt_pk_bf16_f32 v178, v41, v2
	v_pk_add_f32 v[20:21], v[4:5], v[18:19]
	v_sub_f32_e32 v5, v6, v213
	v_sub_f32_e32 v6, v22, v213
	v_pk_add_f32 v[20:21], v[20:21], v[20:21] op_sel_hi:[0,1]
	v_exp_f32_e32 v19, v6
	v_sub_f32_e32 v6, v7, v213
	v_exp_f32_e32 v5, v5
	v_exp_f32_e32 v20, v6
	v_sub_f32_e32 v6, v23, v213
	v_exp_f32_e32 v6, v6
	v_add_f32_e32 v7, v19, v5
	v_and_b32_e32 v0, 3, v0
	v_mov_b32_e32 v2, s31
	v_pk_add_f32 v[22:23], v[6:7], v[20:21]
	v_sub_f32_e32 v7, v8, v213
	v_sub_f32_e32 v8, v24, v213
	v_pk_add_f32 v[22:23], v[22:23], v[22:23] op_sel_hi:[0,1]
	v_exp_f32_e32 v21, v8
	v_sub_f32_e32 v8, v9, v213
	v_exp_f32_e32 v7, v7
	v_exp_f32_e32 v22, v8
	v_sub_f32_e32 v8, v25, v213
	v_exp_f32_e32 v8, v8
	v_add_f32_e32 v9, v21, v7
	s_add_i32 s20, s20, s56
	v_mad_u32_u24 v244, v0, s27, v2
	v_pk_add_f32 v[24:25], v[8:9], v[22:23]
	v_sub_f32_e32 v9, v10, v213
	v_sub_f32_e32 v10, v26, v213
	v_pk_add_f32 v[24:25], v[24:25], v[24:25] op_sel_hi:[0,1]
	v_exp_f32_e32 v23, v10
	v_sub_f32_e32 v10, v11, v213
	v_exp_f32_e32 v9, v9
	v_exp_f32_e32 v24, v10
	v_sub_f32_e32 v10, v27, v213
	v_exp_f32_e32 v10, v10
	v_add_f32_e32 v11, v23, v9
	v_add_u32_e32 v2, s20, v233
	v_cvt_pk_bf16_f32 v163, v3, v18
	v_pk_add_f32 v[26:27], v[10:11], v[24:25]
	v_sub_f32_e32 v11, v12, v213
	v_sub_f32_e32 v12, v28, v213
	v_pk_add_f32 v[26:27], v[26:27], v[26:27] op_sel_hi:[0,1]
	v_exp_f32_e32 v25, v12
	v_sub_f32_e32 v12, v13, v213
	v_exp_f32_e32 v11, v11
	v_exp_f32_e32 v26, v12
	v_sub_f32_e32 v12, v29, v213
	v_exp_f32_e32 v12, v12
	v_add_f32_e32 v13, v25, v11
	v_ashrrev_i32_e32 v3, 31, v2
	v_lshlrev_b64 v[2:3], 12, v[2:3]
	v_pk_add_f32 v[28:29], v[12:13], v[26:27]
	v_sub_f32_e32 v13, v14, v213
	v_sub_f32_e32 v14, v30, v213
	v_pk_add_f32 v[28:29], v[28:29], v[28:29] op_sel_hi:[0,1]
	v_exp_f32_e32 v27, v14
	v_sub_f32_e32 v14, v15, v213
	v_exp_f32_e32 v13, v13
	v_exp_f32_e32 v28, v14
	v_sub_f32_e32 v14, v31, v213
	v_exp_f32_e32 v14, v14
	v_sub_f32_e32 v15, v16, v213
	v_exp_f32_e32 v48, v15
	v_sub_f32_e32 v15, v32, v213
	v_exp_f32_e32 v32, v15
	v_add_f32_e32 v15, v27, v13
	v_pk_add_f32 v[30:31], v[14:15], v[28:29]
	v_and_b32_e32 v0, 15, v34
	v_pk_add_f32 v[30:31], v[30:31], v[30:31] op_sel_hi:[0,1]
	v_sub_f32_e32 v15, v17, v213
	v_or_b32_e32 v2, s37, v2
	v_lshlrev_b32_e32 v0, 4, v0
	s_add_i32 s21, s21, s36
	v_exp_f32_e32 v30, v15
	v_sub_f32_e32 v15, v33, v213
	v_lshl_add_u64 v[214:215], v[2:3], 0, v[0:1]
	v_add_u32_e32 v2, s21, v36
	v_and_b32_e32 v39, 7, v38
	v_bitop3_b32 v44, v38, v234, 7 bitop3:0x6c
	v_exp_f32_e32 v38, v15
	v_ashrrev_i32_e32 v3, 31, v2
	v_lshlrev_b64 v[2:3], 15, v[2:3]
	v_and_b32_e32 v0, 7, v35
	s_and_b32 s26, s47, 15
	v_lshl_or_b32 v2, v0, 4, v2
	v_sub_u32_e32 v0, v236, v235
	v_lshlrev_b32_e32 v42, 7, v235
	v_bitop3_b32 v45, v234, v39, 2 bitop3:0x36
	v_bitop3_b32 v46, v234, v39, 4 bitop3:0x36
	v_bitop3_b32 v47, v234, v39, 6 bitop3:0x36
	s_lshl_b32 s26, s26, 7
	v_add_f32_e32 v39, v32, v48
	v_cvt_pk_bf16_f32 v188, v27, v14
	v_subrev_u32_e32 v0, s28, v0
	v_mov_b32_e32 v14, v1
	v_mov_b32_e32 v15, v1
	s_lshl_b32 s17, s46, 1
	s_lshr_b32 s19, s16, 6
	v_pk_add_f32 v[16:17], v[38:39], v[30:31]
	v_cvt_pk_bf16_f32 v164, v5, v20
	v_cvt_pk_bf16_f32 v165, v7, v22
	v_cvt_pk_bf16_f32 v170, v9, v24
	v_cvt_pk_bf16_f32 v171, v11, v26
	v_cvt_pk_bf16_f32 v172, v13, v28
	v_cvt_pk_bf16_f32 v173, v48, v30
	v_cvt_pk_bf16_f32 v179, v43, v4
	v_cvt_pk_bf16_f32 v180, v19, v6
	v_cvt_pk_bf16_f32 v181, v21, v8
	v_cvt_pk_bf16_f32 v186, v23, v10
	v_cvt_pk_bf16_f32 v187, v25, v12
	v_cvt_pk_bf16_f32 v189, v32, v38
	v_lshl_or_b32 v245, v44, 4, v42
	v_lshl_or_b32 v246, v45, 4, v42
	v_lshl_or_b32 v247, v46, 4, v42
	v_lshl_or_b32 v248, v47, 4, v42
	v_lshl_add_u64 v[216:217], v[2:3], 0, s[44:45]
	v_subrev_u32_e32 v249, s26, v0
	v_mov_b32_e32 v0, v1
	v_mov_b32_e32 v2, v1
	v_mov_b32_e32 v3, v1
	v_mov_b32_e32 v4, v1
	v_mov_b32_e32 v5, v1
	v_mov_b32_e32 v6, v1
	v_mov_b32_e32 v7, v1
	v_mov_b32_e32 v8, v1
	v_mov_b32_e32 v9, v1
	v_mov_b32_e32 v10, v1
	v_mov_b32_e32 v11, v1
	v_mov_b32_e32 v12, v1
	v_mov_b32_e32 v13, v1
	v_mov_b64_e32 v[64:65], v[14:15]
	v_mov_b64_e32 v[48:49], v[14:15]
	v_mov_b64_e32 v[32:33], v[14:15]
	s_add_i32 s18, s17, 2
	s_add_i32 s19, s19, 1
	v_xor_b32_e32 v66, 0x80000000, v213
	v_add_f32_e32 v243, v16, v17
	v_mov_b64_e32 v[62:63], v[12:13]
	v_mov_b64_e32 v[60:61], v[10:11]
	v_mov_b64_e32 v[58:59], v[8:9]
	v_mov_b64_e32 v[56:57], v[6:7]
	v_mov_b64_e32 v[54:55], v[4:5]
	v_mov_b64_e32 v[52:53], v[2:3]
	v_mov_b64_e32 v[50:51], v[0:1]
	v_mov_b64_e32 v[46:47], v[12:13]
	v_mov_b64_e32 v[44:45], v[10:11]
	v_mov_b64_e32 v[42:43], v[8:9]
	v_mov_b64_e32 v[40:41], v[6:7]
	v_mov_b64_e32 v[38:39], v[4:5]
	v_mov_b64_e32 v[36:37], v[2:3]
	v_mov_b64_e32 v[34:35], v[0:1]
	v_mov_b64_e32 v[30:31], v[12:13]
	v_mov_b64_e32 v[28:29], v[10:11]
	v_mov_b64_e32 v[26:27], v[8:9]
	v_mov_b64_e32 v[24:25], v[6:7]
	v_mov_b64_e32 v[22:23], v[4:5]
	v_mov_b64_e32 v[20:21], v[2:3]
	v_mov_b64_e32 v[18:19], v[0:1]
	v_mov_b64_e32 v[16:17], v[14:15]
	s_mov_b32 s22, 1
	s_mov_b32 s23, 0x8000
	s_min_u32 s19, s18, s19
	v_mov_b32_e32 v67, v66
	v_mov_b32_e32 v68, v66
	v_mov_b32_e32 v69, v66
	v_mov_b32_e32 v70, v66
	v_mov_b32_e32 v71, v66
	v_mov_b32_e32 v72, v66
	v_mov_b32_e32 v73, v66
	v_mov_b32_e32 v74, v66
	v_mov_b32_e32 v75, v66
	v_mov_b32_e32 v76, v66
	v_mov_b32_e32 v77, v66
	v_mov_b32_e32 v78, v66
	v_mov_b32_e32 v79, v66
	v_mov_b32_e32 v80, v66
	v_mov_b32_e32 v81, v66
	s_mov_b32 s28, 0
	s_movk_i32 s20, 0xf0
	v_mov_b32_e32 v166, 0
	v_mov_b32_e32 v167, 0
	v_mov_b32_e32 v168, 0
	v_mov_b32_e32 v169, 0
	v_mov_b32_e32 v174, 0
	v_mov_b32_e32 v175, 0
	v_mov_b32_e32 v176, 0
	v_mov_b32_e32 v177, 0
	v_mov_b32_e32 v182, 0
	v_mov_b32_e32 v183, 0
	v_mov_b32_e32 v184, 0
	v_mov_b32_e32 v185, 0
	v_mov_b32_e32 v190, 0
	v_mov_b32_e32 v191, 0
	v_mov_b32_e32 v192, 0
	v_mov_b32_e32 v193, 0
	v_mov_b64_e32 v[14:15], v[12:13]
	v_mov_b64_e32 v[12:13], v[10:11]
	v_mov_b64_e32 v[10:11], v[8:9]
	v_mov_b64_e32 v[8:9], v[6:7]
	v_mov_b64_e32 v[6:7], v[4:5]
	v_mov_b64_e32 v[4:5], v[2:3]
	v_mov_b64_e32 v[2:3], v[0:1]
	s_mov_b32 s31, 0x4000
	s_mov_b32 s33, 0
	v_add_u32_e32 v245, 0x8000, v245
	v_add_u32_e32 v246, 0x8000, v246
	v_add_u32_e32 v247, 0x8000, v247
	v_add_u32_e32 v248, 0x8000, v248

.LBB0_277:
	s_mov_b32 s36, 0xffff8000
	s_cmp_ge_u32 s22, s19
	s_cbranch_scc1 .Lslow_u2e
.LBB0_288:
	s_add_i32 s100, s10, 0x0
	s_add_i32 s101, s10, 0x8000
	ds_read_b128 v[126:129], v245 offset:16384
	s_waitcnt lgkmcnt(1)
	v_mfma_f32_32x32x16_bf16 v[82:97], v[98:101], v[146:149], v[66:81]
	ds_read_b128 v[122:125], v240 offset:24576
	v_mfma_f32_32x32x16_bf16 v[98:113], v[114:117], v[146:149], v[66:81]
	ds_read_b128 v[114:117], v241 offset:16384
	v_mfma_f32_32x32x16_bf16 v[82:97], v[118:121], v[150:153], v[82:97]
	ds_read_b128 v[118:121], v241 offset:24576
	s_waitcnt lgkmcnt(0)
	v_mfma_f32_32x32x16_bf16 v[98:113], v[122:125], v[150:153], v[98:113]
	ds_read_b128 v[122:125], v242 offset:16384
	v_mfma_f32_32x32x16_bf16 v[82:97], v[114:117], v[154:157], v[82:97]
	ds_read_b128 v[114:117], v242 offset:24576
	v_mfma_f32_32x32x16_bf16 v[98:113], v[118:121], v[154:157], v[98:113]
	s_waitcnt lgkmcnt(0)
	v_mfma_f32_32x32x16_bf16 v[82:97], v[122:125], v[158:161], v[82:97]
	v_mfma_f32_32x32x16_bf16 v[98:113], v[114:117], v[158:161], v[98:113]
	s_nop 0
	ds_read_b128 v[122:125], v245 offset:20480
	ds_read_b128 v[118:121], v245 offset:24576
	ds_read_b128 v[114:117], v245 offset:28672
	s_cmp_le_u32 s20, s16
	s_cbranch_scc0 .Lnear_u2e
.LBB0_291:
	v_mfma_f32_32x32x16_bf16 v[50:65], v[126:129], v[162:165], v[50:65]
	ds_read_b128 v[126:129], v246 offset:16384
	s_nop 1
	v_exp_f32_e32 v130, v82
	v_exp_f32_e32 v131, v83
	v_add_f32_e32 v132, v1, v130
	v_add_f32_e32 v133, v1, v131
	v_cvt_pk_bf16_f32 v166, v130, v131
	s_waitcnt lgkmcnt(3)
	v_mfma_f32_32x32x16_bf16 v[34:49], v[122:125], v[162:165], v[34:49]
	ds_read_b128 v[122:125], v246 offset:20480
	v_exp_f32_e32 v134, v84
	v_exp_f32_e32 v135, v85
	s_add_i32 s21, s22, 2
	v_add_f32_e32 v130, v132, v134
	v_add_f32_e32 v131, v133, v135
	v_cvt_pk_bf16_f32 v167, v134, v135
	s_mov_b32 m0, s100
	s_cmp_ge_u32 s21, s18
	s_cbranch_scc1 .LBB0_293
	global_load_lds_dwordx4 v214, s[80:81]
	s_add_i32 m0, s100, 0x2000
	s_nop 0
	global_load_lds_dwordx4 v214, s[62:63]
.LBB0_293:
	s_waitcnt lgkmcnt(2)
	v_mfma_f32_32x32x16_bf16 v[18:33], v[118:121], v[162:165], v[18:33]
	ds_read_b128 v[118:121], v246 offset:24576
	v_exp_f32_e32 v132, v86
	v_exp_f32_e32 v133, v87
	v_add_f32_e32 v130, v130, v132
	v_add_f32_e32 v131, v131, v133
	v_cvt_pk_bf16_f32 v168, v132, v133
	v_mfma_f32_32x32x16_bf16 v[2:17], v[114:117], v[162:165], v[2:17]
	ds_read_b128 v[114:117], v246 offset:28672
	v_exp_f32_e32 v0, v88
	v_exp_f32_e32 v132, v89
	v_add_f32_e32 v130, v130, v0
	v_add_f32_e32 v131, v131, v132
	v_cvt_pk_bf16_f32 v169, v0, v132
	s_waitcnt lgkmcnt(2)
	v_mfma_f32_32x32x16_bf16 v[50:65], v[126:129], v[170:173], v[50:65]
	ds_read_b128 v[126:129], v247 offset:16384
	v_exp_f32_e32 v132, v90
	v_exp_f32_e32 v133, v91
	v_add_f32_e32 v130, v130, v132
	v_add_f32_e32 v131, v131, v133
	v_cvt_pk_bf16_f32 v174, v132, v133
	v_mfma_f32_32x32x16_bf16 v[34:49], v[122:125], v[170:173], v[34:49]
	ds_read_b128 v[122:125], v247 offset:20480
	v_exp_f32_e32 v132, v92
	v_exp_f32_e32 v133, v93
	v_add_f32_e32 v130, v130, v132
	v_add_f32_e32 v131, v131, v133
	v_cvt_pk_bf16_f32 v175, v132, v133
.LBB0_295:
	s_waitcnt lgkmcnt(2)
	v_mfma_f32_32x32x16_bf16 v[18:33], v[118:121], v[170:173], v[18:33]
	ds_read_b128 v[118:121], v247 offset:24576
	v_exp_f32_e32 v132, v94
	v_exp_f32_e32 v133, v95
	v_add_f32_e32 v130, v130, v132
	v_add_f32_e32 v131, v131, v133
	v_cvt_pk_bf16_f32 v176, v132, v133
	v_mfma_f32_32x32x16_bf16 v[2:17], v[114:117], v[170:173], v[2:17]
	ds_read_b128 v[114:117], v247 offset:28672
	v_exp_f32_e32 v0, v96
	v_exp_f32_e32 v132, v97
	v_add_f32_e32 v130, v130, v0
	v_add_f32_e32 v131, v131, v132
	v_cvt_pk_bf16_f32 v177, v0, v132
	s_waitcnt lgkmcnt(2)
	v_mfma_f32_32x32x16_bf16 v[50:65], v[126:129], v[178:181], v[50:65]
	ds_read_b128 v[126:129], v248 offset:16384
	v_exp_f32_e32 v132, v98
	v_exp_f32_e32 v133, v99
	v_add_f32_e32 v130, v130, v132
	v_add_f32_e32 v131, v131, v133
	v_cvt_pk_bf16_f32 v182, v132, v133
	v_mfma_f32_32x32x16_bf16 v[34:49], v[122:125], v[178:181], v[34:49]
	v_exp_f32_e32 v132, v100
	v_exp_f32_e32 v133, v101
	ds_read_b128 v[122:125], v248 offset:20480
	v_add_f32_e32 v130, v130, v132
	v_add_f32_e32 v131, v131, v133
	v_cvt_pk_bf16_f32 v183, v132, v133
	s_add_i32 m0, s101, 0xc000
	s_cmp_eq_u64 s[44:45], 0
	s_cbranch_scc1 .LBB0_297
	global_load_lds_dwordx4 v216, s[96:97]
	s_add_i32 m0, s101, 0xe000
	s_nop 0
	global_load_lds_dwordx4 v216, s[58:59]
.LBB0_297:
	s_waitcnt lgkmcnt(2)
	v_mfma_f32_32x32x16_bf16 v[18:33], v[118:121], v[178:181], v[18:33]
	ds_read_b128 v[118:121], v248 offset:24576
	v_exp_f32_e32 v132, v102
	v_exp_f32_e32 v133, v103
	v_add_f32_e32 v130, v130, v132
	v_add_f32_e32 v131, v131, v133
	v_cvt_pk_bf16_f32 v184, v132, v133
	v_mfma_f32_32x32x16_bf16 v[2:17], v[114:117], v[178:181], v[2:17]
	ds_read_b128 v[114:117], v248 offset:28672
	v_exp_f32_e32 v0, v104
	v_exp_f32_e32 v132, v105
	v_add_f32_e32 v130, v130, v0
	v_add_f32_e32 v131, v131, v132
	v_cvt_pk_bf16_f32 v185, v0, v132
	s_waitcnt lgkmcnt(2)
	v_mfma_f32_32x32x16_bf16 v[50:65], v[126:129], v[186:189], v[50:65]
	v_exp_f32_e32 v0, v106
	v_exp_f32_e32 v126, v107
	v_add_f32_e32 v127, v130, v0
	v_add_f32_e32 v128, v131, v126
	v_cvt_pk_bf16_f32 v190, v0, v126
	v_mfma_f32_32x32x16_bf16 v[34:49], v[122:125], v[186:189], v[34:49]
	v_exp_f32_e32 v123, v108
	v_exp_f32_e32 v124, v109
	v_add_f32_e32 v0, v127, v123
	v_add_f32_e32 v122, v128, v124
	v_cvt_pk_bf16_f32 v191, v123, v124

.LBB0_317:
	s_add_i32 s37, s22, 1
	s_mov_b32 s36, 0xffffc000
	s_cmp_ge_u32 s37, s19
	s_cbranch_scc1 .Lslow_u2o
.LBB0_328:
	s_add_i32 s100, s10, 0x4000
	s_add_i32 s101, s10, 0x0
	ds_read_b128 v[126:129], v245 offset:32768
	s_waitcnt lgkmcnt(1)
	v_mfma_f32_32x32x16_bf16 v[82:97], v[98:101], v[146:149], v[66:81]
	ds_read_b128 v[122:125], v240 offset:40960
	v_mfma_f32_32x32x16_bf16 v[98:113], v[114:117], v[146:149], v[66:81]
	ds_read_b128 v[114:117], v241 offset:32768
	v_mfma_f32_32x32x16_bf16 v[82:97], v[118:121], v[150:153], v[82:97]
	ds_read_b128 v[118:121], v241 offset:40960
	s_waitcnt lgkmcnt(0)
	v_mfma_f32_32x32x16_bf16 v[98:113], v[122:125], v[150:153], v[98:113]
	ds_read_b128 v[122:125], v242 offset:32768
	v_mfma_f32_32x32x16_bf16 v[82:97], v[114:117], v[154:157], v[82:97]
	ds_read_b128 v[114:117], v242 offset:40960
	v_mfma_f32_32x32x16_bf16 v[98:113], v[118:121], v[154:157], v[98:113]
	s_waitcnt lgkmcnt(0)
	v_mfma_f32_32x32x16_bf16 v[82:97], v[122:125], v[158:161], v[82:97]
	v_mfma_f32_32x32x16_bf16 v[98:113], v[114:117], v[158:161], v[98:113]
	s_nop 0
	ds_read_b128 v[122:125], v245 offset:36864
	ds_read_b128 v[118:121], v245 offset:40960
	ds_read_b128 v[114:117], v245 offset:45056
	s_add_i32 s26, s20, 64
	s_cmp_le_u32 s26, s16
	s_cbranch_scc0 .Lnear_u2o
.LBB0_331:
	v_mfma_f32_32x32x16_bf16 v[50:65], v[126:129], v[166:169], v[50:65]
	ds_read_b128 v[126:129], v246 offset:32768
	s_nop 0
	v_exp_f32_e32 v130, v82
	v_exp_f32_e32 v131, v83
	v_add_f32_e32 v132, v1, v130
	v_add_f32_e32 v133, v1, v131
	v_cvt_pk_bf16_f32 v162, v130, v131
	s_waitcnt lgkmcnt(3)
	v_mfma_f32_32x32x16_bf16 v[34:49], v[122:125], v[166:169], v[34:49]
	ds_read_b128 v[122:125], v246 offset:36864
	v_exp_f32_e32 v130, v84
	v_exp_f32_e32 v131, v85
	s_add_i32 s22, s22, 3
	v_add_f32_e32 v132, v132, v130
	v_add_f32_e32 v133, v133, v131
	v_cvt_pk_bf16_f32 v163, v130, v131
	s_mov_b32 m0, s100
	s_cmp_gt_u32 s22, s17
	s_cbranch_scc1 .LBB0_333
	global_load_lds_dwordx4 v214, s[50:51]
	s_add_i32 m0, s100, 0x2000
	s_nop 0
	global_load_lds_dwordx4 v214, s[4:5]
.LBB0_333:
	s_waitcnt lgkmcnt(2)
	v_mfma_f32_32x32x16_bf16 v[18:33], v[118:121], v[166:169], v[18:33]
	ds_read_b128 v[118:121], v246 offset:40960
	v_exp_f32_e32 v134, v86
	v_exp_f32_e32 v135, v87
	v_add_f32_e32 v132, v132, v134
	v_add_f32_e32 v133, v133, v135
	v_cvt_pk_bf16_f32 v164, v134, v135
	v_mfma_f32_32x32x16_bf16 v[2:17], v[114:117], v[166:169], v[2:17]
	ds_read_b128 v[114:117], v246 offset:45056
	v_exp_f32_e32 v0, v88
	v_exp_f32_e32 v134, v89
	v_add_f32_e32 v132, v132, v0
	v_add_f32_e32 v133, v133, v134
	v_cvt_pk_bf16_f32 v165, v0, v134
	s_waitcnt lgkmcnt(2)
	v_mfma_f32_32x32x16_bf16 v[50:65], v[126:129], v[174:177], v[50:65]
	ds_read_b128 v[126:129], v247 offset:32768
	v_exp_f32_e32 v134, v90
	v_exp_f32_e32 v135, v91
	v_add_f32_e32 v132, v132, v134
	v_add_f32_e32 v133, v133, v135
	v_cvt_pk_bf16_f32 v170, v134, v135
	v_mfma_f32_32x32x16_bf16 v[34:49], v[122:125], v[174:177], v[34:49]
	ds_read_b128 v[122:125], v247 offset:36864
	v_exp_f32_e32 v134, v92
	v_exp_f32_e32 v135, v93
	v_add_f32_e32 v132, v132, v134
	v_add_f32_e32 v133, v133, v135
	v_cvt_pk_bf16_f32 v171, v134, v135
.LBB0_335:
	s_waitcnt lgkmcnt(2)
	v_mfma_f32_32x32x16_bf16 v[18:33], v[118:121], v[174:177], v[18:33]
	ds_read_b128 v[118:121], v247 offset:40960
	v_exp_f32_e32 v130, v94
	v_exp_f32_e32 v131, v95
	v_add_f32_e32 v132, v132, v130
	v_add_f32_e32 v133, v133, v131
	v_cvt_pk_bf16_f32 v172, v130, v131
	v_mfma_f32_32x32x16_bf16 v[2:17], v[114:117], v[174:177], v[2:17]
	ds_read_b128 v[114:117], v247 offset:45056
	v_exp_f32_e32 v0, v96
	v_exp_f32_e32 v130, v97
	v_add_f32_e32 v131, v132, v0
	v_add_f32_e32 v132, v133, v130
	v_cvt_pk_bf16_f32 v173, v0, v130
	s_waitcnt lgkmcnt(2)
	v_mfma_f32_32x32x16_bf16 v[50:65], v[126:129], v[182:185], v[50:65]
	ds_read_b128 v[126:129], v248 offset:32768
	v_exp_f32_e32 v130, v98
	v_exp_f32_e32 v133, v99
	v_add_f32_e32 v131, v131, v130
	v_add_f32_e32 v134, v132, v133
	v_cvt_pk_bf16_f32 v178, v130, v133
	v_mfma_f32_32x32x16_bf16 v[34:49], v[122:125], v[182:185], v[34:49]
	v_exp_f32_e32 v130, v100
	v_exp_f32_e32 v135, v101
	ds_read_b128 v[122:125], v248 offset:36864
	v_add_f32_e32 v132, v131, v130
	v_add_f32_e32 v133, v134, v135
	v_cvt_pk_bf16_f32 v179, v130, v135
	s_add_i32 m0, s101, 0xc000
	s_cmp_eq_u64 s[44:45], 0
	s_cbranch_scc1 .LBB0_337
	global_load_lds_dwordx4 v216, s[0:1]
	s_add_i32 m0, s101, 0xe000
	s_nop 0
	global_load_lds_dwordx4 v216, s[52:53]
.LBB0_337:
	s_waitcnt lgkmcnt(2)
	v_mfma_f32_32x32x16_bf16 v[18:33], v[118:121], v[182:185], v[18:33]
	ds_read_b128 v[118:121], v248 offset:40960
	v_exp_f32_e32 v134, v102
	v_exp_f32_e32 v135, v103
	v_add_f32_e32 v132, v132, v134
	v_add_f32_e32 v133, v133, v135
	v_cvt_pk_bf16_f32 v180, v134, v135
	v_mfma_f32_32x32x16_bf16 v[2:17], v[114:117], v[182:185], v[2:17]
	ds_read_b128 v[114:117], v248 offset:45056
	v_exp_f32_e32 v0, v104
	v_exp_f32_e32 v134, v105
	v_add_f32_e32 v132, v132, v0
	v_add_f32_e32 v133, v133, v134
	v_cvt_pk_bf16_f32 v181, v0, v134
	s_waitcnt lgkmcnt(2)
	v_mfma_f32_32x32x16_bf16 v[50:65], v[126:129], v[190:193], v[50:65]
	v_exp_f32_e32 v0, v106
	v_exp_f32_e32 v126, v107
	v_add_f32_e32 v127, v132, v0
	v_add_f32_e32 v128, v133, v126
	v_cvt_pk_bf16_f32 v186, v0, v126
	v_mfma_f32_32x32x16_bf16 v[34:49], v[122:125], v[190:193], v[34:49]
	v_exp_f32_e32 v123, v108
	v_exp_f32_e32 v124, v109
	v_add_f32_e32 v0, v127, v123
	v_add_f32_e32 v122, v128, v124
	v_cvt_pk_bf16_f32 v187, v123, v124

.LBB0_343:
	s_addk_i32 s20, 0x80
	s_add_i32 s22, s21, -3
	v_lshl_add_u64 v[214:215], v[214:215], 0, s[34:35]
	s_cmp_ge_u32 s22, s17
	v_lshl_add_u64 v[216:217], v[216:217], 0, s[24:25]
	s_cbranch_scc1 .LBB0_345
	s_mov_b32 s22, s21
	s_branch .Lr1u2_LBB0_267

.Lhd_u2e:
	s_add_i32 s21, s22, 2
	s_cmp_ge_u32 s21, s18
	s_cbranch_scc1 .LBB0_274
	s_mov_b32 s26, 0x0
	s_add_i32 s26, s10, s26
	s_add_i32 s27, s26, 0x2000
	s_mov_b32 m0, s26
	s_nop 0
	global_load_lds_dwordx4 v214, s[80:81]
	s_mov_b32 m0, s27
	s_nop 0
	global_load_lds_dwordx4 v214, s[62:63]
.LBB0_274:
	s_andn2_b64 vcc, exec, s[44:45]
	s_cbranch_vccnz .LBB0_276
	s_mov_b32 s26, 0x8000
	s_add_i32 s26, s10, s26
	s_add_i32 m0, s26, 0xc000
	s_add_i32 s26, s26, 0xe000
	global_load_lds_dwordx4 v216, s[96:97]
	s_mov_b32 m0, s26
	s_nop 0
	global_load_lds_dwordx4 v216, s[58:59]

.Lpvo_u2e:
	v_add_u32_e32 v212, s36, v245
	v_add_u32_e32 v0, s36, v246
	s_mov_b64 s[26:27], -1
	ds_read_b128 v[98:101], v212 offset:49152
	ds_read_b128 v[114:117], v212 offset:53248
	ds_read_b128 v[130:133], v212 offset:57344
	ds_read_b128 v[194:197], v212 offset:61440
	s_waitcnt lgkmcnt(0)
	v_mfma_f32_32x32x16_bf16 v[82:97], v[98:101], v[162:165], v[50:65]
	ds_read_b128 v[206:209], v0 offset:49152
	v_mfma_f32_32x32x16_bf16 v[98:113], v[114:117], v[162:165], v[34:49]
	ds_read_b128 v[198:201], v0 offset:53248
	s_add_i32 s21, s22, 2
	s_cmp_lt_u32 s21, s18
	s_cselect_b64 s[26:27], -1, 0
	s_cmp_ge_u32 s21, s18
	s_cbranch_scc1 .LBB0_281
	s_mov_b32 s37, 0x0
	s_add_i32 m0, s10, s37
	s_nop 0
	global_load_lds_dwordx4 v214, s[80:81]
.LBB0_281:
	v_mfma_f32_32x32x16_bf16 v[114:129], v[130:133], v[162:165], v[18:33]
	ds_read_b128 v[202:205], v0 offset:57344
	v_mfma_f32_32x32x16_bf16 v[130:145], v[194:197], v[162:165], v[2:17]
	ds_read_b128 v[194:197], v0 offset:61440
	s_waitcnt lgkmcnt(0)
	v_mfma_f32_32x32x16_bf16 v[82:97], v[206:209], v[170:173], v[82:97]
	v_add_u32_e32 v250, s36, v247
	ds_read_b128 v[206:209], v250 offset:49152
	v_mfma_f32_32x32x16_bf16 v[98:113], v[198:201], v[170:173], v[98:113]
	ds_read_b128 v[198:201], v250 offset:53248
	s_andn2_b64 vcc, exec, s[26:27]
	s_cbranch_vccnz .LBB0_283
	s_mov_b32 s26, 0x0
	s_add_i32 s26, s10, s26
	s_add_i32 m0, s26, 0x2000
	s_nop 0
	global_load_lds_dwordx4 v214, s[62:63]
.LBB0_283:
	v_mfma_f32_32x32x16_bf16 v[114:129], v[202:205], v[170:173], v[114:129]
	ds_read_b128 v[202:205], v250 offset:57344
	v_mfma_f32_32x32x16_bf16 v[130:145], v[194:197], v[170:173], v[130:145]
	ds_read_b128 v[194:197], v250 offset:61440
	s_waitcnt lgkmcnt(0)
	v_mfma_f32_32x32x16_bf16 v[82:97], v[206:209], v[178:181], v[82:97]
	v_add_u32_e32 v250, s36, v248
	ds_read_b128 v[206:209], v250 offset:49152
	v_mfma_f32_32x32x16_bf16 v[98:113], v[198:201], v[178:181], v[98:113]
	ds_read_b128 v[198:201], v250 offset:53248
	v_cndmask_b32_e64 v224, 0, 1, s[44:45]
	v_cmp_ne_u32_e64 s[40:41], 1, v224
	s_andn2_b64 vcc, exec, s[44:45]
	s_cbranch_vccnz .LBB0_285
	s_mov_b32 s26, 0x8000
	s_add_i32 s26, s10, s26
	s_add_i32 m0, s26, 0xc000
	s_nop 0
	global_load_lds_dwordx4 v216, s[96:97]
.LBB0_285:
	v_mfma_f32_32x32x16_bf16 v[114:129], v[202:205], v[178:181], v[114:129]
	ds_read_b128 v[202:205], v250 offset:57344
	v_mfma_f32_32x32x16_bf16 v[130:145], v[194:197], v[178:181], v[130:145]
	ds_read_b128 v[194:197], v250 offset:61440
	s_waitcnt lgkmcnt(0)
	v_mfma_f32_32x32x16_bf16 v[82:97], v[206:209], v[186:189], v[82:97]
	v_mfma_f32_32x32x16_bf16 v[98:113], v[198:201], v[186:189], v[98:113]
	s_and_b64 vcc, exec, s[40:41]
	s_cbranch_vccnz .LBB0_287
	s_mov_b32 s26, 0x8000
	s_add_i32 s26, s10, s26
	s_add_i32 m0, s26, 0xe000
	s_nop 0
	global_load_lds_dwordx4 v216, s[58:59]

.Lhd_u2o:
	s_add_i32 s26, s22, 3
	s_cmp_gt_u32 s26, s17
	s_cbranch_scc1 .LBB0_314
	s_mov_b32 s26, 0x4000
	s_add_i32 s26, s10, s26
	s_add_i32 s27, s26, 0x2000
	s_mov_b32 m0, s26
	s_nop 0
	global_load_lds_dwordx4 v214, s[50:51]
	s_mov_b32 m0, s27
	s_nop 0
	global_load_lds_dwordx4 v214, s[4:5]
.LBB0_314:
	s_andn2_b64 vcc, exec, s[44:45]
	s_cbranch_vccnz .LBB0_316
	s_mov_b32 s26, 0x0
	s_add_i32 s26, s10, s26
	s_add_i32 m0, s26, 0xc000
	s_add_i32 s26, s26, 0xe000
	global_load_lds_dwordx4 v216, s[0:1]
	s_mov_b32 m0, s26
	s_nop 0
	global_load_lds_dwordx4 v216, s[52:53]

.Lpvo_u2o:
	v_add_u32_e32 v212, s36, v245
	v_add_u32_e32 v0, s36, v246
	s_mov_b64 s[26:27], -1
	ds_read_b128 v[98:101], v212 offset:49152
	ds_read_b128 v[114:117], v212 offset:53248
	ds_read_b128 v[130:133], v212 offset:57344
	ds_read_b128 v[194:197], v212 offset:61440
	s_waitcnt lgkmcnt(0)
	v_mfma_f32_32x32x16_bf16 v[82:97], v[98:101], v[166:169], v[50:65]
	ds_read_b128 v[206:209], v0 offset:49152
	v_mfma_f32_32x32x16_bf16 v[98:113], v[114:117], v[166:169], v[34:49]
	ds_read_b128 v[198:201], v0 offset:53248
	s_add_i32 s37, s22, 3
	s_cmp_le_u32 s37, s17
	s_cselect_b64 s[26:27], -1, 0
	s_cmp_gt_u32 s37, s17
	s_cbranch_scc1 .LBB0_321
	s_mov_b32 s37, 0x4000
	s_add_i32 m0, s10, s37
	s_nop 0
	global_load_lds_dwordx4 v214, s[50:51]
.LBB0_321:
	v_mfma_f32_32x32x16_bf16 v[114:129], v[130:133], v[166:169], v[18:33]
	ds_read_b128 v[202:205], v0 offset:57344
	v_mfma_f32_32x32x16_bf16 v[130:145], v[194:197], v[166:169], v[2:17]
	ds_read_b128 v[194:197], v0 offset:61440
	s_waitcnt lgkmcnt(0)
	v_mfma_f32_32x32x16_bf16 v[82:97], v[206:209], v[174:177], v[82:97]
	v_add_u32_e32 v250, s36, v247
	ds_read_b128 v[206:209], v250 offset:49152
	v_mfma_f32_32x32x16_bf16 v[98:113], v[198:201], v[174:177], v[98:113]
	ds_read_b128 v[198:201], v250 offset:53248
	s_andn2_b64 vcc, exec, s[26:27]
	s_cbranch_vccnz .LBB0_323
	s_mov_b32 s26, 0x4000
	s_add_i32 s26, s10, s26
	s_add_i32 m0, s26, 0x2000
	s_nop 0
	global_load_lds_dwordx4 v214, s[4:5]
.LBB0_323:
	v_mfma_f32_32x32x16_bf16 v[114:129], v[202:205], v[174:177], v[114:129]
	ds_read_b128 v[202:205], v250 offset:57344
	v_mfma_f32_32x32x16_bf16 v[130:145], v[194:197], v[174:177], v[130:145]
	ds_read_b128 v[194:197], v250 offset:61440
	s_waitcnt lgkmcnt(0)
	v_mfma_f32_32x32x16_bf16 v[82:97], v[206:209], v[182:185], v[82:97]
	v_add_u32_e32 v250, s36, v248
	ds_read_b128 v[206:209], v250 offset:49152
	v_mfma_f32_32x32x16_bf16 v[98:113], v[198:201], v[182:185], v[98:113]
	ds_read_b128 v[198:201], v250 offset:53248
	v_cndmask_b32_e64 v224, 0, 1, s[44:45]
	v_cmp_ne_u32_e64 s[40:41], 1, v224
	s_andn2_b64 vcc, exec, s[44:45]
	s_cbranch_vccnz .LBB0_325
	s_mov_b32 s26, 0x0
	s_add_i32 s26, s10, s26
	s_add_i32 m0, s26, 0xc000
	s_nop 0
	global_load_lds_dwordx4 v216, s[0:1]
.LBB0_325:
	v_mfma_f32_32x32x16_bf16 v[114:129], v[202:205], v[182:185], v[114:129]
	ds_read_b128 v[202:205], v250 offset:57344
	v_mfma_f32_32x32x16_bf16 v[130:145], v[194:197], v[182:185], v[130:145]
	ds_read_b128 v[194:197], v250 offset:61440
	s_waitcnt lgkmcnt(0)
	v_mfma_f32_32x32x16_bf16 v[82:97], v[206:209], v[190:193], v[82:97]
	v_mfma_f32_32x32x16_bf16 v[98:113], v[198:201], v[190:193], v[98:113]
	s_and_b64 vcc, exec, s[40:41]
	s_cbranch_vccnz .LBB0_327
	s_mov_b32 s26, 0x0
	s_add_i32 s26, s10, s26
	s_add_i32 m0, s26, 0xe000
	s_nop 0
	global_load_lds_dwordx4 v216, s[52:53]

.Lotail_u2o:
	s_add_i32 s26, s22, -1
	s_cmp_lt_u32 s26, s17
	s_cbranch_scc1 .Low2_u2o
	s_waitcnt vmcnt(0)
	s_branch .LBB0_311
.Lr1u2_LBB0_267:
	s_add_i32 s21, s22, -1
	s_cmp_lt_u32 s21, s17
	s_cselect_b64 s[44:45], -1, 0
	s_waitcnt vmcnt(2)

.Lr1u2_LBB0_277:
	s_mov_b32 s36, 0x0
	s_cmp_ge_u32 s22, s19
	s_cbranch_scc1 .Lr1u2_Lslow_u2e
.Lr1u2_LBB0_288:
	s_add_i32 s100, s10, 0x8000
	s_add_i32 s101, s10, 0x4000
	ds_read_b128 v[126:129], v245 offset:49152
	s_waitcnt lgkmcnt(1)
	v_mfma_f32_32x32x16_bf16 v[82:97], v[98:101], v[146:149], v[66:81]
	ds_read_b128 v[122:125], v240 offset:8192
	v_mfma_f32_32x32x16_bf16 v[98:113], v[114:117], v[146:149], v[66:81]
	ds_read_b128 v[114:117], v241
	v_mfma_f32_32x32x16_bf16 v[82:97], v[118:121], v[150:153], v[82:97]
	ds_read_b128 v[118:121], v241 offset:8192
	s_waitcnt lgkmcnt(0)
	v_mfma_f32_32x32x16_bf16 v[98:113], v[122:125], v[150:153], v[98:113]
	ds_read_b128 v[122:125], v242
	v_mfma_f32_32x32x16_bf16 v[82:97], v[114:117], v[154:157], v[82:97]
	ds_read_b128 v[114:117], v242 offset:8192
	v_mfma_f32_32x32x16_bf16 v[98:113], v[118:121], v[154:157], v[98:113]
	s_waitcnt lgkmcnt(0)
	v_mfma_f32_32x32x16_bf16 v[82:97], v[122:125], v[158:161], v[82:97]
	v_mfma_f32_32x32x16_bf16 v[98:113], v[114:117], v[158:161], v[98:113]
	s_nop 0
	ds_read_b128 v[122:125], v245 offset:53248
	ds_read_b128 v[118:121], v245 offset:57344
	ds_read_b128 v[114:117], v245 offset:61440
	s_cmp_le_u32 s20, s16
	s_cbranch_scc0 .Lr1u2_Lnear_u2e
.Lr1u2_LBB0_291:
	v_mfma_f32_32x32x16_bf16 v[50:65], v[126:129], v[162:165], v[50:65]
	ds_read_b128 v[126:129], v246 offset:49152
	s_nop 1
	v_exp_f32_e32 v130, v82
	v_exp_f32_e32 v131, v83
	v_add_f32_e32 v132, v1, v130
	v_add_f32_e32 v133, v1, v131
	v_cvt_pk_bf16_f32 v166, v130, v131
	s_waitcnt lgkmcnt(3)
	v_mfma_f32_32x32x16_bf16 v[34:49], v[122:125], v[162:165], v[34:49]
	ds_read_b128 v[122:125], v246 offset:53248
	v_exp_f32_e32 v134, v84
	v_exp_f32_e32 v135, v85
	s_add_i32 s21, s22, 2
	v_add_f32_e32 v130, v132, v134
	v_add_f32_e32 v131, v133, v135
	v_cvt_pk_bf16_f32 v167, v134, v135
	s_mov_b32 m0, s100
	s_cmp_ge_u32 s21, s18
	s_cbranch_scc1 .Lr1u2_LBB0_293
	global_load_lds_dwordx4 v214, s[80:81]
	s_add_i32 m0, s100, 0x2000
	s_nop 0
	global_load_lds_dwordx4 v214, s[62:63]
.Lr1u2_LBB0_293:
	s_waitcnt lgkmcnt(2)
	v_mfma_f32_32x32x16_bf16 v[18:33], v[118:121], v[162:165], v[18:33]
	ds_read_b128 v[118:121], v246 offset:57344
	v_exp_f32_e32 v132, v86
	v_exp_f32_e32 v133, v87
	v_add_f32_e32 v130, v130, v132
	v_add_f32_e32 v131, v131, v133
	v_cvt_pk_bf16_f32 v168, v132, v133
	v_mfma_f32_32x32x16_bf16 v[2:17], v[114:117], v[162:165], v[2:17]
	ds_read_b128 v[114:117], v246 offset:61440
	v_exp_f32_e32 v0, v88
	v_exp_f32_e32 v132, v89
	v_add_f32_e32 v130, v130, v0
	v_add_f32_e32 v131, v131, v132
	v_cvt_pk_bf16_f32 v169, v0, v132
	s_waitcnt lgkmcnt(2)
	v_mfma_f32_32x32x16_bf16 v[50:65], v[126:129], v[170:173], v[50:65]
	ds_read_b128 v[126:129], v247 offset:49152
	v_exp_f32_e32 v132, v90
	v_exp_f32_e32 v133, v91
	v_add_f32_e32 v130, v130, v132
	v_add_f32_e32 v131, v131, v133
	v_cvt_pk_bf16_f32 v174, v132, v133
	v_mfma_f32_32x32x16_bf16 v[34:49], v[122:125], v[170:173], v[34:49]
	ds_read_b128 v[122:125], v247 offset:53248
	v_exp_f32_e32 v132, v92
	v_exp_f32_e32 v133, v93
	v_add_f32_e32 v130, v130, v132
	v_add_f32_e32 v131, v131, v133
	v_cvt_pk_bf16_f32 v175, v132, v133
.Lr1u2_LBB0_295:
	s_waitcnt lgkmcnt(2)
	v_mfma_f32_32x32x16_bf16 v[18:33], v[118:121], v[170:173], v[18:33]
	ds_read_b128 v[118:121], v247 offset:57344
	v_exp_f32_e32 v132, v94
	v_exp_f32_e32 v133, v95
	v_add_f32_e32 v130, v130, v132
	v_add_f32_e32 v131, v131, v133
	v_cvt_pk_bf16_f32 v176, v132, v133
	v_mfma_f32_32x32x16_bf16 v[2:17], v[114:117], v[170:173], v[2:17]
	ds_read_b128 v[114:117], v247 offset:61440
	v_exp_f32_e32 v0, v96
	v_exp_f32_e32 v132, v97
	v_add_f32_e32 v130, v130, v0
	v_add_f32_e32 v131, v131, v132
	v_cvt_pk_bf16_f32 v177, v0, v132
	s_waitcnt lgkmcnt(2)
	v_mfma_f32_32x32x16_bf16 v[50:65], v[126:129], v[178:181], v[50:65]
	ds_read_b128 v[126:129], v248 offset:49152
	v_exp_f32_e32 v132, v98
	v_exp_f32_e32 v133, v99
	v_add_f32_e32 v130, v130, v132
	v_add_f32_e32 v131, v131, v133
	v_cvt_pk_bf16_f32 v182, v132, v133
	v_mfma_f32_32x32x16_bf16 v[34:49], v[122:125], v[178:181], v[34:49]
	v_exp_f32_e32 v132, v100
	v_exp_f32_e32 v133, v101
	ds_read_b128 v[122:125], v248 offset:53248
	v_add_f32_e32 v130, v130, v132
	v_add_f32_e32 v131, v131, v133
	v_cvt_pk_bf16_f32 v183, v132, v133
	s_add_i32 m0, s101, 0xc000
	s_cmp_eq_u64 s[44:45], 0
	s_cbranch_scc1 .Lr1u2_LBB0_297
	global_load_lds_dwordx4 v216, s[96:97]
	s_add_i32 m0, s101, 0xe000
	s_nop 0
	global_load_lds_dwordx4 v216, s[58:59]
.Lr1u2_LBB0_297:
	s_waitcnt lgkmcnt(2)
	v_mfma_f32_32x32x16_bf16 v[18:33], v[118:121], v[178:181], v[18:33]
	ds_read_b128 v[118:121], v248 offset:57344
	v_exp_f32_e32 v132, v102
	v_exp_f32_e32 v133, v103
	v_add_f32_e32 v130, v130, v132
	v_add_f32_e32 v131, v131, v133
	v_cvt_pk_bf16_f32 v184, v132, v133
	v_mfma_f32_32x32x16_bf16 v[2:17], v[114:117], v[178:181], v[2:17]
	ds_read_b128 v[114:117], v248 offset:61440
	v_exp_f32_e32 v0, v104
	v_exp_f32_e32 v132, v105
	v_add_f32_e32 v130, v130, v0
	v_add_f32_e32 v131, v131, v132
	v_cvt_pk_bf16_f32 v185, v0, v132
	s_waitcnt lgkmcnt(2)
	v_mfma_f32_32x32x16_bf16 v[50:65], v[126:129], v[186:189], v[50:65]
	v_exp_f32_e32 v0, v106
	v_exp_f32_e32 v126, v107
	v_add_f32_e32 v127, v130, v0
	v_add_f32_e32 v128, v131, v126
	v_cvt_pk_bf16_f32 v190, v0, v126
	v_mfma_f32_32x32x16_bf16 v[34:49], v[122:125], v[186:189], v[34:49]
	v_exp_f32_e32 v123, v108
	v_exp_f32_e32 v124, v109
	v_add_f32_e32 v0, v127, v123
	v_add_f32_e32 v122, v128, v124
	v_cvt_pk_bf16_f32 v191, v123, v124

.Lr1u2_LBB0_317:
	s_add_i32 s37, s22, 1
	s_mov_b32 s36, 0xffff8000
	s_cmp_ge_u32 s37, s19
	s_cbranch_scc1 .Lr1u2_Lslow_u2o
.Lr1u2_LBB0_328:
	s_add_i32 s100, s10, 0x0
	s_add_i32 s101, s10, 0x8000
	ds_read_b128 v[126:129], v245 offset:16384
	s_waitcnt lgkmcnt(1)
	v_mfma_f32_32x32x16_bf16 v[82:97], v[98:101], v[146:149], v[66:81]
	ds_read_b128 v[122:125], v240 offset:24576
	v_mfma_f32_32x32x16_bf16 v[98:113], v[114:117], v[146:149], v[66:81]
	ds_read_b128 v[114:117], v241 offset:16384
	v_mfma_f32_32x32x16_bf16 v[82:97], v[118:121], v[150:153], v[82:97]
	ds_read_b128 v[118:121], v241 offset:24576
	s_waitcnt lgkmcnt(0)
	v_mfma_f32_32x32x16_bf16 v[98:113], v[122:125], v[150:153], v[98:113]
	ds_read_b128 v[122:125], v242 offset:16384
	v_mfma_f32_32x32x16_bf16 v[82:97], v[114:117], v[154:157], v[82:97]
	ds_read_b128 v[114:117], v242 offset:24576
	v_mfma_f32_32x32x16_bf16 v[98:113], v[118:121], v[154:157], v[98:113]
	s_waitcnt lgkmcnt(0)
	v_mfma_f32_32x32x16_bf16 v[82:97], v[122:125], v[158:161], v[82:97]
	v_mfma_f32_32x32x16_bf16 v[98:113], v[114:117], v[158:161], v[98:113]
	s_nop 0
	ds_read_b128 v[122:125], v245 offset:20480
	ds_read_b128 v[118:121], v245 offset:24576
	ds_read_b128 v[114:117], v245 offset:28672
	s_add_i32 s26, s20, 64
	s_cmp_le_u32 s26, s16
	s_cbranch_scc0 .Lr1u2_Lnear_u2o
.Lr1u2_LBB0_331:
	v_mfma_f32_32x32x16_bf16 v[50:65], v[126:129], v[166:169], v[50:65]
	ds_read_b128 v[126:129], v246 offset:16384
	s_nop 0
	v_exp_f32_e32 v130, v82
	v_exp_f32_e32 v131, v83
	v_add_f32_e32 v132, v1, v130
	v_add_f32_e32 v133, v1, v131
	v_cvt_pk_bf16_f32 v162, v130, v131
	s_waitcnt lgkmcnt(3)
	v_mfma_f32_32x32x16_bf16 v[34:49], v[122:125], v[166:169], v[34:49]
	ds_read_b128 v[122:125], v246 offset:20480
	v_exp_f32_e32 v130, v84
	v_exp_f32_e32 v131, v85
	s_add_i32 s22, s22, 3
	v_add_f32_e32 v132, v132, v130
	v_add_f32_e32 v133, v133, v131
	v_cvt_pk_bf16_f32 v163, v130, v131
	s_mov_b32 m0, s100
	s_cmp_gt_u32 s22, s17
	s_cbranch_scc1 .Lr1u2_LBB0_333
	global_load_lds_dwordx4 v214, s[50:51]
	s_add_i32 m0, s100, 0x2000
	s_nop 0
	global_load_lds_dwordx4 v214, s[4:5]
.Lr1u2_LBB0_333:
	s_waitcnt lgkmcnt(2)
	v_mfma_f32_32x32x16_bf16 v[18:33], v[118:121], v[166:169], v[18:33]
	ds_read_b128 v[118:121], v246 offset:24576
	v_exp_f32_e32 v134, v86
	v_exp_f32_e32 v135, v87
	v_add_f32_e32 v132, v132, v134
	v_add_f32_e32 v133, v133, v135
	v_cvt_pk_bf16_f32 v164, v134, v135
	v_mfma_f32_32x32x16_bf16 v[2:17], v[114:117], v[166:169], v[2:17]
	ds_read_b128 v[114:117], v246 offset:28672
	v_exp_f32_e32 v0, v88
	v_exp_f32_e32 v134, v89
	v_add_f32_e32 v132, v132, v0
	v_add_f32_e32 v133, v133, v134
	v_cvt_pk_bf16_f32 v165, v0, v134
	s_waitcnt lgkmcnt(2)
	v_mfma_f32_32x32x16_bf16 v[50:65], v[126:129], v[174:177], v[50:65]
	ds_read_b128 v[126:129], v247 offset:16384
	v_exp_f32_e32 v134, v90
	v_exp_f32_e32 v135, v91
	v_add_f32_e32 v132, v132, v134
	v_add_f32_e32 v133, v133, v135
	v_cvt_pk_bf16_f32 v170, v134, v135
	v_mfma_f32_32x32x16_bf16 v[34:49], v[122:125], v[174:177], v[34:49]
	ds_read_b128 v[122:125], v247 offset:20480
	v_exp_f32_e32 v134, v92
	v_exp_f32_e32 v135, v93
	v_add_f32_e32 v132, v132, v134
	v_add_f32_e32 v133, v133, v135
	v_cvt_pk_bf16_f32 v171, v134, v135
.Lr1u2_LBB0_335:
	s_waitcnt lgkmcnt(2)
	v_mfma_f32_32x32x16_bf16 v[18:33], v[118:121], v[174:177], v[18:33]
	ds_read_b128 v[118:121], v247 offset:24576
	v_exp_f32_e32 v130, v94
	v_exp_f32_e32 v131, v95
	v_add_f32_e32 v132, v132, v130
	v_add_f32_e32 v133, v133, v131
	v_cvt_pk_bf16_f32 v172, v130, v131
	v_mfma_f32_32x32x16_bf16 v[2:17], v[114:117], v[174:177], v[2:17]
	ds_read_b128 v[114:117], v247 offset:28672
	v_exp_f32_e32 v0, v96
	v_exp_f32_e32 v130, v97
	v_add_f32_e32 v131, v132, v0
	v_add_f32_e32 v132, v133, v130
	v_cvt_pk_bf16_f32 v173, v0, v130
	s_waitcnt lgkmcnt(2)
	v_mfma_f32_32x32x16_bf16 v[50:65], v[126:129], v[182:185], v[50:65]
	ds_read_b128 v[126:129], v248 offset:16384
	v_exp_f32_e32 v130, v98
	v_exp_f32_e32 v133, v99
	v_add_f32_e32 v131, v131, v130
	v_add_f32_e32 v134, v132, v133
	v_cvt_pk_bf16_f32 v178, v130, v133
	v_mfma_f32_32x32x16_bf16 v[34:49], v[122:125], v[182:185], v[34:49]
	v_exp_f32_e32 v130, v100
	v_exp_f32_e32 v135, v101
	ds_read_b128 v[122:125], v248 offset:20480
	v_add_f32_e32 v132, v131, v130
	v_add_f32_e32 v133, v134, v135
	v_cvt_pk_bf16_f32 v179, v130, v135
	s_add_i32 m0, s101, 0xc000
	s_cmp_eq_u64 s[44:45], 0
	s_cbranch_scc1 .Lr1u2_LBB0_337
	global_load_lds_dwordx4 v216, s[0:1]
	s_add_i32 m0, s101, 0xe000
	s_nop 0
	global_load_lds_dwordx4 v216, s[52:53]
.Lr1u2_LBB0_337:
	s_waitcnt lgkmcnt(2)
	v_mfma_f32_32x32x16_bf16 v[18:33], v[118:121], v[182:185], v[18:33]
	ds_read_b128 v[118:121], v248 offset:24576
	v_exp_f32_e32 v134, v102
	v_exp_f32_e32 v135, v103
	v_add_f32_e32 v132, v132, v134
	v_add_f32_e32 v133, v133, v135
	v_cvt_pk_bf16_f32 v180, v134, v135
	v_mfma_f32_32x32x16_bf16 v[2:17], v[114:117], v[182:185], v[2:17]
	ds_read_b128 v[114:117], v248 offset:28672
	v_exp_f32_e32 v0, v104
	v_exp_f32_e32 v134, v105
	v_add_f32_e32 v132, v132, v0
	v_add_f32_e32 v133, v133, v134
	v_cvt_pk_bf16_f32 v181, v0, v134
	s_waitcnt lgkmcnt(2)
	v_mfma_f32_32x32x16_bf16 v[50:65], v[126:129], v[190:193], v[50:65]
	v_exp_f32_e32 v0, v106
	v_exp_f32_e32 v126, v107
	v_add_f32_e32 v127, v132, v0
	v_add_f32_e32 v128, v133, v126
	v_cvt_pk_bf16_f32 v186, v0, v126
	v_mfma_f32_32x32x16_bf16 v[34:49], v[122:125], v[190:193], v[34:49]
	v_exp_f32_e32 v123, v108
	v_exp_f32_e32 v124, v109
	v_add_f32_e32 v0, v127, v123
	v_add_f32_e32 v122, v128, v124
	v_cvt_pk_bf16_f32 v187, v123, v124

.Lr1u2_Lhd_u2e:
	s_add_i32 s21, s22, 2
	s_cmp_ge_u32 s21, s18
	s_cbranch_scc1 .Lr1u2_LBB0_274
	s_mov_b32 s26, 0x8000
	s_add_i32 s26, s10, s26
	s_add_i32 s27, s26, 0x2000
	s_mov_b32 m0, s26
	s_nop 0
	global_load_lds_dwordx4 v214, s[80:81]
	s_mov_b32 m0, s27
	s_nop 0
	global_load_lds_dwordx4 v214, s[62:63]
.Lr1u2_LBB0_274:
	s_andn2_b64 vcc, exec, s[44:45]
	s_cbranch_vccnz .Lr1u2_LBB0_276
	s_mov_b32 s26, 0x4000
	s_add_i32 s26, s10, s26
	s_add_i32 m0, s26, 0xc000
	s_add_i32 s26, s26, 0xe000
	global_load_lds_dwordx4 v216, s[96:97]
	s_mov_b32 m0, s26
	s_nop 0
	global_load_lds_dwordx4 v216, s[58:59]

.Lr1u2_Lpvo_u2e:
	v_add_u32_e32 v212, s36, v245
	v_add_u32_e32 v0, s36, v246
	s_mov_b64 s[26:27], -1
	ds_read_b128 v[98:101], v212 offset:49152
	ds_read_b128 v[114:117], v212 offset:53248
	ds_read_b128 v[130:133], v212 offset:57344
	ds_read_b128 v[194:197], v212 offset:61440
	s_waitcnt lgkmcnt(0)
	v_mfma_f32_32x32x16_bf16 v[82:97], v[98:101], v[162:165], v[50:65]
	ds_read_b128 v[206:209], v0 offset:49152
	v_mfma_f32_32x32x16_bf16 v[98:113], v[114:117], v[162:165], v[34:49]
	ds_read_b128 v[198:201], v0 offset:53248
	s_add_i32 s21, s22, 2
	s_cmp_lt_u32 s21, s18
	s_cselect_b64 s[26:27], -1, 0
	s_cmp_ge_u32 s21, s18
	s_cbranch_scc1 .Lr1u2_LBB0_281
	s_mov_b32 s37, 0x8000
	s_add_i32 m0, s10, s37
	s_nop 0
	global_load_lds_dwordx4 v214, s[80:81]
.Lr1u2_LBB0_281:
	v_mfma_f32_32x32x16_bf16 v[114:129], v[130:133], v[162:165], v[18:33]
	ds_read_b128 v[202:205], v0 offset:57344
	v_mfma_f32_32x32x16_bf16 v[130:145], v[194:197], v[162:165], v[2:17]
	ds_read_b128 v[194:197], v0 offset:61440
	s_waitcnt lgkmcnt(0)
	v_mfma_f32_32x32x16_bf16 v[82:97], v[206:209], v[170:173], v[82:97]
	v_add_u32_e32 v250, s36, v247
	ds_read_b128 v[206:209], v250 offset:49152
	v_mfma_f32_32x32x16_bf16 v[98:113], v[198:201], v[170:173], v[98:113]
	ds_read_b128 v[198:201], v250 offset:53248
	s_andn2_b64 vcc, exec, s[26:27]
	s_cbranch_vccnz .Lr1u2_LBB0_283
	s_mov_b32 s26, 0x8000
	s_add_i32 s26, s10, s26
	s_add_i32 m0, s26, 0x2000
	s_nop 0
	global_load_lds_dwordx4 v214, s[62:63]
.Lr1u2_LBB0_283:
	v_mfma_f32_32x32x16_bf16 v[114:129], v[202:205], v[170:173], v[114:129]
	ds_read_b128 v[202:205], v250 offset:57344
	v_mfma_f32_32x32x16_bf16 v[130:145], v[194:197], v[170:173], v[130:145]
	ds_read_b128 v[194:197], v250 offset:61440
	s_waitcnt lgkmcnt(0)
	v_mfma_f32_32x32x16_bf16 v[82:97], v[206:209], v[178:181], v[82:97]
	v_add_u32_e32 v250, s36, v248
	ds_read_b128 v[206:209], v250 offset:49152
	v_mfma_f32_32x32x16_bf16 v[98:113], v[198:201], v[178:181], v[98:113]
	ds_read_b128 v[198:201], v250 offset:53248
	v_cndmask_b32_e64 v224, 0, 1, s[44:45]
	v_cmp_ne_u32_e64 s[40:41], 1, v224
	s_andn2_b64 vcc, exec, s[44:45]
	s_cbranch_vccnz .Lr1u2_LBB0_285
	s_mov_b32 s26, 0x4000
	s_add_i32 s26, s10, s26
	s_add_i32 m0, s26, 0xc000
	s_nop 0
	global_load_lds_dwordx4 v216, s[96:97]
.Lr1u2_LBB0_285:
	v_mfma_f32_32x32x16_bf16 v[114:129], v[202:205], v[178:181], v[114:129]
	ds_read_b128 v[202:205], v250 offset:57344
	v_mfma_f32_32x32x16_bf16 v[130:145], v[194:197], v[178:181], v[130:145]
	ds_read_b128 v[194:197], v250 offset:61440
	s_waitcnt lgkmcnt(0)
	v_mfma_f32_32x32x16_bf16 v[82:97], v[206:209], v[186:189], v[82:97]
	v_mfma_f32_32x32x16_bf16 v[98:113], v[198:201], v[186:189], v[98:113]
	s_and_b64 vcc, exec, s[40:41]
	s_cbranch_vccnz .Lr1u2_LBB0_287
	s_mov_b32 s26, 0x4000
	s_add_i32 s26, s10, s26
	s_add_i32 m0, s26, 0xe000
	s_nop 0
	global_load_lds_dwordx4 v216, s[58:59]

.Lr1u2_Lhd_u2o:
	s_add_i32 s26, s22, 3
	s_cmp_gt_u32 s26, s17
	s_cbranch_scc1 .Lr1u2_LBB0_314
	s_mov_b32 s26, 0x0
	s_add_i32 s26, s10, s26
	s_add_i32 s27, s26, 0x2000
	s_mov_b32 m0, s26
	s_nop 0
	global_load_lds_dwordx4 v214, s[50:51]
	s_mov_b32 m0, s27
	s_nop 0
	global_load_lds_dwordx4 v214, s[4:5]
.Lr1u2_LBB0_314:
	s_andn2_b64 vcc, exec, s[44:45]
	s_cbranch_vccnz .Lr1u2_LBB0_316
	s_mov_b32 s26, 0x8000
	s_add_i32 s26, s10, s26
	s_add_i32 m0, s26, 0xc000
	s_add_i32 s26, s26, 0xe000
	global_load_lds_dwordx4 v216, s[0:1]
	s_mov_b32 m0, s26
	s_nop 0
	global_load_lds_dwordx4 v216, s[52:53]

.Lr1u2_Lpvo_u2o:
	v_add_u32_e32 v212, s36, v245
	v_add_u32_e32 v0, s36, v246
	s_mov_b64 s[26:27], -1
	ds_read_b128 v[98:101], v212 offset:49152
	ds_read_b128 v[114:117], v212 offset:53248
	ds_read_b128 v[130:133], v212 offset:57344
	ds_read_b128 v[194:197], v212 offset:61440
	s_waitcnt lgkmcnt(0)
	v_mfma_f32_32x32x16_bf16 v[82:97], v[98:101], v[166:169], v[50:65]
	ds_read_b128 v[206:209], v0 offset:49152
	v_mfma_f32_32x32x16_bf16 v[98:113], v[114:117], v[166:169], v[34:49]
	ds_read_b128 v[198:201], v0 offset:53248
	s_add_i32 s37, s22, 3
	s_cmp_le_u32 s37, s17
	s_cselect_b64 s[26:27], -1, 0
	s_cmp_gt_u32 s37, s17
	s_cbranch_scc1 .Lr1u2_LBB0_321
	s_mov_b32 s37, 0x0
	s_add_i32 m0, s10, s37
	s_nop 0
	global_load_lds_dwordx4 v214, s[50:51]
.Lr1u2_LBB0_321:
	v_mfma_f32_32x32x16_bf16 v[114:129], v[130:133], v[166:169], v[18:33]
	ds_read_b128 v[202:205], v0 offset:57344
	v_mfma_f32_32x32x16_bf16 v[130:145], v[194:197], v[166:169], v[2:17]
	ds_read_b128 v[194:197], v0 offset:61440
	s_waitcnt lgkmcnt(0)
	v_mfma_f32_32x32x16_bf16 v[82:97], v[206:209], v[174:177], v[82:97]
	v_add_u32_e32 v250, s36, v247
	ds_read_b128 v[206:209], v250 offset:49152
	v_mfma_f32_32x32x16_bf16 v[98:113], v[198:201], v[174:177], v[98:113]
	ds_read_b128 v[198:201], v250 offset:53248
	s_andn2_b64 vcc, exec, s[26:27]
	s_cbranch_vccnz .Lr1u2_LBB0_323
	s_mov_b32 s26, 0x0
	s_add_i32 s26, s10, s26
	s_add_i32 m0, s26, 0x2000
	s_nop 0
	global_load_lds_dwordx4 v214, s[4:5]
.Lr1u2_LBB0_323:
	v_mfma_f32_32x32x16_bf16 v[114:129], v[202:205], v[174:177], v[114:129]
	ds_read_b128 v[202:205], v250 offset:57344
	v_mfma_f32_32x32x16_bf16 v[130:145], v[194:197], v[174:177], v[130:145]
	ds_read_b128 v[194:197], v250 offset:61440
	s_waitcnt lgkmcnt(0)
	v_mfma_f32_32x32x16_bf16 v[82:97], v[206:209], v[182:185], v[82:97]
	v_add_u32_e32 v250, s36, v248
	ds_read_b128 v[206:209], v250 offset:49152
	v_mfma_f32_32x32x16_bf16 v[98:113], v[198:201], v[182:185], v[98:113]
	ds_read_b128 v[198:201], v250 offset:53248
	v_cndmask_b32_e64 v224, 0, 1, s[44:45]
	v_cmp_ne_u32_e64 s[40:41], 1, v224
	s_andn2_b64 vcc, exec, s[44:45]
	s_cbranch_vccnz .Lr1u2_LBB0_325
	s_mov_b32 s26, 0x8000
	s_add_i32 s26, s10, s26
	s_add_i32 m0, s26, 0xc000
	s_nop 0
	global_load_lds_dwordx4 v216, s[0:1]
.Lr1u2_LBB0_325:
	v_mfma_f32_32x32x16_bf16 v[114:129], v[202:205], v[182:185], v[114:129]
	ds_read_b128 v[202:205], v250 offset:57344
	v_mfma_f32_32x32x16_bf16 v[130:145], v[194:197], v[182:185], v[130:145]
	ds_read_b128 v[194:197], v250 offset:61440
	s_waitcnt lgkmcnt(0)
	v_mfma_f32_32x32x16_bf16 v[82:97], v[206:209], v[190:193], v[82:97]
	v_mfma_f32_32x32x16_bf16 v[98:113], v[198:201], v[190:193], v[98:113]
	s_and_b64 vcc, exec, s[40:41]
	s_cbranch_vccnz .Lr1u2_LBB0_327
	s_mov_b32 s26, 0x8000
	s_add_i32 s26, s10, s26
	s_add_i32 m0, s26, 0xe000
	s_nop 0
	global_load_lds_dwordx4 v216, s[52:53]

.Lr1u2_Lotail_u2o:
	s_add_i32 s26, s22, -1
	s_cmp_lt_u32 s26, s17
	s_cbranch_scc1 .Lr1u2_Low2_u2o
	s_waitcnt vmcnt(0)
	s_branch .Lr1u2_LBB0_311
.Lr2u2_LBB0_267:
	s_add_i32 s21, s22, -1
	s_cmp_lt_u32 s21, s17
	s_cselect_b64 s[44:45], -1, 0
	s_waitcnt vmcnt(2)

.Lr2u2_LBB0_277:
	s_mov_b32 s36, 0xffffc000
	s_cmp_ge_u32 s22, s19
	s_cbranch_scc1 .Lr2u2_Lslow_u2e
.Lr2u2_LBB0_288:
	s_add_i32 s100, s10, 0x4000
	s_add_i32 s101, s10, 0x0
	ds_read_b128 v[126:129], v245 offset:32768
	s_waitcnt lgkmcnt(1)
	v_mfma_f32_32x32x16_bf16 v[82:97], v[98:101], v[146:149], v[66:81]
	ds_read_b128 v[122:125], v240 offset:40960
	v_mfma_f32_32x32x16_bf16 v[98:113], v[114:117], v[146:149], v[66:81]
	ds_read_b128 v[114:117], v241 offset:32768
	v_mfma_f32_32x32x16_bf16 v[82:97], v[118:121], v[150:153], v[82:97]
	ds_read_b128 v[118:121], v241 offset:40960
	s_waitcnt lgkmcnt(0)
	v_mfma_f32_32x32x16_bf16 v[98:113], v[122:125], v[150:153], v[98:113]
	ds_read_b128 v[122:125], v242 offset:32768
	v_mfma_f32_32x32x16_bf16 v[82:97], v[114:117], v[154:157], v[82:97]
	ds_read_b128 v[114:117], v242 offset:40960
	v_mfma_f32_32x32x16_bf16 v[98:113], v[118:121], v[154:157], v[98:113]
	s_waitcnt lgkmcnt(0)
	v_mfma_f32_32x32x16_bf16 v[82:97], v[122:125], v[158:161], v[82:97]
	v_mfma_f32_32x32x16_bf16 v[98:113], v[114:117], v[158:161], v[98:113]
	s_nop 0
	ds_read_b128 v[122:125], v245 offset:36864
	ds_read_b128 v[118:121], v245 offset:40960
	ds_read_b128 v[114:117], v245 offset:45056
	s_cmp_le_u32 s20, s16
	s_cbranch_scc0 .Lr2u2_Lnear_u2e
.Lr2u2_LBB0_291:
	v_mfma_f32_32x32x16_bf16 v[50:65], v[126:129], v[162:165], v[50:65]
	ds_read_b128 v[126:129], v246 offset:32768
	s_nop 1
	v_exp_f32_e32 v130, v82
	v_exp_f32_e32 v131, v83
	v_add_f32_e32 v132, v1, v130
	v_add_f32_e32 v133, v1, v131
	v_cvt_pk_bf16_f32 v166, v130, v131
	s_waitcnt lgkmcnt(3)
	v_mfma_f32_32x32x16_bf16 v[34:49], v[122:125], v[162:165], v[34:49]
	ds_read_b128 v[122:125], v246 offset:36864
	v_exp_f32_e32 v134, v84
	v_exp_f32_e32 v135, v85
	s_add_i32 s21, s22, 2
	v_add_f32_e32 v130, v132, v134
	v_add_f32_e32 v131, v133, v135
	v_cvt_pk_bf16_f32 v167, v134, v135
	s_mov_b32 m0, s100
	s_cmp_ge_u32 s21, s18
	s_cbranch_scc1 .Lr2u2_LBB0_293
	global_load_lds_dwordx4 v214, s[80:81]
	s_add_i32 m0, s100, 0x2000
	s_nop 0
	global_load_lds_dwordx4 v214, s[62:63]
.Lr2u2_LBB0_293:
	s_waitcnt lgkmcnt(2)
	v_mfma_f32_32x32x16_bf16 v[18:33], v[118:121], v[162:165], v[18:33]
	ds_read_b128 v[118:121], v246 offset:40960
	v_exp_f32_e32 v132, v86
	v_exp_f32_e32 v133, v87
	v_add_f32_e32 v130, v130, v132
	v_add_f32_e32 v131, v131, v133
	v_cvt_pk_bf16_f32 v168, v132, v133
	v_mfma_f32_32x32x16_bf16 v[2:17], v[114:117], v[162:165], v[2:17]
	ds_read_b128 v[114:117], v246 offset:45056
	v_exp_f32_e32 v0, v88
	v_exp_f32_e32 v132, v89
	v_add_f32_e32 v130, v130, v0
	v_add_f32_e32 v131, v131, v132
	v_cvt_pk_bf16_f32 v169, v0, v132
	s_waitcnt lgkmcnt(2)
	v_mfma_f32_32x32x16_bf16 v[50:65], v[126:129], v[170:173], v[50:65]
	ds_read_b128 v[126:129], v247 offset:32768
	v_exp_f32_e32 v132, v90
	v_exp_f32_e32 v133, v91
	v_add_f32_e32 v130, v130, v132
	v_add_f32_e32 v131, v131, v133
	v_cvt_pk_bf16_f32 v174, v132, v133
	v_mfma_f32_32x32x16_bf16 v[34:49], v[122:125], v[170:173], v[34:49]
	ds_read_b128 v[122:125], v247 offset:36864
	v_exp_f32_e32 v132, v92
	v_exp_f32_e32 v133, v93
	v_add_f32_e32 v130, v130, v132
	v_add_f32_e32 v131, v131, v133
	v_cvt_pk_bf16_f32 v175, v132, v133
.Lr2u2_LBB0_295:
	s_waitcnt lgkmcnt(2)
	v_mfma_f32_32x32x16_bf16 v[18:33], v[118:121], v[170:173], v[18:33]
	ds_read_b128 v[118:121], v247 offset:40960
	v_exp_f32_e32 v132, v94
	v_exp_f32_e32 v133, v95
	v_add_f32_e32 v130, v130, v132
	v_add_f32_e32 v131, v131, v133
	v_cvt_pk_bf16_f32 v176, v132, v133
	v_mfma_f32_32x32x16_bf16 v[2:17], v[114:117], v[170:173], v[2:17]
	ds_read_b128 v[114:117], v247 offset:45056
	v_exp_f32_e32 v0, v96
	v_exp_f32_e32 v132, v97
	v_add_f32_e32 v130, v130, v0
	v_add_f32_e32 v131, v131, v132
	v_cvt_pk_bf16_f32 v177, v0, v132
	s_waitcnt lgkmcnt(2)
	v_mfma_f32_32x32x16_bf16 v[50:65], v[126:129], v[178:181], v[50:65]
	ds_read_b128 v[126:129], v248 offset:32768
	v_exp_f32_e32 v132, v98
	v_exp_f32_e32 v133, v99
	v_add_f32_e32 v130, v130, v132
	v_add_f32_e32 v131, v131, v133
	v_cvt_pk_bf16_f32 v182, v132, v133
	v_mfma_f32_32x32x16_bf16 v[34:49], v[122:125], v[178:181], v[34:49]
	v_exp_f32_e32 v132, v100
	v_exp_f32_e32 v133, v101
	ds_read_b128 v[122:125], v248 offset:36864
	v_add_f32_e32 v130, v130, v132
	v_add_f32_e32 v131, v131, v133
	v_cvt_pk_bf16_f32 v183, v132, v133
	s_add_i32 m0, s101, 0xc000
	s_cmp_eq_u64 s[44:45], 0
	s_cbranch_scc1 .Lr2u2_LBB0_297
	global_load_lds_dwordx4 v216, s[96:97]
	s_add_i32 m0, s101, 0xe000
	s_nop 0
	global_load_lds_dwordx4 v216, s[58:59]
.Lr2u2_LBB0_297:
	s_waitcnt lgkmcnt(2)
	v_mfma_f32_32x32x16_bf16 v[18:33], v[118:121], v[178:181], v[18:33]
	ds_read_b128 v[118:121], v248 offset:40960
	v_exp_f32_e32 v132, v102
	v_exp_f32_e32 v133, v103
	v_add_f32_e32 v130, v130, v132
	v_add_f32_e32 v131, v131, v133
	v_cvt_pk_bf16_f32 v184, v132, v133
	v_mfma_f32_32x32x16_bf16 v[2:17], v[114:117], v[178:181], v[2:17]
	ds_read_b128 v[114:117], v248 offset:45056
	v_exp_f32_e32 v0, v104
	v_exp_f32_e32 v132, v105
	v_add_f32_e32 v130, v130, v0
	v_add_f32_e32 v131, v131, v132
	v_cvt_pk_bf16_f32 v185, v0, v132
	s_waitcnt lgkmcnt(2)
	v_mfma_f32_32x32x16_bf16 v[50:65], v[126:129], v[186:189], v[50:65]
	v_exp_f32_e32 v0, v106
	v_exp_f32_e32 v126, v107
	v_add_f32_e32 v127, v130, v0
	v_add_f32_e32 v128, v131, v126
	v_cvt_pk_bf16_f32 v190, v0, v126
	v_mfma_f32_32x32x16_bf16 v[34:49], v[122:125], v[186:189], v[34:49]
	v_exp_f32_e32 v123, v108
	v_exp_f32_e32 v124, v109
	v_add_f32_e32 v0, v127, v123
	v_add_f32_e32 v122, v128, v124
	v_cvt_pk_bf16_f32 v191, v123, v124

.Lr2u2_LBB0_317:
	s_add_i32 s37, s22, 1
	s_mov_b32 s36, 0x0
	s_cmp_ge_u32 s37, s19
	s_cbranch_scc1 .Lr2u2_Lslow_u2o
.Lr2u2_LBB0_328:
	s_add_i32 s100, s10, 0x8000
	s_add_i32 s101, s10, 0x4000
	ds_read_b128 v[126:129], v245 offset:49152
	s_waitcnt lgkmcnt(1)
	v_mfma_f32_32x32x16_bf16 v[82:97], v[98:101], v[146:149], v[66:81]
	ds_read_b128 v[122:125], v240 offset:8192
	v_mfma_f32_32x32x16_bf16 v[98:113], v[114:117], v[146:149], v[66:81]
	ds_read_b128 v[114:117], v241
	v_mfma_f32_32x32x16_bf16 v[82:97], v[118:121], v[150:153], v[82:97]
	ds_read_b128 v[118:121], v241 offset:8192
	s_waitcnt lgkmcnt(0)
	v_mfma_f32_32x32x16_bf16 v[98:113], v[122:125], v[150:153], v[98:113]
	ds_read_b128 v[122:125], v242
	v_mfma_f32_32x32x16_bf16 v[82:97], v[114:117], v[154:157], v[82:97]
	ds_read_b128 v[114:117], v242 offset:8192
	v_mfma_f32_32x32x16_bf16 v[98:113], v[118:121], v[154:157], v[98:113]
	s_waitcnt lgkmcnt(0)
	v_mfma_f32_32x32x16_bf16 v[82:97], v[122:125], v[158:161], v[82:97]
	v_mfma_f32_32x32x16_bf16 v[98:113], v[114:117], v[158:161], v[98:113]
	s_nop 0
	ds_read_b128 v[122:125], v245 offset:53248
	ds_read_b128 v[118:121], v245 offset:57344
	ds_read_b128 v[114:117], v245 offset:61440
	s_add_i32 s26, s20, 64
	s_cmp_le_u32 s26, s16
	s_cbranch_scc0 .Lr2u2_Lnear_u2o
.Lr2u2_LBB0_331:
	v_mfma_f32_32x32x16_bf16 v[50:65], v[126:129], v[166:169], v[50:65]
	ds_read_b128 v[126:129], v246 offset:49152
	s_nop 0
	v_exp_f32_e32 v130, v82
	v_exp_f32_e32 v131, v83
	v_add_f32_e32 v132, v1, v130
	v_add_f32_e32 v133, v1, v131
	v_cvt_pk_bf16_f32 v162, v130, v131
	s_waitcnt lgkmcnt(3)
	v_mfma_f32_32x32x16_bf16 v[34:49], v[122:125], v[166:169], v[34:49]
	ds_read_b128 v[122:125], v246 offset:53248
	v_exp_f32_e32 v130, v84
	v_exp_f32_e32 v131, v85
	s_add_i32 s22, s22, 3
	v_add_f32_e32 v132, v132, v130
	v_add_f32_e32 v133, v133, v131
	v_cvt_pk_bf16_f32 v163, v130, v131
	s_mov_b32 m0, s100
	s_cmp_gt_u32 s22, s17
	s_cbranch_scc1 .Lr2u2_LBB0_333
	global_load_lds_dwordx4 v214, s[50:51]
	s_add_i32 m0, s100, 0x2000
	s_nop 0
	global_load_lds_dwordx4 v214, s[4:5]
.Lr2u2_LBB0_333:
	s_waitcnt lgkmcnt(2)
	v_mfma_f32_32x32x16_bf16 v[18:33], v[118:121], v[166:169], v[18:33]
	ds_read_b128 v[118:121], v246 offset:57344
	v_exp_f32_e32 v134, v86
	v_exp_f32_e32 v135, v87
	v_add_f32_e32 v132, v132, v134
	v_add_f32_e32 v133, v133, v135
	v_cvt_pk_bf16_f32 v164, v134, v135
	v_mfma_f32_32x32x16_bf16 v[2:17], v[114:117], v[166:169], v[2:17]
	ds_read_b128 v[114:117], v246 offset:61440
	v_exp_f32_e32 v0, v88
	v_exp_f32_e32 v134, v89
	v_add_f32_e32 v132, v132, v0
	v_add_f32_e32 v133, v133, v134
	v_cvt_pk_bf16_f32 v165, v0, v134
	s_waitcnt lgkmcnt(2)
	v_mfma_f32_32x32x16_bf16 v[50:65], v[126:129], v[174:177], v[50:65]
	ds_read_b128 v[126:129], v247 offset:49152
	v_exp_f32_e32 v134, v90
	v_exp_f32_e32 v135, v91
	v_add_f32_e32 v132, v132, v134
	v_add_f32_e32 v133, v133, v135
	v_cvt_pk_bf16_f32 v170, v134, v135
	v_mfma_f32_32x32x16_bf16 v[34:49], v[122:125], v[174:177], v[34:49]
	ds_read_b128 v[122:125], v247 offset:53248
	v_exp_f32_e32 v134, v92
	v_exp_f32_e32 v135, v93
	v_add_f32_e32 v132, v132, v134
	v_add_f32_e32 v133, v133, v135
	v_cvt_pk_bf16_f32 v171, v134, v135
.Lr2u2_LBB0_335:
	s_waitcnt lgkmcnt(2)
	v_mfma_f32_32x32x16_bf16 v[18:33], v[118:121], v[174:177], v[18:33]
	ds_read_b128 v[118:121], v247 offset:57344
	v_exp_f32_e32 v130, v94
	v_exp_f32_e32 v131, v95
	v_add_f32_e32 v132, v132, v130
	v_add_f32_e32 v133, v133, v131
	v_cvt_pk_bf16_f32 v172, v130, v131
	v_mfma_f32_32x32x16_bf16 v[2:17], v[114:117], v[174:177], v[2:17]
	ds_read_b128 v[114:117], v247 offset:61440
	v_exp_f32_e32 v0, v96
	v_exp_f32_e32 v130, v97
	v_add_f32_e32 v131, v132, v0
	v_add_f32_e32 v132, v133, v130
	v_cvt_pk_bf16_f32 v173, v0, v130
	s_waitcnt lgkmcnt(2)
	v_mfma_f32_32x32x16_bf16 v[50:65], v[126:129], v[182:185], v[50:65]
	ds_read_b128 v[126:129], v248 offset:49152
	v_exp_f32_e32 v130, v98
	v_exp_f32_e32 v133, v99
	v_add_f32_e32 v131, v131, v130
	v_add_f32_e32 v134, v132, v133
	v_cvt_pk_bf16_f32 v178, v130, v133
	v_mfma_f32_32x32x16_bf16 v[34:49], v[122:125], v[182:185], v[34:49]
	v_exp_f32_e32 v130, v100
	v_exp_f32_e32 v135, v101
	ds_read_b128 v[122:125], v248 offset:53248
	v_add_f32_e32 v132, v131, v130
	v_add_f32_e32 v133, v134, v135
	v_cvt_pk_bf16_f32 v179, v130, v135
	s_add_i32 m0, s101, 0xc000
	s_cmp_eq_u64 s[44:45], 0
	s_cbranch_scc1 .Lr2u2_LBB0_337
	global_load_lds_dwordx4 v216, s[0:1]
	s_add_i32 m0, s101, 0xe000
	s_nop 0
	global_load_lds_dwordx4 v216, s[52:53]
.Lr2u2_LBB0_337:
	s_waitcnt lgkmcnt(2)
	v_mfma_f32_32x32x16_bf16 v[18:33], v[118:121], v[182:185], v[18:33]
	ds_read_b128 v[118:121], v248 offset:57344
	v_exp_f32_e32 v134, v102
	v_exp_f32_e32 v135, v103
	v_add_f32_e32 v132, v132, v134
	v_add_f32_e32 v133, v133, v135
	v_cvt_pk_bf16_f32 v180, v134, v135
	v_mfma_f32_32x32x16_bf16 v[2:17], v[114:117], v[182:185], v[2:17]
	ds_read_b128 v[114:117], v248 offset:61440
	v_exp_f32_e32 v0, v104
	v_exp_f32_e32 v134, v105
	v_add_f32_e32 v132, v132, v0
	v_add_f32_e32 v133, v133, v134
	v_cvt_pk_bf16_f32 v181, v0, v134
	s_waitcnt lgkmcnt(2)
	v_mfma_f32_32x32x16_bf16 v[50:65], v[126:129], v[190:193], v[50:65]
	v_exp_f32_e32 v0, v106
	v_exp_f32_e32 v126, v107
	v_add_f32_e32 v127, v132, v0
	v_add_f32_e32 v128, v133, v126
	v_cvt_pk_bf16_f32 v186, v0, v126
	v_mfma_f32_32x32x16_bf16 v[34:49], v[122:125], v[190:193], v[34:49]
	v_exp_f32_e32 v123, v108
	v_exp_f32_e32 v124, v109
	v_add_f32_e32 v0, v127, v123
	v_add_f32_e32 v122, v128, v124
	v_cvt_pk_bf16_f32 v187, v123, v124

.Lr2u2_Lhd_u2e:
	s_add_i32 s21, s22, 2
	s_cmp_ge_u32 s21, s18
	s_cbranch_scc1 .Lr2u2_LBB0_274
	s_mov_b32 s26, 0x4000
	s_add_i32 s26, s10, s26
	s_add_i32 s27, s26, 0x2000
	s_mov_b32 m0, s26
	s_nop 0
	global_load_lds_dwordx4 v214, s[80:81]
	s_mov_b32 m0, s27
	s_nop 0
	global_load_lds_dwordx4 v214, s[62:63]
.Lr2u2_LBB0_274:
	s_andn2_b64 vcc, exec, s[44:45]
	s_cbranch_vccnz .Lr2u2_LBB0_276
	s_mov_b32 s26, 0x0
	s_add_i32 s26, s10, s26
	s_add_i32 m0, s26, 0xc000
	s_add_i32 s26, s26, 0xe000
	global_load_lds_dwordx4 v216, s[96:97]
	s_mov_b32 m0, s26
	s_nop 0
	global_load_lds_dwordx4 v216, s[58:59]

.Lr2u2_Lpvo_u2e:
	v_add_u32_e32 v212, s36, v245
	v_add_u32_e32 v0, s36, v246
	s_mov_b64 s[26:27], -1
	ds_read_b128 v[98:101], v212 offset:49152
	ds_read_b128 v[114:117], v212 offset:53248
	ds_read_b128 v[130:133], v212 offset:57344
	ds_read_b128 v[194:197], v212 offset:61440
	s_waitcnt lgkmcnt(0)
	v_mfma_f32_32x32x16_bf16 v[82:97], v[98:101], v[162:165], v[50:65]
	ds_read_b128 v[206:209], v0 offset:49152
	v_mfma_f32_32x32x16_bf16 v[98:113], v[114:117], v[162:165], v[34:49]
	ds_read_b128 v[198:201], v0 offset:53248
	s_add_i32 s21, s22, 2
	s_cmp_lt_u32 s21, s18
	s_cselect_b64 s[26:27], -1, 0
	s_cmp_ge_u32 s21, s18
	s_cbranch_scc1 .Lr2u2_LBB0_281
	s_mov_b32 s37, 0x4000
	s_add_i32 m0, s10, s37
	s_nop 0
	global_load_lds_dwordx4 v214, s[80:81]
.Lr2u2_LBB0_281:
	v_mfma_f32_32x32x16_bf16 v[114:129], v[130:133], v[162:165], v[18:33]
	ds_read_b128 v[202:205], v0 offset:57344
	v_mfma_f32_32x32x16_bf16 v[130:145], v[194:197], v[162:165], v[2:17]
	ds_read_b128 v[194:197], v0 offset:61440
	s_waitcnt lgkmcnt(0)
	v_mfma_f32_32x32x16_bf16 v[82:97], v[206:209], v[170:173], v[82:97]
	v_add_u32_e32 v250, s36, v247
	ds_read_b128 v[206:209], v250 offset:49152
	v_mfma_f32_32x32x16_bf16 v[98:113], v[198:201], v[170:173], v[98:113]
	ds_read_b128 v[198:201], v250 offset:53248
	s_andn2_b64 vcc, exec, s[26:27]
	s_cbranch_vccnz .Lr2u2_LBB0_283
	s_mov_b32 s26, 0x4000
	s_add_i32 s26, s10, s26
	s_add_i32 m0, s26, 0x2000
	s_nop 0
	global_load_lds_dwordx4 v214, s[62:63]
.Lr2u2_LBB0_283:
	v_mfma_f32_32x32x16_bf16 v[114:129], v[202:205], v[170:173], v[114:129]
	ds_read_b128 v[202:205], v250 offset:57344
	v_mfma_f32_32x32x16_bf16 v[130:145], v[194:197], v[170:173], v[130:145]
	ds_read_b128 v[194:197], v250 offset:61440
	s_waitcnt lgkmcnt(0)
	v_mfma_f32_32x32x16_bf16 v[82:97], v[206:209], v[178:181], v[82:97]
	v_add_u32_e32 v250, s36, v248
	ds_read_b128 v[206:209], v250 offset:49152
	v_mfma_f32_32x32x16_bf16 v[98:113], v[198:201], v[178:181], v[98:113]
	ds_read_b128 v[198:201], v250 offset:53248
	v_cndmask_b32_e64 v224, 0, 1, s[44:45]
	v_cmp_ne_u32_e64 s[40:41], 1, v224
	s_andn2_b64 vcc, exec, s[44:45]
	s_cbranch_vccnz .Lr2u2_LBB0_285
	s_mov_b32 s26, 0x0
	s_add_i32 s26, s10, s26
	s_add_i32 m0, s26, 0xc000
	s_nop 0
	global_load_lds_dwordx4 v216, s[96:97]
.Lr2u2_LBB0_285:
	v_mfma_f32_32x32x16_bf16 v[114:129], v[202:205], v[178:181], v[114:129]
	ds_read_b128 v[202:205], v250 offset:57344
	v_mfma_f32_32x32x16_bf16 v[130:145], v[194:197], v[178:181], v[130:145]
	ds_read_b128 v[194:197], v250 offset:61440
	s_waitcnt lgkmcnt(0)
	v_mfma_f32_32x32x16_bf16 v[82:97], v[206:209], v[186:189], v[82:97]
	v_mfma_f32_32x32x16_bf16 v[98:113], v[198:201], v[186:189], v[98:113]
	s_and_b64 vcc, exec, s[40:41]
	s_cbranch_vccnz .Lr2u2_LBB0_287
	s_mov_b32 s26, 0x0
	s_add_i32 s26, s10, s26
	s_add_i32 m0, s26, 0xe000
	s_nop 0
	global_load_lds_dwordx4 v216, s[58:59]

.Lr2u2_Lhd_u2o:
	s_add_i32 s26, s22, 3
	s_cmp_gt_u32 s26, s17
	s_cbranch_scc1 .Lr2u2_LBB0_314
	s_mov_b32 s26, 0x8000
	s_add_i32 s26, s10, s26
	s_add_i32 s27, s26, 0x2000
	s_mov_b32 m0, s26
	s_nop 0
	global_load_lds_dwordx4 v214, s[50:51]
	s_mov_b32 m0, s27
	s_nop 0
	global_load_lds_dwordx4 v214, s[4:5]
.Lr2u2_LBB0_314:
	s_andn2_b64 vcc, exec, s[44:45]
	s_cbranch_vccnz .Lr2u2_LBB0_316
	s_mov_b32 s26, 0x4000
	s_add_i32 s26, s10, s26
	s_add_i32 m0, s26, 0xc000
	s_add_i32 s26, s26, 0xe000
	global_load_lds_dwordx4 v216, s[0:1]
	s_mov_b32 m0, s26
	s_nop 0
	global_load_lds_dwordx4 v216, s[52:53]

.Lr2u2_Lpvo_u2o:
	v_add_u32_e32 v212, s36, v245
	v_add_u32_e32 v0, s36, v246
	s_mov_b64 s[26:27], -1
	ds_read_b128 v[98:101], v212 offset:49152
	ds_read_b128 v[114:117], v212 offset:53248
	ds_read_b128 v[130:133], v212 offset:57344
	ds_read_b128 v[194:197], v212 offset:61440
	s_waitcnt lgkmcnt(0)
	v_mfma_f32_32x32x16_bf16 v[82:97], v[98:101], v[166:169], v[50:65]
	ds_read_b128 v[206:209], v0 offset:49152
	v_mfma_f32_32x32x16_bf16 v[98:113], v[114:117], v[166:169], v[34:49]
	ds_read_b128 v[198:201], v0 offset:53248
	s_add_i32 s37, s22, 3
	s_cmp_le_u32 s37, s17
	s_cselect_b64 s[26:27], -1, 0
	s_cmp_gt_u32 s37, s17
	s_cbranch_scc1 .Lr2u2_LBB0_321
	s_mov_b32 s37, 0x8000
	s_add_i32 m0, s10, s37
	s_nop 0
	global_load_lds_dwordx4 v214, s[50:51]
.Lr2u2_LBB0_321:
	v_mfma_f32_32x32x16_bf16 v[114:129], v[130:133], v[166:169], v[18:33]
	ds_read_b128 v[202:205], v0 offset:57344
	v_mfma_f32_32x32x16_bf16 v[130:145], v[194:197], v[166:169], v[2:17]
	ds_read_b128 v[194:197], v0 offset:61440
	s_waitcnt lgkmcnt(0)
	v_mfma_f32_32x32x16_bf16 v[82:97], v[206:209], v[174:177], v[82:97]
	v_add_u32_e32 v250, s36, v247
	ds_read_b128 v[206:209], v250 offset:49152
	v_mfma_f32_32x32x16_bf16 v[98:113], v[198:201], v[174:177], v[98:113]
	ds_read_b128 v[198:201], v250 offset:53248
	s_andn2_b64 vcc, exec, s[26:27]
	s_cbranch_vccnz .Lr2u2_LBB0_323
	s_mov_b32 s26, 0x8000
	s_add_i32 s26, s10, s26
	s_add_i32 m0, s26, 0x2000
	s_nop 0
	global_load_lds_dwordx4 v214, s[4:5]
.Lr2u2_LBB0_323:
	v_mfma_f32_32x32x16_bf16 v[114:129], v[202:205], v[174:177], v[114:129]
	ds_read_b128 v[202:205], v250 offset:57344
	v_mfma_f32_32x32x16_bf16 v[130:145], v[194:197], v[174:177], v[130:145]
	ds_read_b128 v[194:197], v250 offset:61440
	s_waitcnt lgkmcnt(0)
	v_mfma_f32_32x32x16_bf16 v[82:97], v[206:209], v[182:185], v[82:97]
	v_add_u32_e32 v250, s36, v248
	ds_read_b128 v[206:209], v250 offset:49152
	v_mfma_f32_32x32x16_bf16 v[98:113], v[198:201], v[182:185], v[98:113]
	ds_read_b128 v[198:201], v250 offset:53248
	v_cndmask_b32_e64 v224, 0, 1, s[44:45]
	v_cmp_ne_u32_e64 s[40:41], 1, v224
	s_andn2_b64 vcc, exec, s[44:45]
	s_cbranch_vccnz .Lr2u2_LBB0_325
	s_mov_b32 s26, 0x4000
	s_add_i32 s26, s10, s26
	s_add_i32 m0, s26, 0xc000
	s_nop 0
	global_load_lds_dwordx4 v216, s[0:1]
.Lr2u2_LBB0_325:
	v_mfma_f32_32x32x16_bf16 v[114:129], v[202:205], v[182:185], v[114:129]
	ds_read_b128 v[202:205], v250 offset:57344
	v_mfma_f32_32x32x16_bf16 v[130:145], v[194:197], v[182:185], v[130:145]
	ds_read_b128 v[194:197], v250 offset:61440
	s_waitcnt lgkmcnt(0)
	v_mfma_f32_32x32x16_bf16 v[82:97], v[206:209], v[190:193], v[82:97]
	v_mfma_f32_32x32x16_bf16 v[98:113], v[198:201], v[190:193], v[98:113]
	s_and_b64 vcc, exec, s[40:41]
	s_cbranch_vccnz .Lr2u2_LBB0_327
	s_mov_b32 s26, 0x4000
	s_add_i32 s26, s10, s26
	s_add_i32 m0, s26, 0xe000
	s_nop 0
	global_load_lds_dwordx4 v216, s[52:53]
